# hand-written up-projection epilogue entry pinned at byte phase 60 mod 64 (GLU and in-projection epilogues pinned where they were)
# baseline (speedup 1.0000x reference)
; __device__ __forceinline__ float fast_sigmoid(float x) { return __builtin_amdgcn_rcpf(1.0f + __builtin_amdgcn_exp2f(x * -1.44269504f)); }
;     __device__ __forceinline__ void operator()(const Acc& acc, const Unit& u, int wr, int wc, int fr, int fq, LAS unsigned char* lds, f32x4 epar) const {
;         const int c0 = u.pn * 128 + wc * 32 + 8 * fq;
;         f32x4 xv[2][4][2];
; #pragma unroll
;         for (int ai = 0; ai < 2; ++ai)
; #pragma unroll
;             for (int m = 0; m < 4; ++m) { const int r = u.pm * BM + ai * HALF + wr * 64 + m * 16 + fr; const size_t off = (size_t)r * DM + c0;
;                 xv[ai][m][0] = __builtin_nontemporal_load((const f32x4*)(x + off)); xv[ai][m][1] = __builtin_nontemporal_load((const f32x4*)(x + off + 4)); }
; #pragma unroll
;         for (int ai = 0; ai < 2; ++ai)
; #pragma unroll
;             for (int m = 0; m < 4; ++m) { const int r = u.pm * BM + ai * HALF + wr * 64 + m * 16 + fr; const size_t off = (size_t)r * DM + c0;
;                 f32x4 v0 = xv[ai][m][0], v1 = xv[ai][m][1];
;                 const f32x4 za0 = acc[ai][0][m][0], za1 = acc[ai][0][m][1], zg0 = acc[ai][1][m][0], zg1 = acc[ai][1][m][1];
; #pragma unroll
;                 for (int j = 0; j < 4; ++j) { v0[j] += za0[j] * fast_sigmoid(zg0[j]); v1[j] += za1[j] * fast_sigmoid(zg1[j]); }
.LBB0_629:
	.p2align 6
	s_nop 0
	s_nop 0
	s_nop 0
	s_nop 0
	s_nop 0
	s_nop 0
	s_nop 0
	s_nop 0
	s_mov_b32 s101, 1.0
	s_mov_b32 s100, 0xbfb8aa3b
	v_readlane_b32 s44, v252, 6
	v_readlane_b32 s45, v252, 7
	v_readlane_b32 s46, v252, 8
	v_readlane_b32 s47, v252, 9
	v_readlane_b32 s48, v252, 10
	v_readlane_b32 s49, v252, 11
	v_readlane_b32 s50, v252, 12
	v_readlane_b32 s51, v252, 13
	v_readlane_b32 s52, v252, 14
	v_readlane_b32 s53, v252, 15
	v_readlane_b32 s54, v252, 16
	v_readlane_b32 s55, v252, 17
	v_readlane_b32 s56, v252, 18
	v_readlane_b32 s57, v252, 19
	v_readlane_b32 s58, v252, 20
	v_readlane_b32 s59, v252, 21
	s_mov_b64 s[0:1], exec
	v_lshl_add_u32 v188, s66, 8, v210
	v_lshl_or_b32 v189, s64, 7, v211
	v_lshlrev_b32_e32 v190, 12, v188
	v_lshlrev_b32_e32 v191, 11, v188
	v_lshlrev_b32_e32 v192, 2, v188
	v_lshl_add_u32 v190, v189, 2, v190
	v_lshl_add_u32 v191, v189, 1, v191
	global_load_dwordx4 v[222:225], v190, s[44:45] nt
	global_load_dwordx4 v[218:221], v190, s[44:45] offset:16 nt
	v_add_u32_e32 v193, 0x10000, v190
	global_load_dwordx4 v[180:183], v193, s[44:45] nt
	global_load_dwordx4 v[176:179], v193, s[44:45] offset:16 nt
	v_add_u32_e32 v193, 0x20000, v190
	global_load_dwordx4 v[172:175], v193, s[44:45] nt
	global_load_dwordx4 v[168:171], v193, s[44:45] offset:16 nt
	v_add_u32_e32 v193, 0x30000, v190
	global_load_dwordx4 v[164:167], v193, s[44:45] nt
	global_load_dwordx4 v[160:163], v193, s[44:45] offset:16 nt
	v_add_u32_e32 v193, 0x80000, v190
	global_load_dwordx4 v[156:159], v193, s[44:45] nt
	global_load_dwordx4 v[152:155], v193, s[44:45] offset:16 nt
	v_add_u32_e32 v193, 0x90000, v190
	global_load_dwordx4 v[148:151], v193, s[44:45] nt
	global_load_dwordx4 v[144:147], v193, s[44:45] offset:16 nt
	v_add_u32_e32 v193, 0xa0000, v190
	global_load_dwordx4 v[140:143], v193, s[44:45] nt
	global_load_dwordx4 v[136:139], v193, s[44:45] offset:16 nt
	v_add_u32_e32 v193, 0xb0000, v190
	global_load_dwordx4 v[132:135], v193, s[44:45] nt
	global_load_dwordx4 v[128:131], v193, s[44:45] offset:16 nt
	v_pk_mul_f32 v[124:125], s[100:101], v[124:125] op_sel_hi:[0,1]
	v_pk_mul_f32 v[126:127], s[100:101], v[126:127] op_sel_hi:[0,1]
	v_pk_mul_f32 v[120:121], s[100:101], v[120:121] op_sel_hi:[0,1]
	v_pk_mul_f32 v[122:123], s[100:101], v[122:123] op_sel_hi:[0,1]
	v_exp_f32_e32 v124, v124
	v_exp_f32_e32 v125, v125
	v_exp_f32_e32 v126, v126
	v_exp_f32_e32 v127, v127
	v_exp_f32_e32 v120, v120
	v_exp_f32_e32 v121, v121
	v_exp_f32_e32 v122, v122
	v_exp_f32_e32 v123, v123
	v_pk_add_f32 v[124:125], s[100:101], v[124:125] op_sel:[1,0]
	v_pk_add_f32 v[126:127], s[100:101], v[126:127] op_sel:[1,0]
	v_pk_add_f32 v[120:121], s[100:101], v[120:121] op_sel:[1,0]
	v_pk_add_f32 v[122:123], s[100:101], v[122:123] op_sel:[1,0]
	v_rcp_f32_e32 v124, v124
	v_rcp_f32_e32 v125, v125
	v_rcp_f32_e32 v126, v126
	v_rcp_f32_e32 v127, v127
	v_rcp_f32_e32 v120, v120
	v_rcp_f32_e32 v121, v121
	v_rcp_f32_e32 v122, v122
	v_rcp_f32_e32 v123, v123
	v_pk_mul_f32 v[108:109], s[100:101], v[108:109] op_sel_hi:[0,1]
	v_pk_mul_f32 v[110:111], s[100:101], v[110:111] op_sel_hi:[0,1]
	v_pk_mul_f32 v[104:105], s[100:101], v[104:105] op_sel_hi:[0,1]
	v_pk_mul_f32 v[106:107], s[100:101], v[106:107] op_sel_hi:[0,1]
	v_exp_f32_e32 v108, v108
	v_exp_f32_e32 v109, v109
	v_exp_f32_e32 v110, v110
	v_exp_f32_e32 v111, v111
	v_exp_f32_e32 v104, v104
	v_exp_f32_e32 v105, v105
	v_exp_f32_e32 v106, v106
	v_exp_f32_e32 v107, v107
	v_pk_add_f32 v[108:109], s[100:101], v[108:109] op_sel:[1,0]
	v_pk_add_f32 v[110:111], s[100:101], v[110:111] op_sel:[1,0]
	v_pk_add_f32 v[104:105], s[100:101], v[104:105] op_sel:[1,0]
	v_pk_add_f32 v[106:107], s[100:101], v[106:107] op_sel:[1,0]
	v_rcp_f32_e32 v108, v108
	v_rcp_f32_e32 v109, v109
	v_rcp_f32_e32 v110, v110
	v_rcp_f32_e32 v111, v111
	v_rcp_f32_e32 v104, v104
	v_rcp_f32_e32 v105, v105
	v_rcp_f32_e32 v106, v106
	v_rcp_f32_e32 v107, v107
	v_pk_mul_f32 v[92:93], s[100:101], v[92:93] op_sel_hi:[0,1]
	v_pk_mul_f32 v[94:95], s[100:101], v[94:95] op_sel_hi:[0,1]
	v_pk_mul_f32 v[88:89], s[100:101], v[88:89] op_sel_hi:[0,1]
	v_pk_mul_f32 v[90:91], s[100:101], v[90:91] op_sel_hi:[0,1]
	v_exp_f32_e32 v92, v92
	v_exp_f32_e32 v93, v93
	v_exp_f32_e32 v94, v94
	v_exp_f32_e32 v95, v95
	v_exp_f32_e32 v88, v88
	v_exp_f32_e32 v89, v89
	v_exp_f32_e32 v90, v90
	v_exp_f32_e32 v91, v91
	v_pk_add_f32 v[92:93], s[100:101], v[92:93] op_sel:[1,0]
	v_pk_add_f32 v[94:95], s[100:101], v[94:95] op_sel:[1,0]
	v_pk_add_f32 v[88:89], s[100:101], v[88:89] op_sel:[1,0]
	v_pk_add_f32 v[90:91], s[100:101], v[90:91] op_sel:[1,0]
	v_rcp_f32_e32 v92, v92
	v_rcp_f32_e32 v93, v93
	v_rcp_f32_e32 v94, v94
	v_rcp_f32_e32 v95, v95
	v_rcp_f32_e32 v88, v88
	v_rcp_f32_e32 v89, v89
	v_rcp_f32_e32 v90, v90
	v_rcp_f32_e32 v91, v91
	v_pk_mul_f32 v[76:77], s[100:101], v[76:77] op_sel_hi:[0,1]
	v_pk_mul_f32 v[78:79], s[100:101], v[78:79] op_sel_hi:[0,1]
	v_pk_mul_f32 v[72:73], s[100:101], v[72:73] op_sel_hi:[0,1]
	v_pk_mul_f32 v[74:75], s[100:101], v[74:75] op_sel_hi:[0,1]
	v_exp_f32_e32 v76, v76
	v_exp_f32_e32 v77, v77
	v_exp_f32_e32 v78, v78
	v_exp_f32_e32 v79, v79
	v_exp_f32_e32 v72, v72
	v_exp_f32_e32 v73, v73
	v_exp_f32_e32 v74, v74
	v_exp_f32_e32 v75, v75
	v_pk_add_f32 v[76:77], s[100:101], v[76:77] op_sel:[1,0]
	v_pk_add_f32 v[78:79], s[100:101], v[78:79] op_sel:[1,0]
	v_pk_add_f32 v[72:73], s[100:101], v[72:73] op_sel:[1,0]
	v_pk_add_f32 v[74:75], s[100:101], v[74:75] op_sel:[1,0]
	v_rcp_f32_e32 v76, v76
	v_rcp_f32_e32 v77, v77
	v_rcp_f32_e32 v78, v78
	v_rcp_f32_e32 v79, v79
	v_rcp_f32_e32 v72, v72
	v_rcp_f32_e32 v73, v73
	v_rcp_f32_e32 v74, v74
	v_rcp_f32_e32 v75, v75
	v_pk_mul_f32 v[60:61], s[100:101], v[60:61] op_sel_hi:[0,1]
; __device__ __forceinline__ unsigned cvt_pk_bf16(float lo, float hi) { unsigned r; asm volatile("v_cvt_pk_bf16_f32 %0, %1, %2" : "=v"(r) : "v"(lo), "v"(hi)); return r; }
; __device__ __forceinline__ float fast_sigmoid(float x) { return __builtin_amdgcn_rcpf(1.0f + __builtin_amdgcn_exp2f(x * -1.44269504f)); }
;     __device__ __forceinline__ void operator()(const Acc& acc, const Unit& u, int wr, int wc, int fr, int fq, LAS unsigned char* lds, f32x4 epar) const {
;     ...
;         for (int ai = 0; ai < 2; ++ai)
; #pragma unroll
;             for (int m = 0; m < 4; ++m) { const int r = u.pm * BM + ai * HALF + wr * 64 + m * 16 + fr; const size_t off = (size_t)r * DM + c0;
;                 f32x4 v0 = xv[ai][m][0], v1 = xv[ai][m][1];
;                 const f32x4 za0 = acc[ai][0][m][0], za1 = acc[ai][0][m][1], zg0 = acc[ai][1][m][0], zg1 = acc[ai][1][m][1];
; #pragma unroll
;                 for (int j = 0; j < 4; ++j) { v0[j] += za0[j] * fast_sigmoid(zg0[j]); v1[j] += za1[j] * fast_sigmoid(zg1[j]); }
;                 u32x4 w; w.x = cvt_pk_bf16(v0[0], v0[1]); w.y = cvt_pk_bf16(v0[2], v0[3]); w.z = cvt_pk_bf16(v1[0], v1[1]); w.w = cvt_pk_bf16(v1[2], v1[3]);
;                 *(u32x4*)(HB + off) = w;
;                 float s = (v0[0] * v0[0] + v0[1] * v0[1]) + (v0[2] * v0[2] + v0[3] * v0[3]) + (v1[0] * v1[0] + v1[1] * v1[1]) + (v1[2] * v1[2] + v1[3] * v1[3]);
;                 s += __shfl_xor(s, 16); s += __shfl_xor(s, 32);
;                 if (fq == 0) unsafeAtomicAdd(ssq + r, s); }
	v_pk_mul_f32 v[62:63], s[100:101], v[62:63] op_sel_hi:[0,1]
	v_pk_mul_f32 v[56:57], s[100:101], v[56:57] op_sel_hi:[0,1]
	v_pk_mul_f32 v[58:59], s[100:101], v[58:59] op_sel_hi:[0,1]
	v_exp_f32_e32 v60, v60
	v_exp_f32_e32 v61, v61
	v_exp_f32_e32 v62, v62
	v_exp_f32_e32 v63, v63
	v_exp_f32_e32 v56, v56
	v_exp_f32_e32 v57, v57
	v_exp_f32_e32 v58, v58
	v_exp_f32_e32 v59, v59
	v_pk_add_f32 v[60:61], s[100:101], v[60:61] op_sel:[1,0]
	v_pk_add_f32 v[62:63], s[100:101], v[62:63] op_sel:[1,0]
	v_pk_add_f32 v[56:57], s[100:101], v[56:57] op_sel:[1,0]
	v_pk_add_f32 v[58:59], s[100:101], v[58:59] op_sel:[1,0]
	v_rcp_f32_e32 v60, v60
	v_rcp_f32_e32 v61, v61
	v_rcp_f32_e32 v62, v62
	v_rcp_f32_e32 v63, v63
	v_rcp_f32_e32 v56, v56
	v_rcp_f32_e32 v57, v57
	v_rcp_f32_e32 v58, v58
	v_rcp_f32_e32 v59, v59
	v_pk_mul_f32 v[44:45], s[100:101], v[44:45] op_sel_hi:[0,1]
	v_pk_mul_f32 v[46:47], s[100:101], v[46:47] op_sel_hi:[0,1]
	v_pk_mul_f32 v[40:41], s[100:101], v[40:41] op_sel_hi:[0,1]
	v_pk_mul_f32 v[42:43], s[100:101], v[42:43] op_sel_hi:[0,1]
	v_exp_f32_e32 v44, v44
	v_exp_f32_e32 v45, v45
	v_exp_f32_e32 v46, v46
	v_exp_f32_e32 v47, v47
	v_exp_f32_e32 v40, v40
	v_exp_f32_e32 v41, v41
	v_exp_f32_e32 v42, v42
	v_exp_f32_e32 v43, v43
	v_pk_add_f32 v[44:45], s[100:101], v[44:45] op_sel:[1,0]
	v_pk_add_f32 v[46:47], s[100:101], v[46:47] op_sel:[1,0]
	v_pk_add_f32 v[40:41], s[100:101], v[40:41] op_sel:[1,0]
	v_pk_add_f32 v[42:43], s[100:101], v[42:43] op_sel:[1,0]
	v_rcp_f32_e32 v44, v44
	v_rcp_f32_e32 v45, v45
	v_rcp_f32_e32 v46, v46
	v_rcp_f32_e32 v47, v47
	v_rcp_f32_e32 v40, v40
	v_rcp_f32_e32 v41, v41
	v_rcp_f32_e32 v42, v42
	v_rcp_f32_e32 v43, v43
	v_pk_mul_f32 v[28:29], s[100:101], v[28:29] op_sel_hi:[0,1]
	v_pk_mul_f32 v[30:31], s[100:101], v[30:31] op_sel_hi:[0,1]
	v_pk_mul_f32 v[24:25], s[100:101], v[24:25] op_sel_hi:[0,1]
	v_pk_mul_f32 v[26:27], s[100:101], v[26:27] op_sel_hi:[0,1]
	v_exp_f32_e32 v28, v28
	v_exp_f32_e32 v29, v29
	v_exp_f32_e32 v30, v30
	v_exp_f32_e32 v31, v31
	v_exp_f32_e32 v24, v24
	v_exp_f32_e32 v25, v25
	v_exp_f32_e32 v26, v26
	v_exp_f32_e32 v27, v27
	v_pk_add_f32 v[28:29], s[100:101], v[28:29] op_sel:[1,0]
	v_pk_add_f32 v[30:31], s[100:101], v[30:31] op_sel:[1,0]
	v_pk_add_f32 v[24:25], s[100:101], v[24:25] op_sel:[1,0]
	v_pk_add_f32 v[26:27], s[100:101], v[26:27] op_sel:[1,0]
	v_rcp_f32_e32 v28, v28
	v_rcp_f32_e32 v29, v29
	v_rcp_f32_e32 v30, v30
	v_rcp_f32_e32 v31, v31
	v_rcp_f32_e32 v24, v24
	v_rcp_f32_e32 v25, v25
	v_rcp_f32_e32 v26, v26
	v_rcp_f32_e32 v27, v27
	v_pk_mul_f32 v[12:13], s[100:101], v[12:13] op_sel_hi:[0,1]
	v_pk_mul_f32 v[14:15], s[100:101], v[14:15] op_sel_hi:[0,1]
	v_pk_mul_f32 v[8:9], s[100:101], v[8:9] op_sel_hi:[0,1]
	v_pk_mul_f32 v[10:11], s[100:101], v[10:11] op_sel_hi:[0,1]
	v_exp_f32_e32 v12, v12
	v_exp_f32_e32 v13, v13
	v_exp_f32_e32 v14, v14
	v_exp_f32_e32 v15, v15
	v_exp_f32_e32 v8, v8
	v_exp_f32_e32 v9, v9
	v_exp_f32_e32 v10, v10
	v_exp_f32_e32 v11, v11
	v_pk_add_f32 v[12:13], s[100:101], v[12:13] op_sel:[1,0]
	v_pk_add_f32 v[14:15], s[100:101], v[14:15] op_sel:[1,0]
	v_pk_add_f32 v[8:9], s[100:101], v[8:9] op_sel:[1,0]
	v_pk_add_f32 v[10:11], s[100:101], v[10:11] op_sel:[1,0]
	v_rcp_f32_e32 v12, v12
	v_rcp_f32_e32 v13, v13
	v_rcp_f32_e32 v14, v14
	v_rcp_f32_e32 v15, v15
	v_rcp_f32_e32 v8, v8
	v_rcp_f32_e32 v9, v9
	v_rcp_f32_e32 v10, v10
	v_rcp_f32_e32 v11, v11
	s_nop 0
	s_waitcnt vmcnt(14)
	v_pk_fma_f32 v[222:223], v[124:125], v[112:113], v[222:223]
	v_pk_fma_f32 v[224:225], v[126:127], v[114:115], v[224:225]
	v_pk_fma_f32 v[218:219], v[120:121], v[116:117], v[218:219]
	v_pk_fma_f32 v[220:221], v[122:123], v[118:119], v[220:221]
	v_mul_f32_e32 v124, v222, v222
	v_mul_f32_e32 v125, v224, v224
	v_mul_f32_e32 v126, v218, v218
	v_mul_f32_e32 v127, v220, v220
	v_fmac_f32_e32 v124, v223, v223
	v_fmac_f32_e32 v125, v225, v225
	v_fmac_f32_e32 v126, v219, v219
	v_fmac_f32_e32 v127, v221, v221
	v_cvt_pk_bf16_f32 v112, v222, v223
	v_cvt_pk_bf16_f32 v113, v224, v225
	v_cvt_pk_bf16_f32 v114, v218, v219
	v_cvt_pk_bf16_f32 v115, v220, v221
	v_add_f32_e32 v124, v124, v125
	v_add_f32_e32 v126, v126, v127
	v_add_f32_e32 v194, v124, v126
	global_store_dwordx4 v191, v[112:115], s[20:21]
	v_mov_b32_e32 v202, v194
	s_nop 0
	s_nop 0
	v_permlane16_swap_b32_e32 v194, v202
	v_add_f32_e32 v194, v194, v202
	v_mov_b32_e32 v202, v194
	s_nop 1
	v_permlane32_swap_b32_e32 v194, v202
	v_add_f32_e32 v194, v194, v202
	s_and_b64 exec, exec, s[4:5]
	global_atomic_add_f32 v192, v194, s[60:61]
	s_mov_b64 exec, s[0:1]
	s_waitcnt vmcnt(14)
	v_pk_fma_f32 v[180:181], v[108:109], v[100:101], v[180:181]
	v_pk_fma_f32 v[182:183], v[110:111], v[102:103], v[182:183]
	v_pk_fma_f32 v[176:177], v[104:105], v[96:97], v[176:177]
	v_pk_fma_f32 v[178:179], v[106:107], v[98:99], v[178:179]
	v_mul_f32_e32 v108, v180, v180
	v_mul_f32_e32 v109, v182, v182
	v_mul_f32_e32 v110, v176, v176
	v_mul_f32_e32 v111, v178, v178
	v_fmac_f32_e32 v108, v181, v181
	v_fmac_f32_e32 v109, v183, v183
	v_fmac_f32_e32 v110, v177, v177
	v_fmac_f32_e32 v111, v179, v179
	v_cvt_pk_bf16_f32 v100, v180, v181
	v_cvt_pk_bf16_f32 v101, v182, v183
	v_cvt_pk_bf16_f32 v102, v176, v177
	v_cvt_pk_bf16_f32 v103, v178, v179
	v_add_f32_e32 v108, v108, v109
	v_add_f32_e32 v110, v110, v111
	v_add_u32_e32 v193, 0x8000, v191
	v_add_f32_e32 v195, v108, v110
	global_store_dwordx4 v193, v[100:103], s[20:21]
	v_mov_b32_e32 v203, v195
	v_add_u32_e32 v193, 0x40, v192
	s_nop 0
	v_permlane16_swap_b32_e32 v195, v203
	v_add_f32_e32 v195, v195, v203
	v_mov_b32_e32 v203, v195
	s_nop 1
	v_permlane32_swap_b32_e32 v195, v203
	v_add_f32_e32 v195, v195, v203
	s_and_b64 exec, exec, s[4:5]
	global_atomic_add_f32 v193, v195, s[60:61]
	s_mov_b64 exec, s[0:1]
	s_waitcnt vmcnt(14)
; __device__ __forceinline__ unsigned cvt_pk_bf16(float lo, float hi) { unsigned r; asm volatile("v_cvt_pk_bf16_f32 %0, %1, %2" : "=v"(r) : "v"(lo), "v"(hi)); return r; }
; __device__ __forceinline__ float fast_sigmoid(float x) { return __builtin_amdgcn_rcpf(1.0f + __builtin_amdgcn_exp2f(x * -1.44269504f)); }
;     __device__ __forceinline__ void operator()(const Acc& acc, const Unit& u, int wr, int wc, int fr, int fq, LAS unsigned char* lds, f32x4 epar) const {
;     ...
;         for (int ai = 0; ai < 2; ++ai)
; #pragma unroll
;             for (int m = 0; m < 4; ++m) { const int r = u.pm * BM + ai * HALF + wr * 64 + m * 16 + fr; const size_t off = (size_t)r * DM + c0;
;                 f32x4 v0 = xv[ai][m][0], v1 = xv[ai][m][1];
;                 const f32x4 za0 = acc[ai][0][m][0], za1 = acc[ai][0][m][1], zg0 = acc[ai][1][m][0], zg1 = acc[ai][1][m][1];
; #pragma unroll
;                 for (int j = 0; j < 4; ++j) { v0[j] += za0[j] * fast_sigmoid(zg0[j]); v1[j] += za1[j] * fast_sigmoid(zg1[j]); }
;                 u32x4 w; w.x = cvt_pk_bf16(v0[0], v0[1]); w.y = cvt_pk_bf16(v0[2], v0[3]); w.z = cvt_pk_bf16(v1[0], v1[1]); w.w = cvt_pk_bf16(v1[2], v1[3]);
;                 *(u32x4*)(HB + off) = w;
;                 float s = (v0[0] * v0[0] + v0[1] * v0[1]) + (v0[2] * v0[2] + v0[3] * v0[3]) + (v1[0] * v1[0] + v1[1] * v1[1]) + (v1[2] * v1[2] + v1[3] * v1[3]);
;                 s += __shfl_xor(s, 16); s += __shfl_xor(s, 32);
;                 if (fq == 0) unsafeAtomicAdd(ssq + r, s); }
	v_pk_fma_f32 v[172:173], v[92:93], v[84:85], v[172:173]
	v_pk_fma_f32 v[174:175], v[94:95], v[86:87], v[174:175]
	v_pk_fma_f32 v[168:169], v[88:89], v[80:81], v[168:169]
	v_pk_fma_f32 v[170:171], v[90:91], v[82:83], v[170:171]
	v_mul_f32_e32 v92, v172, v172
	v_mul_f32_e32 v93, v174, v174
	v_mul_f32_e32 v94, v168, v168
	v_mul_f32_e32 v95, v170, v170
	v_fmac_f32_e32 v92, v173, v173
	v_fmac_f32_e32 v93, v175, v175
	v_fmac_f32_e32 v94, v169, v169
	v_fmac_f32_e32 v95, v171, v171
	v_cvt_pk_bf16_f32 v84, v172, v173
	v_cvt_pk_bf16_f32 v85, v174, v175
	v_cvt_pk_bf16_f32 v86, v168, v169
	v_cvt_pk_bf16_f32 v87, v170, v171
	v_add_f32_e32 v92, v92, v93
	v_add_f32_e32 v94, v94, v95
	v_add_u32_e32 v193, 0x10000, v191
	v_add_f32_e32 v196, v92, v94
	global_store_dwordx4 v193, v[84:87], s[20:21]
	v_mov_b32_e32 v204, v196
	v_add_u32_e32 v193, 0x80, v192
	s_nop 0
	v_permlane16_swap_b32_e32 v196, v204
	v_add_f32_e32 v196, v196, v204
	v_mov_b32_e32 v204, v196
	s_nop 1
	v_permlane32_swap_b32_e32 v196, v204
	v_add_f32_e32 v196, v196, v204
	s_and_b64 exec, exec, s[4:5]
	global_atomic_add_f32 v193, v196, s[60:61]
	s_mov_b64 exec, s[0:1]
	s_waitcnt vmcnt(14)
	v_pk_fma_f32 v[164:165], v[76:77], v[68:69], v[164:165]
	v_pk_fma_f32 v[166:167], v[78:79], v[70:71], v[166:167]
	v_pk_fma_f32 v[160:161], v[72:73], v[64:65], v[160:161]
	v_pk_fma_f32 v[162:163], v[74:75], v[66:67], v[162:163]
	v_mul_f32_e32 v76, v164, v164
	v_mul_f32_e32 v77, v166, v166
	v_mul_f32_e32 v78, v160, v160
	v_mul_f32_e32 v79, v162, v162
	v_fmac_f32_e32 v76, v165, v165
	v_fmac_f32_e32 v77, v167, v167
	v_fmac_f32_e32 v78, v161, v161
	v_fmac_f32_e32 v79, v163, v163
	v_cvt_pk_bf16_f32 v68, v164, v165
	v_cvt_pk_bf16_f32 v69, v166, v167
	v_cvt_pk_bf16_f32 v70, v160, v161
	v_cvt_pk_bf16_f32 v71, v162, v163
	v_add_f32_e32 v76, v76, v77
	v_add_f32_e32 v78, v78, v79
	v_add_u32_e32 v193, 0x18000, v191
	v_add_f32_e32 v197, v76, v78
	global_store_dwordx4 v193, v[68:71], s[20:21]
	v_mov_b32_e32 v205, v197
	v_add_u32_e32 v193, 0xc0, v192
	s_nop 0
	v_permlane16_swap_b32_e32 v197, v205
	v_add_f32_e32 v197, v197, v205
	v_mov_b32_e32 v205, v197
	s_nop 1
	v_permlane32_swap_b32_e32 v197, v205
	v_add_f32_e32 v197, v197, v205
	s_and_b64 exec, exec, s[4:5]
	global_atomic_add_f32 v193, v197, s[60:61]
	s_mov_b64 exec, s[0:1]
	s_waitcnt vmcnt(14)
	v_pk_fma_f32 v[156:157], v[60:61], v[52:53], v[156:157]
	v_pk_fma_f32 v[158:159], v[62:63], v[54:55], v[158:159]
	v_pk_fma_f32 v[152:153], v[56:57], v[48:49], v[152:153]
	v_pk_fma_f32 v[154:155], v[58:59], v[50:51], v[154:155]
	v_mul_f32_e32 v60, v156, v156
	v_mul_f32_e32 v61, v158, v158
	v_mul_f32_e32 v62, v152, v152
	v_mul_f32_e32 v63, v154, v154
	v_fmac_f32_e32 v60, v157, v157
	v_fmac_f32_e32 v61, v159, v159
	v_fmac_f32_e32 v62, v153, v153
	v_fmac_f32_e32 v63, v155, v155
	v_cvt_pk_bf16_f32 v52, v156, v157
	v_cvt_pk_bf16_f32 v53, v158, v159
	v_cvt_pk_bf16_f32 v54, v152, v153
	v_cvt_pk_bf16_f32 v55, v154, v155
	v_add_f32_e32 v60, v60, v61
	v_add_f32_e32 v62, v62, v63
	v_add_u32_e32 v193, 0x40000, v191
	v_add_f32_e32 v198, v60, v62
	global_store_dwordx4 v193, v[52:55], s[20:21]
	v_mov_b32_e32 v124, v198
	v_add_u32_e32 v193, 0x200, v192
	s_nop 0
	v_permlane16_swap_b32_e32 v198, v124
	v_add_f32_e32 v198, v198, v124
	v_mov_b32_e32 v124, v198
	s_nop 1
	v_permlane32_swap_b32_e32 v198, v124
	v_add_f32_e32 v198, v198, v124
	s_and_b64 exec, exec, s[4:5]
	global_atomic_add_f32 v193, v198, s[60:61]
	s_mov_b64 exec, s[0:1]
	s_waitcnt vmcnt(14)
	v_pk_fma_f32 v[148:149], v[44:45], v[36:37], v[148:149]
	v_pk_fma_f32 v[150:151], v[46:47], v[38:39], v[150:151]
	v_pk_fma_f32 v[144:145], v[40:41], v[32:33], v[144:145]
	v_pk_fma_f32 v[146:147], v[42:43], v[34:35], v[146:147]
	v_mul_f32_e32 v44, v148, v148
	v_mul_f32_e32 v45, v150, v150
	v_mul_f32_e32 v46, v144, v144
	v_mul_f32_e32 v47, v146, v146
	v_fmac_f32_e32 v44, v149, v149
	v_fmac_f32_e32 v45, v151, v151
	v_fmac_f32_e32 v46, v145, v145
	v_fmac_f32_e32 v47, v147, v147
	v_cvt_pk_bf16_f32 v36, v148, v149
	v_cvt_pk_bf16_f32 v37, v150, v151
	v_cvt_pk_bf16_f32 v38, v144, v145
	v_cvt_pk_bf16_f32 v39, v146, v147
	v_add_f32_e32 v44, v44, v45
	v_add_f32_e32 v46, v46, v47
	v_add_u32_e32 v193, 0x48000, v191
	v_add_f32_e32 v199, v44, v46
	global_store_dwordx4 v193, v[36:39], s[20:21]
	v_mov_b32_e32 v125, v199
	v_add_u32_e32 v193, 0x240, v192
	s_nop 0
	v_permlane16_swap_b32_e32 v199, v125
	v_add_f32_e32 v199, v199, v125
	v_mov_b32_e32 v125, v199
	s_nop 1
	v_permlane32_swap_b32_e32 v199, v125
	v_add_f32_e32 v199, v199, v125
	s_and_b64 exec, exec, s[4:5]
	global_atomic_add_f32 v193, v199, s[60:61]
	s_mov_b64 exec, s[0:1]
	s_waitcnt vmcnt(14)
	v_pk_fma_f32 v[140:141], v[28:29], v[20:21], v[140:141]
	v_pk_fma_f32 v[142:143], v[30:31], v[22:23], v[142:143]
	v_pk_fma_f32 v[136:137], v[24:25], v[16:17], v[136:137]
	v_pk_fma_f32 v[138:139], v[26:27], v[18:19], v[138:139]
	v_mul_f32_e32 v28, v140, v140
	v_mul_f32_e32 v29, v142, v142
	v_mul_f32_e32 v30, v136, v136
	v_mul_f32_e32 v31, v138, v138
	v_fmac_f32_e32 v28, v141, v141
	v_fmac_f32_e32 v29, v143, v143
	v_fmac_f32_e32 v30, v137, v137
	v_fmac_f32_e32 v31, v139, v139
	v_cvt_pk_bf16_f32 v20, v140, v141
	v_cvt_pk_bf16_f32 v21, v142, v143
	v_cvt_pk_bf16_f32 v22, v136, v137
	v_cvt_pk_bf16_f32 v23, v138, v139
	v_add_f32_e32 v28, v28, v29
	v_add_f32_e32 v30, v30, v31
	v_add_u32_e32 v193, 0x50000, v191
	v_add_f32_e32 v200, v28, v30
	global_store_dwordx4 v193, v[20:23], s[20:21]
	v_mov_b32_e32 v126, v200
	v_add_u32_e32 v193, 0x280, v192
	s_nop 0
	v_permlane16_swap_b32_e32 v200, v126
	v_add_f32_e32 v200, v200, v126
	v_mov_b32_e32 v126, v200
	s_nop 1
	v_permlane32_swap_b32_e32 v200, v126
	v_add_f32_e32 v200, v200, v126
	s_and_b64 exec, exec, s[4:5]
	global_atomic_add_f32 v193, v200, s[60:61]
	s_mov_b64 exec, s[0:1]
	s_waitcnt vmcnt(14)
	v_pk_fma_f32 v[132:133], v[12:13], v[4:5], v[132:133]
	v_pk_fma_f32 v[134:135], v[14:15], v[6:7], v[134:135]
	v_pk_fma_f32 v[128:129], v[8:9], v[0:1], v[128:129]
	v_pk_fma_f32 v[130:131], v[10:11], v[2:3], v[130:131]
	v_mul_f32_e32 v12, v132, v132
	v_mul_f32_e32 v13, v134, v134
	v_mul_f32_e32 v14, v128, v128
	v_mul_f32_e32 v15, v130, v130
	v_fmac_f32_e32 v12, v133, v133
	v_fmac_f32_e32 v13, v135, v135
	v_fmac_f32_e32 v14, v129, v129
	v_fmac_f32_e32 v15, v131, v131
	v_cvt_pk_bf16_f32 v4, v132, v133
	v_cvt_pk_bf16_f32 v5, v134, v135
	v_cvt_pk_bf16_f32 v6, v128, v129
	v_cvt_pk_bf16_f32 v7, v130, v131
	v_add_f32_e32 v12, v12, v13
	v_add_f32_e32 v14, v14, v15
	v_add_u32_e32 v193, 0x58000, v191
	v_add_f32_e32 v201, v12, v14
	global_store_dwordx4 v193, v[4:7], s[20:21]
	v_mov_b32_e32 v127, v201
	v_add_u32_e32 v193, 0x2c0, v192
	s_nop 0
	v_permlane16_swap_b32_e32 v201, v127
	v_add_f32_e32 v201, v201, v127
	v_mov_b32_e32 v127, v201
	s_nop 1
	v_permlane32_swap_b32_e32 v201, v127
	v_add_f32_e32 v201, v201, v127
	s_and_b64 exec, exec, s[4:5]
	global_atomic_add_f32 v193, v201, s[60:61]
	s_mov_b64 exec, s[0:1]
	s_branch .LBB0_618

;     __device__ __forceinline__ void operator()(const Acc& acc, const Unit& u, int wr, int wc, int fr, int fq, LAS unsigned char* lds, f32x4 epar) const {
;     ...
;         LAS float* pw = (LAS float*)(lds + STAGE_BYTES + 64 + (wr * 4 + wc) * 1024);
;         *(LAS f32x4*)(pw + (fq * 16 + fr) * 4) = epar;
;         asm volatile("s_waitcnt lgkmcnt(0)" ::: "memory");
;         float w0[NV], w1[NV], w2[NV], bb[NV];
; #pragma unroll
;         for (int i = 0; i < NV; i += 4) { const f32x4 a = *(const LAS f32x4*)(pw + NV * fq + i), b = *(const LAS f32x4*)(pw + 32 + NV * fq + i), c = *(const LAS f32x4*)(pw + 64 + NV * fq + i);
;             f32x4 d = (f32x4){0.f, 0.f, 0.f, 0.f}; if (MODE == 0) d = *(const LAS f32x4*)(pw + 96 + NV * fq + i);
; #pragma unroll
;             for (int j = 0; j < 4; ++j) { w0[i + j] = a[j]; w1[i + j] = b[j]; w2[i + j] = c[j]; bb[i + j] = d[j]; } }
;         float sq[2][4];
; #pragma unroll
;         for (int ai = 0; ai < 2; ++ai)
; #pragma unroll
;             for (int m = 0; m < 4; ++m) sq[ai][m] = pw[128 + ai * 64 + m * 16 + fr];
; #pragma unroll
;         for (int ai = 0; ai < 2; ++ai) {
;             const int strip = u.pm * 4 + ai * 2 + wr;
;             float p1prev[NV], p2prev[NV];
; #pragma unroll
;             for (int i = 0; i < NV; ++i) { p1prev[i] = 0.f; p2prev[i] = 0.f; }
; #pragma unroll
;             for (int m = 0; m < 4; ++m) {
;                 const int r = u.pm * BM + ai * HALF + wr * 64 + m * 16 + fr;
;                 const float rs = __builtin_amdgcn_rsqf(sq[ai][m] * (1.0f / DM) + RMS_EPS);
;                 float X[NV], Y[NV], o[NV];
;                 if (MODE == 0) {
; #pragma unroll
;                     for (int n = 0; n < 2; ++n)
; #pragma unroll
;                         for (int j = 0; j < 4; ++j) { X[n * 4 + j] = acc[ai][0][m][n][j] * rs; Y[n * 4 + j] = acc[ai][1][m][n][j] * rs; }
;                 } else {
; #pragma unroll
;                     for (int j = 0; j < 4; ++j) { X[j] = (acc[ai][0][m][1][j] * rs) * (acc[ai][1][m][0][j] * rs); Y[j] = acc[ai][0][m][0][j] * rs; }
;                 }
; #pragma unroll
;                 for (int i = 0; i < NV; ++i) {
;                     const float a1 = dpp_rot<0x121>(X[i]), a2 = dpp_rot<0x122>(X[i]);
;                     const float q1 = fr >= 1 ? a1 : p1prev[i], q2 = fr >= 2 ? a2 : p2prev[i];
;                     p1prev[i] = a1; p2prev[i] = a2;
.LBB0_692:
	.p2align 6
	s_nop 0
	s_nop 0
	s_nop 0
	s_nop 0
	s_nop 0
	s_nop 0
	s_nop 0
	s_nop 0
	s_nop 0
	s_nop 0
	s_nop 0
	s_nop 0
	s_nop 0
	s_nop 0
	s_nop 0
	s_mov_b32 s100, 0xbfb8aa3b
	ds_write_b128 v198, v[72:75]
	s_mov_b64 s[24:25], exec
	s_waitcnt lgkmcnt(0)
	ds_read_b128 v[88:91], v199
	ds_read_b128 v[92:95], v199 offset:16
	ds_read_b128 v[128:131], v199 offset:128
	ds_read_b128 v[132:135], v199 offset:144
	ds_read_b128 v[136:139], v199 offset:256
	ds_read_b128 v[140:143], v199 offset:272
	ds_read_b128 v[174:177], v199 offset:384
	ds_read_b128 v[178:181], v199 offset:400
	ds_read2_b32 v[182:183], v191 offset0:128 offset1:144
	ds_read2_b32 v[184:185], v191 offset0:160 offset1:176
	ds_read2_b32 v[76:77], v191 offset0:192 offset1:208
	ds_read2_b32 v[78:79], v191 offset0:224 offset1:240
	v_lshl_add_u32 v230, s70, 8, v190
	v_lshl_or_b32 v231, s72, 7, v192
	v_mul_u32_u24_e32 v230, 0x1600, v230
	s_lshl_b32 s26, s70, 2
	s_add_i32 s26, s26, s14
	s_mul_i32 s16, s26, 6
	v_and_b32_e32 v233, 15, v190
	v_lshl_add_u32 v230, v231, 1, v230
	v_add_u32_e32 v233, s16, v233
	v_mul_u32_u24_e32 v233, 0x1600, v233
	s_nop 0
	v_lshl_add_u32 v233, v231, 1, v233
	s_waitcnt lgkmcnt(0)
	v_pk_mul_f32 v[88:89], s[100:101], v[88:89] op_sel_hi:[0,1]
	v_pk_mul_f32 v[90:91], s[100:101], v[90:91] op_sel_hi:[0,1]
	v_pk_mul_f32 v[92:93], s[100:101], v[92:93] op_sel_hi:[0,1]
	v_pk_mul_f32 v[94:95], s[100:101], v[94:95] op_sel_hi:[0,1]
	v_pk_mul_f32 v[128:129], s[100:101], v[128:129] op_sel_hi:[0,1]
	v_pk_mul_f32 v[130:131], s[100:101], v[130:131] op_sel_hi:[0,1]
	v_pk_mul_f32 v[132:133], s[100:101], v[132:133] op_sel_hi:[0,1]
	v_pk_mul_f32 v[134:135], s[100:101], v[134:135] op_sel_hi:[0,1]
	v_pk_mul_f32 v[136:137], s[100:101], v[136:137] op_sel_hi:[0,1]
	v_pk_mul_f32 v[138:139], s[100:101], v[138:139] op_sel_hi:[0,1]
	v_pk_mul_f32 v[140:141], s[100:101], v[140:141] op_sel_hi:[0,1]
	v_pk_mul_f32 v[142:143], s[100:101], v[142:143] op_sel_hi:[0,1]
	v_pk_mul_f32 v[174:175], s[100:101], v[174:175] op_sel_hi:[0,1]
	v_pk_mul_f32 v[176:177], s[100:101], v[176:177] op_sel_hi:[0,1]
	v_pk_mul_f32 v[178:179], s[100:101], v[178:179] op_sel_hi:[0,1]
	v_pk_mul_f32 v[180:181], s[100:101], v[180:181] op_sel_hi:[0,1]
	v_fmamk_f32 v182, v182, 0x3a800000, v200
	v_fmamk_f32 v183, v183, 0x3a800000, v200
	v_fmamk_f32 v184, v184, 0x3a800000, v200
	v_fmamk_f32 v185, v185, 0x3a800000, v200
	v_fmamk_f32 v76, v76, 0x3a800000, v200
	v_fmamk_f32 v77, v77, 0x3a800000, v200
	v_fmamk_f32 v78, v78, 0x3a800000, v200
	v_fmamk_f32 v79, v79, 0x3a800000, v200
	v_pk_mul_f32 v[202:203], s[100:101], v[182:183] op_sel_hi:[0,1]
	v_pk_mul_f32 v[204:205], s[100:101], v[184:185] op_sel_hi:[0,1]
	v_pk_mul_f32 v[206:207], s[100:101], v[76:77] op_sel_hi:[0,1]
	v_pk_mul_f32 v[208:209], s[100:101], v[78:79] op_sel_hi:[0,1]
	v_rsq_f32_e32 v182, v182
	v_rsq_f32_e32 v183, v183
	v_rsq_f32_e32 v184, v184
	v_rsq_f32_e32 v185, v185
	v_rsq_f32_e32 v76, v76
	v_rsq_f32_e32 v77, v77
	v_rsq_f32_e32 v78, v78
	v_rsq_f32_e32 v79, v79
	s_nop 0
	v_pk_mul_f32 v[202:203], v[202:203], v[182:183]
	v_pk_mul_f32 v[204:205], v[204:205], v[184:185]
	v_pk_mul_f32 v[206:207], v[206:207], v[76:77]
	v_pk_mul_f32 v[208:209], v[208:209], v[78:79]
	v_pk_mul_f32 v[152:153], v[152:153], v[182:183] op_sel_hi:[1,0]
	v_pk_mul_f32 v[154:155], v[154:155], v[182:183] op_sel_hi:[1,0]
	v_pk_mul_f32 v[144:145], v[144:145], v[182:183] op_sel_hi:[1,0]
	v_pk_mul_f32 v[146:147], v[146:147], v[182:183] op_sel_hi:[1,0]
	v_pk_fma_f32 v[210:211], v[152:153], v[136:137], v[174:175]
	v_pk_fma_f32 v[212:213], v[154:155], v[138:139], v[176:177]
	v_pk_fma_f32 v[214:215], v[144:145], v[140:141], v[178:179]
	v_pk_fma_f32 v[216:217], v[146:147], v[142:143], v[180:181]
	v_pk_mul_f32 v[218:219], v[156:157], v[182:183] op_sel_hi:[1,0]
	v_pk_mul_f32 v[220:221], v[158:159], v[182:183] op_sel_hi:[1,0]
	v_pk_mul_f32 v[222:223], v[148:149], v[182:183] op_sel_hi:[1,0]
	v_pk_mul_f32 v[224:225], v[150:151], v[182:183] op_sel_hi:[1,0]
	v_cvt_pk_bf16_f32 v236, v152, v153
	v_cvt_pk_bf16_f32 v237, v154, v155
	v_cvt_pk_bf16_f32 v238, v144, v145
	v_cvt_pk_bf16_f32 v239, v146, v147
	v_cvt_pk_bf16_f32 v240, v218, v219
	v_cvt_pk_bf16_f32 v241, v220, v221
	v_cvt_pk_bf16_f32 v242, v222, v223
	v_cvt_pk_bf16_f32 v243, v224, v225
	v_add_u32_e32 v234, 0x2c00, v233
	v_add_u32_e32 v235, 0x5800, v233
	s_andn2_b64 exec, exec, s[8:9]
	global_store_dwordx4 v234, v[236:239], s[42:43]
	global_store_dwordx4 v235, v[240:243], s[42:43]
	s_mov_b64 exec, s[24:25]
	v_fmac_f32_dpp v210, v152, v128 row_shr:1 row_mask:0xf bank_mask:0xf
	v_fmac_f32_dpp v211, v153, v129 row_shr:1 row_mask:0xf bank_mask:0xf
	v_fmac_f32_dpp v212, v154, v130 row_shr:1 row_mask:0xf bank_mask:0xf
	v_fmac_f32_dpp v213, v155, v131 row_shr:1 row_mask:0xf bank_mask:0xf
	v_fmac_f32_dpp v214, v144, v132 row_shr:1 row_mask:0xf bank_mask:0xf
	v_fmac_f32_dpp v215, v145, v133 row_shr:1 row_mask:0xf bank_mask:0xf
	v_fmac_f32_dpp v216, v146, v134 row_shr:1 row_mask:0xf bank_mask:0xf
	v_fmac_f32_dpp v217, v147, v135 row_shr:1 row_mask:0xf bank_mask:0xf
	v_fmac_f32_dpp v210, v152, v88 row_shr:2 row_mask:0xf bank_mask:0xf
	v_fmac_f32_dpp v211, v153, v89 row_shr:2 row_mask:0xf bank_mask:0xf
	v_fmac_f32_dpp v212, v154, v90 row_shr:2 row_mask:0xf bank_mask:0xf
	v_fmac_f32_dpp v213, v155, v91 row_shr:2 row_mask:0xf bank_mask:0xf
	v_fmac_f32_dpp v214, v144, v92 row_shr:2 row_mask:0xf bank_mask:0xf
	v_fmac_f32_dpp v215, v145, v93 row_shr:2 row_mask:0xf bank_mask:0xf
	v_fmac_f32_dpp v216, v146, v94 row_shr:2 row_mask:0xf bank_mask:0xf
	v_fmac_f32_dpp v217, v147, v95 row_shr:2 row_mask:0xf bank_mask:0xf
	v_exp_f32_e32 v218, v210
	v_exp_f32_e32 v219, v211
; __device__ __forceinline__ unsigned cvt_pk_bf16(float lo, float hi) { unsigned r; asm volatile("v_cvt_pk_bf16_f32 %0, %1, %2" : "=v"(r) : "v"(lo), "v"(hi)); return r; }
; __device__ __forceinline__ float silu_f(float x) { return x * __builtin_amdgcn_rcpf(1.0f + __builtin_amdgcn_exp2f(x * -1.44269504f)); }
; template <int CTRL> __device__ __forceinline__ float dpp_rot(float x) { return __int_as_float(__builtin_amdgcn_mov_dpp(__float_as_int(x), CTRL, 0xf, 0xf, false)); }
;     __device__ __forceinline__ void operator()(const Acc& acc, const Unit& u, int wr, int wc, int fr, int fq, LAS unsigned char* lds, f32x4 epar) const {
;     ...
; #pragma unroll
;                 for (int i = 0; i < NV; ++i) {
;                     const float a1 = dpp_rot<0x121>(X[i]), a2 = dpp_rot<0x122>(X[i]);
;                     const float q1 = fr >= 1 ? a1 : p1prev[i], q2 = fr >= 2 ? a2 : p2prev[i];
;                     p1prev[i] = a1; p2prev[i] = a2;
;                     const float cv = w2[i] * X[i] + w1[i] * q1 + w0[i] * q2 + bb[i];
;                     o[i] = MODE == 0 ? silu_f(cv) * Y[i] : cv * Y[i];
;                 }
;                 if (m == 0 && fr < 2) {
;                     bf16_t* hx = halo + ((size_t)strip * 6 + 2 + fr) * C + c0; bf16_t* hy = halo + ((size_t)strip * 6 + 4 + fr) * C + c0;
;                     u32x4 px, py; px.x = cvt_pk_bf16(X[0], X[1]); px.y = cvt_pk_bf16(X[2], X[3]); px.z = cvt_pk_bf16(X[4 % NV], X[5 % NV]); px.w = cvt_pk_bf16(X[6 % NV], X[7 % NV]);
;                     py.x = cvt_pk_bf16(Y[0], Y[1]); py.y = cvt_pk_bf16(Y[2], Y[3]); py.z = cvt_pk_bf16(Y[4 % NV], Y[5 % NV]); py.w = cvt_pk_bf16(Y[6 % NV], Y[7 % NV]);
;                     if (MODE == 0) { *(u32x4*)hx = px; *(u32x4*)hy = py; } else { u32x2 a; a.x = px.x; a.y = px.y; *(u32x2*)hx = a; u32x2 b; b.x = py.x; b.y = py.y; *(u32x2*)hy = b; }
;                 } else {
;                     if (MODE == 0) { u32x4 w; w.x = cvt_pk_bf16(o[0], o[1]); w.y = cvt_pk_bf16(o[2], o[3]); w.z = cvt_pk_bf16(o[4 % NV], o[5 % NV]); w.w = cvt_pk_bf16(o[6 % NV], o[7 % NV]);
;                         __builtin_nontemporal_store(w, (u32x4*)(out + (size_t)r * C + c0)); }
;                     else { u32x2 w; w.x = cvt_pk_bf16(o[0], o[1]); w.y = cvt_pk_bf16(o[2], o[3]); __builtin_nontemporal_store(w, (u32x2*)(out + (size_t)r * C + c0)); }
;                 }
	v_exp_f32_e32 v220, v212
	v_exp_f32_e32 v221, v213
	v_exp_f32_e32 v222, v214
	v_exp_f32_e32 v223, v215
	v_exp_f32_e32 v224, v216
	v_exp_f32_e32 v225, v217
	v_pk_fma_f32 v[218:219], v[218:219], v[202:203], v[202:203] op_sel_hi:[1,0,0]
	v_pk_fma_f32 v[220:221], v[220:221], v[202:203], v[202:203] op_sel_hi:[1,0,0]
	v_pk_fma_f32 v[222:223], v[222:223], v[202:203], v[202:203] op_sel_hi:[1,0,0]
	v_pk_fma_f32 v[224:225], v[224:225], v[202:203], v[202:203] op_sel_hi:[1,0,0]
	v_rcp_f32_e32 v218, v218
	v_rcp_f32_e32 v219, v219
	v_rcp_f32_e32 v220, v220
	v_rcp_f32_e32 v221, v221
	v_rcp_f32_e32 v222, v222
	v_rcp_f32_e32 v223, v223
	v_rcp_f32_e32 v224, v224
	v_rcp_f32_e32 v225, v225
	v_pk_mul_f32 v[210:211], v[210:211], v[218:219]
	v_pk_mul_f32 v[212:213], v[212:213], v[220:221]
	v_pk_mul_f32 v[214:215], v[214:215], v[222:223]
	v_pk_mul_f32 v[216:217], v[216:217], v[224:225]
	v_pk_mul_f32 v[156:157], v[210:211], v[156:157]
	v_pk_mul_f32 v[158:159], v[212:213], v[158:159]
	v_pk_mul_f32 v[148:149], v[214:215], v[148:149]
	v_pk_mul_f32 v[150:151], v[216:217], v[150:151]
	v_cvt_pk_bf16_f32 v226, v156, v157
	v_cvt_pk_bf16_f32 v227, v158, v159
	v_cvt_pk_bf16_f32 v228, v148, v149
	v_cvt_pk_bf16_f32 v229, v150, v151
	v_add_u32_e32 v234, 0x0, v230
	s_and_b64 exec, exec, s[8:9]
	global_store_dwordx4 v234, v[226:229], s[96:97] nt
	s_mov_b64 exec, s[24:25]
	v_pk_mul_f32 v[124:125], v[124:125], v[182:183] op_sel:[0,1]
	v_pk_mul_f32 v[126:127], v[126:127], v[182:183] op_sel:[0,1]
	v_pk_mul_f32 v[120:121], v[120:121], v[182:183] op_sel:[0,1]
	v_pk_mul_f32 v[122:123], v[122:123], v[182:183] op_sel:[0,1]
	v_pk_fma_f32 v[210:211], v[124:125], v[136:137], v[174:175]
	v_pk_fma_f32 v[212:213], v[126:127], v[138:139], v[176:177]
	v_pk_fma_f32 v[214:215], v[120:121], v[140:141], v[178:179]
	v_pk_fma_f32 v[216:217], v[122:123], v[142:143], v[180:181]
	v_fmac_f32_dpp v210, v124, v128 row_shr:1 row_mask:0xf bank_mask:0xf
	v_fmac_f32_dpp v211, v125, v129 row_shr:1 row_mask:0xf bank_mask:0xf
	v_fmac_f32_dpp v212, v126, v130 row_shr:1 row_mask:0xf bank_mask:0xf
	v_fmac_f32_dpp v213, v127, v131 row_shr:1 row_mask:0xf bank_mask:0xf
	v_fmac_f32_dpp v214, v120, v132 row_shr:1 row_mask:0xf bank_mask:0xf
	v_fmac_f32_dpp v215, v121, v133 row_shr:1 row_mask:0xf bank_mask:0xf
	v_fmac_f32_dpp v216, v122, v134 row_shr:1 row_mask:0xf bank_mask:0xf
	v_fmac_f32_dpp v217, v123, v135 row_shr:1 row_mask:0xf bank_mask:0xf
	v_fmac_f32_dpp v210, v124, v88 row_shr:2 row_mask:0xf bank_mask:0xf
	v_fmac_f32_dpp v211, v125, v89 row_shr:2 row_mask:0xf bank_mask:0xf
	v_fmac_f32_dpp v212, v126, v90 row_shr:2 row_mask:0xf bank_mask:0xf
	v_fmac_f32_dpp v213, v127, v91 row_shr:2 row_mask:0xf bank_mask:0xf
	v_fmac_f32_dpp v214, v120, v92 row_shr:2 row_mask:0xf bank_mask:0xf
	v_fmac_f32_dpp v215, v121, v93 row_shr:2 row_mask:0xf bank_mask:0xf
	v_fmac_f32_dpp v216, v122, v94 row_shr:2 row_mask:0xf bank_mask:0xf
	v_fmac_f32_dpp v217, v123, v95 row_shr:2 row_mask:0xf bank_mask:0xf
	v_fmac_f32_dpp v210, v152, v128 row_shl:15 row_mask:0xf bank_mask:0xf
	v_fmac_f32_dpp v211, v153, v129 row_shl:15 row_mask:0xf bank_mask:0xf
	v_fmac_f32_dpp v212, v154, v130 row_shl:15 row_mask:0xf bank_mask:0xf
	v_fmac_f32_dpp v213, v155, v131 row_shl:15 row_mask:0xf bank_mask:0xf
	v_fmac_f32_dpp v214, v144, v132 row_shl:15 row_mask:0xf bank_mask:0xf
	v_fmac_f32_dpp v215, v145, v133 row_shl:15 row_mask:0xf bank_mask:0xf
	v_fmac_f32_dpp v216, v146, v134 row_shl:15 row_mask:0xf bank_mask:0xf
	v_fmac_f32_dpp v217, v147, v135 row_shl:15 row_mask:0xf bank_mask:0xf
	v_fmac_f32_dpp v210, v152, v88 row_shl:14 row_mask:0xf bank_mask:0xf
	v_fmac_f32_dpp v211, v153, v89 row_shl:14 row_mask:0xf bank_mask:0xf
	v_fmac_f32_dpp v212, v154, v90 row_shl:14 row_mask:0xf bank_mask:0xf
	v_fmac_f32_dpp v213, v155, v91 row_shl:14 row_mask:0xf bank_mask:0xf
	v_fmac_f32_dpp v214, v144, v92 row_shl:14 row_mask:0xf bank_mask:0xf
	v_fmac_f32_dpp v215, v145, v93 row_shl:14 row_mask:0xf bank_mask:0xf
	v_fmac_f32_dpp v216, v146, v94 row_shl:14 row_mask:0xf bank_mask:0xf
	v_fmac_f32_dpp v217, v147, v95 row_shl:14 row_mask:0xf bank_mask:0xf
	v_exp_f32_e32 v218, v210
	v_exp_f32_e32 v219, v211
	v_exp_f32_e32 v220, v212
	v_exp_f32_e32 v221, v213
	v_exp_f32_e32 v222, v214
	v_exp_f32_e32 v223, v215
	v_exp_f32_e32 v224, v216
	v_exp_f32_e32 v225, v217
	v_pk_fma_f32 v[218:219], v[218:219], v[202:203], v[202:203] op_sel:[0,1,1]
	v_pk_fma_f32 v[220:221], v[220:221], v[202:203], v[202:203] op_sel:[0,1,1]
	v_pk_fma_f32 v[222:223], v[222:223], v[202:203], v[202:203] op_sel:[0,1,1]
	v_pk_fma_f32 v[224:225], v[224:225], v[202:203], v[202:203] op_sel:[0,1,1]
	v_rcp_f32_e32 v218, v218
	v_rcp_f32_e32 v219, v219
	v_rcp_f32_e32 v220, v220
	v_rcp_f32_e32 v221, v221
	v_rcp_f32_e32 v222, v222
	v_rcp_f32_e32 v223, v223
	v_rcp_f32_e32 v224, v224
	v_rcp_f32_e32 v225, v225
	v_pk_mul_f32 v[210:211], v[210:211], v[218:219]
	v_pk_mul_f32 v[212:213], v[212:213], v[220:221]
	v_pk_mul_f32 v[214:215], v[214:215], v[222:223]
	v_pk_mul_f32 v[216:217], v[216:217], v[224:225]
	v_pk_mul_f32 v[116:117], v[210:211], v[116:117]
	v_pk_mul_f32 v[118:119], v[212:213], v[118:119]
	v_pk_mul_f32 v[112:113], v[214:215], v[112:113]
	v_pk_mul_f32 v[114:115], v[216:217], v[114:115]
	v_cvt_pk_bf16_f32 v226, v116, v117
	v_cvt_pk_bf16_f32 v227, v118, v119
	v_cvt_pk_bf16_f32 v228, v112, v113
	v_cvt_pk_bf16_f32 v229, v114, v115
	v_add_u32_e32 v234, 0x16000, v230
	global_store_dwordx4 v234, v[226:229], s[96:97] nt
	v_pk_mul_f32 v[108:109], v[108:109], v[184:185] op_sel_hi:[1,0]
	v_pk_mul_f32 v[110:111], v[110:111], v[184:185] op_sel_hi:[1,0]
	v_pk_mul_f32 v[104:105], v[104:105], v[184:185] op_sel_hi:[1,0]
;     __device__ __forceinline__ void operator()(const Acc& acc, const Unit& u, int wr, int wc, int fr, int fq, LAS unsigned char* lds, f32x4 epar) const {
;     ...
; #pragma unroll
;             for (int m = 0; m < 4; ++m) {
;                 const int r = u.pm * BM + ai * HALF + wr * 64 + m * 16 + fr;
;                 const float rs = __builtin_amdgcn_rsqf(sq[ai][m] * (1.0f / DM) + RMS_EPS);
;                 float X[NV], Y[NV], o[NV];
;                 if (MODE == 0) {
; #pragma unroll
;                     for (int n = 0; n < 2; ++n)
; #pragma unroll
;                         for (int j = 0; j < 4; ++j) { X[n * 4 + j] = acc[ai][0][m][n][j] * rs; Y[n * 4 + j] = acc[ai][1][m][n][j] * rs; }
;                 } else {
; #pragma unroll
;                     for (int j = 0; j < 4; ++j) { X[j] = (acc[ai][0][m][1][j] * rs) * (acc[ai][1][m][0][j] * rs); Y[j] = acc[ai][0][m][0][j] * rs; }
;                 }
; #pragma unroll
;                 for (int i = 0; i < NV; ++i) {
;                     const float a1 = dpp_rot<0x121>(X[i]), a2 = dpp_rot<0x122>(X[i]);
;                     const float q1 = fr >= 1 ? a1 : p1prev[i], q2 = fr >= 2 ? a2 : p2prev[i];
;                     p1prev[i] = a1; p2prev[i] = a2;
;                     const float cv = w2[i] * X[i] + w1[i] * q1 + w0[i] * q2 + bb[i];
;                     o[i] = MODE == 0 ? silu_f(cv) * Y[i] : cv * Y[i];
;                 }
;                 if (m == 0 && fr < 2) {
;                     bf16_t* hx = halo + ((size_t)strip * 6 + 2 + fr) * C + c0; bf16_t* hy = halo + ((size_t)strip * 6 + 4 + fr) * C + c0;
;                     u32x4 px, py; px.x = cvt_pk_bf16(X[0], X[1]); px.y = cvt_pk_bf16(X[2], X[3]); px.z = cvt_pk_bf16(X[4 % NV], X[5 % NV]); px.w = cvt_pk_bf16(X[6 % NV], X[7 % NV]);
;                     py.x = cvt_pk_bf16(Y[0], Y[1]); py.y = cvt_pk_bf16(Y[2], Y[3]); py.z = cvt_pk_bf16(Y[4 % NV], Y[5 % NV]); py.w = cvt_pk_bf16(Y[6 % NV], Y[7 % NV]);
;                     if (MODE == 0) { *(u32x4*)hx = px; *(u32x4*)hy = py; } else { u32x2 a; a.x = px.x; a.y = px.y; *(u32x2*)hx = a; u32x2 b; b.x = py.x; b.y = py.y; *(u32x2*)hy = b; }
;                 } else {
;                     if (MODE == 0) { u32x4 w; w.x = cvt_pk_bf16(o[0], o[1]); w.y = cvt_pk_bf16(o[2], o[3]); w.z = cvt_pk_bf16(o[4 % NV], o[5 % NV]); w.w = cvt_pk_bf16(o[6 % NV], o[7 % NV]);
	v_pk_mul_f32 v[106:107], v[106:107], v[184:185] op_sel_hi:[1,0]
	v_pk_fma_f32 v[210:211], v[108:109], v[136:137], v[174:175]
	v_pk_fma_f32 v[212:213], v[110:111], v[138:139], v[176:177]
	v_pk_fma_f32 v[214:215], v[104:105], v[140:141], v[178:179]
	v_pk_fma_f32 v[216:217], v[106:107], v[142:143], v[180:181]
	v_fmac_f32_dpp v210, v108, v128 row_shr:1 row_mask:0xf bank_mask:0xf
	v_fmac_f32_dpp v211, v109, v129 row_shr:1 row_mask:0xf bank_mask:0xf
	v_fmac_f32_dpp v212, v110, v130 row_shr:1 row_mask:0xf bank_mask:0xf
	v_fmac_f32_dpp v213, v111, v131 row_shr:1 row_mask:0xf bank_mask:0xf
	v_fmac_f32_dpp v214, v104, v132 row_shr:1 row_mask:0xf bank_mask:0xf
	v_fmac_f32_dpp v215, v105, v133 row_shr:1 row_mask:0xf bank_mask:0xf
	v_fmac_f32_dpp v216, v106, v134 row_shr:1 row_mask:0xf bank_mask:0xf
	v_fmac_f32_dpp v217, v107, v135 row_shr:1 row_mask:0xf bank_mask:0xf
	v_fmac_f32_dpp v210, v108, v88 row_shr:2 row_mask:0xf bank_mask:0xf
	v_fmac_f32_dpp v211, v109, v89 row_shr:2 row_mask:0xf bank_mask:0xf
	v_fmac_f32_dpp v212, v110, v90 row_shr:2 row_mask:0xf bank_mask:0xf
	v_fmac_f32_dpp v213, v111, v91 row_shr:2 row_mask:0xf bank_mask:0xf
	v_fmac_f32_dpp v214, v104, v92 row_shr:2 row_mask:0xf bank_mask:0xf
	v_fmac_f32_dpp v215, v105, v93 row_shr:2 row_mask:0xf bank_mask:0xf
	v_fmac_f32_dpp v216, v106, v94 row_shr:2 row_mask:0xf bank_mask:0xf
	v_fmac_f32_dpp v217, v107, v95 row_shr:2 row_mask:0xf bank_mask:0xf
	v_fmac_f32_dpp v210, v124, v128 row_shl:15 row_mask:0xf bank_mask:0xf
	v_fmac_f32_dpp v211, v125, v129 row_shl:15 row_mask:0xf bank_mask:0xf
	v_fmac_f32_dpp v212, v126, v130 row_shl:15 row_mask:0xf bank_mask:0xf
	v_fmac_f32_dpp v213, v127, v131 row_shl:15 row_mask:0xf bank_mask:0xf
	v_fmac_f32_dpp v214, v120, v132 row_shl:15 row_mask:0xf bank_mask:0xf
	v_fmac_f32_dpp v215, v121, v133 row_shl:15 row_mask:0xf bank_mask:0xf
	v_fmac_f32_dpp v216, v122, v134 row_shl:15 row_mask:0xf bank_mask:0xf
	v_fmac_f32_dpp v217, v123, v135 row_shl:15 row_mask:0xf bank_mask:0xf
	v_fmac_f32_dpp v210, v124, v88 row_shl:14 row_mask:0xf bank_mask:0xf
	v_fmac_f32_dpp v211, v125, v89 row_shl:14 row_mask:0xf bank_mask:0xf
	v_fmac_f32_dpp v212, v126, v90 row_shl:14 row_mask:0xf bank_mask:0xf
	v_fmac_f32_dpp v213, v127, v91 row_shl:14 row_mask:0xf bank_mask:0xf
	v_fmac_f32_dpp v214, v120, v92 row_shl:14 row_mask:0xf bank_mask:0xf
	v_fmac_f32_dpp v215, v121, v93 row_shl:14 row_mask:0xf bank_mask:0xf
	v_fmac_f32_dpp v216, v122, v94 row_shl:14 row_mask:0xf bank_mask:0xf
	v_fmac_f32_dpp v217, v123, v95 row_shl:14 row_mask:0xf bank_mask:0xf
	v_exp_f32_e32 v218, v210
	v_exp_f32_e32 v219, v211
	v_exp_f32_e32 v220, v212
	v_exp_f32_e32 v221, v213
	v_exp_f32_e32 v222, v214
	v_exp_f32_e32 v223, v215
	v_exp_f32_e32 v224, v216
	v_exp_f32_e32 v225, v217
	v_pk_fma_f32 v[218:219], v[218:219], v[204:205], v[204:205] op_sel_hi:[1,0,0]
	v_pk_fma_f32 v[220:221], v[220:221], v[204:205], v[204:205] op_sel_hi:[1,0,0]
	v_pk_fma_f32 v[222:223], v[222:223], v[204:205], v[204:205] op_sel_hi:[1,0,0]
	v_pk_fma_f32 v[224:225], v[224:225], v[204:205], v[204:205] op_sel_hi:[1,0,0]
	v_rcp_f32_e32 v218, v218
	v_rcp_f32_e32 v219, v219
	v_rcp_f32_e32 v220, v220
	v_rcp_f32_e32 v221, v221
	v_rcp_f32_e32 v222, v222
	v_rcp_f32_e32 v223, v223
	v_rcp_f32_e32 v224, v224
	v_rcp_f32_e32 v225, v225
	v_pk_mul_f32 v[210:211], v[210:211], v[218:219]
	v_pk_mul_f32 v[212:213], v[212:213], v[220:221]
	v_pk_mul_f32 v[214:215], v[214:215], v[222:223]
	v_pk_mul_f32 v[216:217], v[216:217], v[224:225]
	v_pk_mul_f32 v[100:101], v[210:211], v[100:101]
	v_pk_mul_f32 v[102:103], v[212:213], v[102:103]
	v_pk_mul_f32 v[96:97], v[214:215], v[96:97]
	v_pk_mul_f32 v[98:99], v[216:217], v[98:99]
	v_cvt_pk_bf16_f32 v226, v100, v101
	v_cvt_pk_bf16_f32 v227, v102, v103
	v_cvt_pk_bf16_f32 v228, v96, v97
	v_cvt_pk_bf16_f32 v229, v98, v99
	v_add_u32_e32 v234, 0x2c000, v230
	global_store_dwordx4 v234, v[226:229], s[96:97] nt
	v_pk_mul_f32 v[84:85], v[84:85], v[184:185] op_sel:[0,1]
	v_pk_mul_f32 v[86:87], v[86:87], v[184:185] op_sel:[0,1]
	v_pk_mul_f32 v[80:81], v[80:81], v[184:185] op_sel:[0,1]
	v_pk_mul_f32 v[82:83], v[82:83], v[184:185] op_sel:[0,1]
	v_pk_fma_f32 v[210:211], v[84:85], v[136:137], v[174:175]
	v_pk_fma_f32 v[212:213], v[86:87], v[138:139], v[176:177]
	v_pk_fma_f32 v[214:215], v[80:81], v[140:141], v[178:179]
	v_pk_fma_f32 v[216:217], v[82:83], v[142:143], v[180:181]
	v_cvt_pk_bf16_f32 v236, v84, v85
	v_cvt_pk_bf16_f32 v237, v86, v87
	v_cvt_pk_bf16_f32 v238, v80, v81
	v_cvt_pk_bf16_f32 v239, v82, v83
	v_add_u32_e32 v235, 0xfffecc00, v233
	s_and_b64 exec, exec, s[10:11]
	global_store_dwordx4 v235, v[236:239], s[42:43]
	s_mov_b64 exec, s[24:25]
	v_fmac_f32_dpp v210, v84, v128 row_shr:1 row_mask:0xf bank_mask:0xf
	v_fmac_f32_dpp v211, v85, v129 row_shr:1 row_mask:0xf bank_mask:0xf
	v_fmac_f32_dpp v212, v86, v130 row_shr:1 row_mask:0xf bank_mask:0xf
	v_fmac_f32_dpp v213, v87, v131 row_shr:1 row_mask:0xf bank_mask:0xf
	v_fmac_f32_dpp v214, v80, v132 row_shr:1 row_mask:0xf bank_mask:0xf
	v_fmac_f32_dpp v215, v81, v133 row_shr:1 row_mask:0xf bank_mask:0xf
	v_fmac_f32_dpp v216, v82, v134 row_shr:1 row_mask:0xf bank_mask:0xf
	v_fmac_f32_dpp v217, v83, v135 row_shr:1 row_mask:0xf bank_mask:0xf
	v_fmac_f32_dpp v210, v84, v88 row_shr:2 row_mask:0xf bank_mask:0xf
	v_fmac_f32_dpp v211, v85, v89 row_shr:2 row_mask:0xf bank_mask:0xf
	v_fmac_f32_dpp v212, v86, v90 row_shr:2 row_mask:0xf bank_mask:0xf
	v_fmac_f32_dpp v213, v87, v91 row_shr:2 row_mask:0xf bank_mask:0xf
	v_fmac_f32_dpp v214, v80, v92 row_shr:2 row_mask:0xf bank_mask:0xf
	v_fmac_f32_dpp v215, v81, v93 row_shr:2 row_mask:0xf bank_mask:0xf
	v_fmac_f32_dpp v216, v82, v94 row_shr:2 row_mask:0xf bank_mask:0xf
;     __device__ __forceinline__ void operator()(const Acc& acc, const Unit& u, int wr, int wc, int fr, int fq, LAS unsigned char* lds, f32x4 epar) const {
;     ...
;         for (int ai = 0; ai < 2; ++ai) {
;             const int strip = u.pm * 4 + ai * 2 + wr;
;             float p1prev[NV], p2prev[NV];
; #pragma unroll
;             for (int i = 0; i < NV; ++i) { p1prev[i] = 0.f; p2prev[i] = 0.f; }
; #pragma unroll
;             for (int m = 0; m < 4; ++m) {
;                 const int r = u.pm * BM + ai * HALF + wr * 64 + m * 16 + fr;
;                 const float rs = __builtin_amdgcn_rsqf(sq[ai][m] * (1.0f / DM) + RMS_EPS);
;                 float X[NV], Y[NV], o[NV];
;                 if (MODE == 0) {
; #pragma unroll
;                     for (int n = 0; n < 2; ++n)
; #pragma unroll
;                         for (int j = 0; j < 4; ++j) { X[n * 4 + j] = acc[ai][0][m][n][j] * rs; Y[n * 4 + j] = acc[ai][1][m][n][j] * rs; }
;                 } else {
; #pragma unroll
;                     for (int j = 0; j < 4; ++j) { X[j] = (acc[ai][0][m][1][j] * rs) * (acc[ai][1][m][0][j] * rs); Y[j] = acc[ai][0][m][0][j] * rs; }
;                 }
; #pragma unroll
;                 for (int i = 0; i < NV; ++i) {
;                     const float a1 = dpp_rot<0x121>(X[i]), a2 = dpp_rot<0x122>(X[i]);
;                     const float q1 = fr >= 1 ? a1 : p1prev[i], q2 = fr >= 2 ? a2 : p2prev[i];
;                     p1prev[i] = a1; p2prev[i] = a2;
;                     const float cv = w2[i] * X[i] + w1[i] * q1 + w0[i] * q2 + bb[i];
;                     o[i] = MODE == 0 ? silu_f(cv) * Y[i] : cv * Y[i];
;                 }
;                 if (m == 0 && fr < 2) {
;                     bf16_t* hx = halo + ((size_t)strip * 6 + 2 + fr) * C + c0; bf16_t* hy = halo + ((size_t)strip * 6 + 4 + fr) * C + c0;
;                     u32x4 px, py; px.x = cvt_pk_bf16(X[0], X[1]); px.y = cvt_pk_bf16(X[2], X[3]); px.z = cvt_pk_bf16(X[4 % NV], X[5 % NV]); px.w = cvt_pk_bf16(X[6 % NV], X[7 % NV]);
;                     py.x = cvt_pk_bf16(Y[0], Y[1]); py.y = cvt_pk_bf16(Y[2], Y[3]); py.z = cvt_pk_bf16(Y[4 % NV], Y[5 % NV]); py.w = cvt_pk_bf16(Y[6 % NV], Y[7 % NV]);
;                     if (MODE == 0) { *(u32x4*)hx = px; *(u32x4*)hy = py; } else { u32x2 a; a.x = px.x; a.y = px.y; *(u32x2*)hx = a; u32x2 b; b.x = py.x; b.y = py.y; *(u32x2*)hy = b; }
;                 } else {
	v_fmac_f32_dpp v217, v83, v95 row_shr:2 row_mask:0xf bank_mask:0xf
	v_fmac_f32_dpp v210, v108, v128 row_shl:15 row_mask:0xf bank_mask:0xf
	v_fmac_f32_dpp v211, v109, v129 row_shl:15 row_mask:0xf bank_mask:0xf
	v_fmac_f32_dpp v212, v110, v130 row_shl:15 row_mask:0xf bank_mask:0xf
	v_fmac_f32_dpp v213, v111, v131 row_shl:15 row_mask:0xf bank_mask:0xf
	v_fmac_f32_dpp v214, v104, v132 row_shl:15 row_mask:0xf bank_mask:0xf
	v_fmac_f32_dpp v215, v105, v133 row_shl:15 row_mask:0xf bank_mask:0xf
	v_fmac_f32_dpp v216, v106, v134 row_shl:15 row_mask:0xf bank_mask:0xf
	v_fmac_f32_dpp v217, v107, v135 row_shl:15 row_mask:0xf bank_mask:0xf
	v_fmac_f32_dpp v210, v108, v88 row_shl:14 row_mask:0xf bank_mask:0xf
	v_fmac_f32_dpp v211, v109, v89 row_shl:14 row_mask:0xf bank_mask:0xf
	v_fmac_f32_dpp v212, v110, v90 row_shl:14 row_mask:0xf bank_mask:0xf
	v_fmac_f32_dpp v213, v111, v91 row_shl:14 row_mask:0xf bank_mask:0xf
	v_fmac_f32_dpp v214, v104, v92 row_shl:14 row_mask:0xf bank_mask:0xf
	v_fmac_f32_dpp v215, v105, v93 row_shl:14 row_mask:0xf bank_mask:0xf
	v_fmac_f32_dpp v216, v106, v94 row_shl:14 row_mask:0xf bank_mask:0xf
	v_fmac_f32_dpp v217, v107, v95 row_shl:14 row_mask:0xf bank_mask:0xf
	v_exp_f32_e32 v218, v210
	v_exp_f32_e32 v219, v211
	v_exp_f32_e32 v220, v212
	v_exp_f32_e32 v221, v213
	v_exp_f32_e32 v222, v214
	v_exp_f32_e32 v223, v215
	v_exp_f32_e32 v224, v216
	v_exp_f32_e32 v225, v217
	v_pk_fma_f32 v[218:219], v[218:219], v[204:205], v[204:205] op_sel:[0,1,1]
	v_pk_fma_f32 v[220:221], v[220:221], v[204:205], v[204:205] op_sel:[0,1,1]
	v_pk_fma_f32 v[222:223], v[222:223], v[204:205], v[204:205] op_sel:[0,1,1]
	v_pk_fma_f32 v[224:225], v[224:225], v[204:205], v[204:205] op_sel:[0,1,1]
	v_rcp_f32_e32 v218, v218
	v_rcp_f32_e32 v219, v219
	v_rcp_f32_e32 v220, v220
	v_rcp_f32_e32 v221, v221
	v_rcp_f32_e32 v222, v222
	v_rcp_f32_e32 v223, v223
	v_rcp_f32_e32 v224, v224
	v_rcp_f32_e32 v225, v225
	v_pk_mul_f32 v[210:211], v[210:211], v[218:219]
	v_pk_mul_f32 v[212:213], v[212:213], v[220:221]
	v_pk_mul_f32 v[214:215], v[214:215], v[222:223]
	v_pk_mul_f32 v[216:217], v[216:217], v[224:225]
	v_pk_mul_f32 v[68:69], v[210:211], v[68:69]
	v_pk_mul_f32 v[70:71], v[212:213], v[70:71]
	v_pk_mul_f32 v[64:65], v[214:215], v[64:65]
	v_pk_mul_f32 v[66:67], v[216:217], v[66:67]
	v_cvt_pk_bf16_f32 v226, v68, v69
	v_cvt_pk_bf16_f32 v227, v70, v71
	v_cvt_pk_bf16_f32 v228, v64, v65
	v_cvt_pk_bf16_f32 v229, v66, v67
	v_add_u32_e32 v234, 0x42000, v230
	global_store_dwordx4 v234, v[226:229], s[96:97] nt
	v_pk_mul_f32 v[60:61], v[60:61], v[76:77] op_sel_hi:[1,0]
	v_pk_mul_f32 v[62:63], v[62:63], v[76:77] op_sel_hi:[1,0]
	v_pk_mul_f32 v[52:53], v[52:53], v[76:77] op_sel_hi:[1,0]
	v_pk_mul_f32 v[54:55], v[54:55], v[76:77] op_sel_hi:[1,0]
	v_pk_fma_f32 v[210:211], v[60:61], v[136:137], v[174:175]
	v_pk_fma_f32 v[212:213], v[62:63], v[138:139], v[176:177]
	v_pk_fma_f32 v[214:215], v[52:53], v[140:141], v[178:179]
	v_pk_fma_f32 v[216:217], v[54:55], v[142:143], v[180:181]
	v_pk_mul_f32 v[218:219], v[56:57], v[76:77] op_sel_hi:[1,0]
	v_pk_mul_f32 v[220:221], v[58:59], v[76:77] op_sel_hi:[1,0]
	v_pk_mul_f32 v[222:223], v[48:49], v[76:77] op_sel_hi:[1,0]
	v_pk_mul_f32 v[224:225], v[50:51], v[76:77] op_sel_hi:[1,0]
	v_cvt_pk_bf16_f32 v236, v60, v61
	v_cvt_pk_bf16_f32 v237, v62, v63
	v_cvt_pk_bf16_f32 v238, v52, v53
	v_cvt_pk_bf16_f32 v239, v54, v55
	v_cvt_pk_bf16_f32 v240, v218, v219
	v_cvt_pk_bf16_f32 v241, v220, v221
	v_cvt_pk_bf16_f32 v242, v222, v223
	v_cvt_pk_bf16_f32 v243, v224, v225
	v_add_u32_e32 v234, 0x13400, v233
	v_add_u32_e32 v235, 0x16000, v233
	s_andn2_b64 exec, exec, s[8:9]
	global_store_dwordx4 v234, v[236:239], s[42:43]
	global_store_dwordx4 v235, v[240:243], s[42:43]
	s_mov_b64 exec, s[24:25]
	v_fmac_f32_dpp v210, v60, v128 row_shr:1 row_mask:0xf bank_mask:0xf
	v_fmac_f32_dpp v211, v61, v129 row_shr:1 row_mask:0xf bank_mask:0xf
	v_fmac_f32_dpp v212, v62, v130 row_shr:1 row_mask:0xf bank_mask:0xf
	v_fmac_f32_dpp v213, v63, v131 row_shr:1 row_mask:0xf bank_mask:0xf
	v_fmac_f32_dpp v214, v52, v132 row_shr:1 row_mask:0xf bank_mask:0xf
	v_fmac_f32_dpp v215, v53, v133 row_shr:1 row_mask:0xf bank_mask:0xf
	v_fmac_f32_dpp v216, v54, v134 row_shr:1 row_mask:0xf bank_mask:0xf
	v_fmac_f32_dpp v217, v55, v135 row_shr:1 row_mask:0xf bank_mask:0xf
	v_fmac_f32_dpp v210, v60, v88 row_shr:2 row_mask:0xf bank_mask:0xf
	v_fmac_f32_dpp v211, v61, v89 row_shr:2 row_mask:0xf bank_mask:0xf
	v_fmac_f32_dpp v212, v62, v90 row_shr:2 row_mask:0xf bank_mask:0xf
	v_fmac_f32_dpp v213, v63, v91 row_shr:2 row_mask:0xf bank_mask:0xf
	v_fmac_f32_dpp v214, v52, v92 row_shr:2 row_mask:0xf bank_mask:0xf
	v_fmac_f32_dpp v215, v53, v93 row_shr:2 row_mask:0xf bank_mask:0xf
	v_fmac_f32_dpp v216, v54, v94 row_shr:2 row_mask:0xf bank_mask:0xf
	v_fmac_f32_dpp v217, v55, v95 row_shr:2 row_mask:0xf bank_mask:0xf
	v_exp_f32_e32 v218, v210
	v_exp_f32_e32 v219, v211
	v_exp_f32_e32 v220, v212
	v_exp_f32_e32 v221, v213
	v_exp_f32_e32 v222, v214
	v_exp_f32_e32 v223, v215
	v_exp_f32_e32 v224, v216
	v_exp_f32_e32 v225, v217
	v_pk_fma_f32 v[218:219], v[218:219], v[206:207], v[206:207] op_sel_hi:[1,0,0]
	v_pk_fma_f32 v[220:221], v[220:221], v[206:207], v[206:207] op_sel_hi:[1,0,0]
	v_pk_fma_f32 v[222:223], v[222:223], v[206:207], v[206:207] op_sel_hi:[1,0,0]
	v_pk_fma_f32 v[224:225], v[224:225], v[206:207], v[206:207] op_sel_hi:[1,0,0]
	v_rcp_f32_e32 v218, v218
	v_rcp_f32_e32 v219, v219
	v_rcp_f32_e32 v220, v220
	v_rcp_f32_e32 v221, v221
	v_rcp_f32_e32 v222, v222
	v_rcp_f32_e32 v223, v223
	v_rcp_f32_e32 v224, v224
	v_rcp_f32_e32 v225, v225
	v_pk_mul_f32 v[210:211], v[210:211], v[218:219]
	v_pk_mul_f32 v[212:213], v[212:213], v[220:221]
;     __device__ __forceinline__ void operator()(const Acc& acc, const Unit& u, int wr, int wc, int fr, int fq, LAS unsigned char* lds, f32x4 epar) const {
;     ...
;         for (int ai = 0; ai < 2; ++ai) {
;             const int strip = u.pm * 4 + ai * 2 + wr;
;             float p1prev[NV], p2prev[NV];
; #pragma unroll
;             for (int i = 0; i < NV; ++i) { p1prev[i] = 0.f; p2prev[i] = 0.f; }
; #pragma unroll
;             for (int m = 0; m < 4; ++m) {
;                 const int r = u.pm * BM + ai * HALF + wr * 64 + m * 16 + fr;
;                 const float rs = __builtin_amdgcn_rsqf(sq[ai][m] * (1.0f / DM) + RMS_EPS);
;                 float X[NV], Y[NV], o[NV];
;                 if (MODE == 0) {
; #pragma unroll
;                     for (int n = 0; n < 2; ++n)
; #pragma unroll
;                         for (int j = 0; j < 4; ++j) { X[n * 4 + j] = acc[ai][0][m][n][j] * rs; Y[n * 4 + j] = acc[ai][1][m][n][j] * rs; }
;                 } else {
; #pragma unroll
;                     for (int j = 0; j < 4; ++j) { X[j] = (acc[ai][0][m][1][j] * rs) * (acc[ai][1][m][0][j] * rs); Y[j] = acc[ai][0][m][0][j] * rs; }
;                 }
; #pragma unroll
;                 for (int i = 0; i < NV; ++i) {
;                     const float a1 = dpp_rot<0x121>(X[i]), a2 = dpp_rot<0x122>(X[i]);
;                     const float q1 = fr >= 1 ? a1 : p1prev[i], q2 = fr >= 2 ? a2 : p2prev[i];
;                     p1prev[i] = a1; p2prev[i] = a2;
;                     const float cv = w2[i] * X[i] + w1[i] * q1 + w0[i] * q2 + bb[i];
;                     o[i] = MODE == 0 ? silu_f(cv) * Y[i] : cv * Y[i];
;                 }
;                 if (m == 0 && fr < 2) {
;                     bf16_t* hx = halo + ((size_t)strip * 6 + 2 + fr) * C + c0; bf16_t* hy = halo + ((size_t)strip * 6 + 4 + fr) * C + c0;
;                     u32x4 px, py; px.x = cvt_pk_bf16(X[0], X[1]); px.y = cvt_pk_bf16(X[2], X[3]); px.z = cvt_pk_bf16(X[4 % NV], X[5 % NV]); px.w = cvt_pk_bf16(X[6 % NV], X[7 % NV]);
;                     py.x = cvt_pk_bf16(Y[0], Y[1]); py.y = cvt_pk_bf16(Y[2], Y[3]); py.z = cvt_pk_bf16(Y[4 % NV], Y[5 % NV]); py.w = cvt_pk_bf16(Y[6 % NV], Y[7 % NV]);
;                     if (MODE == 0) { *(u32x4*)hx = px; *(u32x4*)hy = py; } else { u32x2 a; a.x = px.x; a.y = px.y; *(u32x2*)hx = a; u32x2 b; b.x = py.x; b.y = py.y; *(u32x2*)hy = b; }
;                 } else {
	v_pk_mul_f32 v[214:215], v[214:215], v[222:223]
	v_pk_mul_f32 v[216:217], v[216:217], v[224:225]
	v_pk_mul_f32 v[56:57], v[210:211], v[56:57]
	v_pk_mul_f32 v[58:59], v[212:213], v[58:59]
	v_pk_mul_f32 v[48:49], v[214:215], v[48:49]
	v_pk_mul_f32 v[50:51], v[216:217], v[50:51]
	v_cvt_pk_bf16_f32 v226, v56, v57
	v_cvt_pk_bf16_f32 v227, v58, v59
	v_cvt_pk_bf16_f32 v228, v48, v49
	v_cvt_pk_bf16_f32 v229, v50, v51
	v_add_u32_e32 v234, 0xb0000, v230
	s_and_b64 exec, exec, s[8:9]
	global_store_dwordx4 v234, v[226:229], s[96:97] nt
	s_mov_b64 exec, s[24:25]
	v_pk_mul_f32 v[44:45], v[44:45], v[76:77] op_sel:[0,1]
	v_pk_mul_f32 v[46:47], v[46:47], v[76:77] op_sel:[0,1]
	v_pk_mul_f32 v[40:41], v[40:41], v[76:77] op_sel:[0,1]
	v_pk_mul_f32 v[42:43], v[42:43], v[76:77] op_sel:[0,1]
	v_pk_fma_f32 v[210:211], v[44:45], v[136:137], v[174:175]
	v_pk_fma_f32 v[212:213], v[46:47], v[138:139], v[176:177]
	v_pk_fma_f32 v[214:215], v[40:41], v[140:141], v[178:179]
	v_pk_fma_f32 v[216:217], v[42:43], v[142:143], v[180:181]
	v_fmac_f32_dpp v210, v44, v128 row_shr:1 row_mask:0xf bank_mask:0xf
	v_fmac_f32_dpp v211, v45, v129 row_shr:1 row_mask:0xf bank_mask:0xf
	v_fmac_f32_dpp v212, v46, v130 row_shr:1 row_mask:0xf bank_mask:0xf
	v_fmac_f32_dpp v213, v47, v131 row_shr:1 row_mask:0xf bank_mask:0xf
	v_fmac_f32_dpp v214, v40, v132 row_shr:1 row_mask:0xf bank_mask:0xf
	v_fmac_f32_dpp v215, v41, v133 row_shr:1 row_mask:0xf bank_mask:0xf
	v_fmac_f32_dpp v216, v42, v134 row_shr:1 row_mask:0xf bank_mask:0xf
	v_fmac_f32_dpp v217, v43, v135 row_shr:1 row_mask:0xf bank_mask:0xf
	v_fmac_f32_dpp v210, v44, v88 row_shr:2 row_mask:0xf bank_mask:0xf
	v_fmac_f32_dpp v211, v45, v89 row_shr:2 row_mask:0xf bank_mask:0xf
	v_fmac_f32_dpp v212, v46, v90 row_shr:2 row_mask:0xf bank_mask:0xf
	v_fmac_f32_dpp v213, v47, v91 row_shr:2 row_mask:0xf bank_mask:0xf
	v_fmac_f32_dpp v214, v40, v92 row_shr:2 row_mask:0xf bank_mask:0xf
	v_fmac_f32_dpp v215, v41, v93 row_shr:2 row_mask:0xf bank_mask:0xf
	v_fmac_f32_dpp v216, v42, v94 row_shr:2 row_mask:0xf bank_mask:0xf
	v_fmac_f32_dpp v217, v43, v95 row_shr:2 row_mask:0xf bank_mask:0xf
	v_fmac_f32_dpp v210, v60, v128 row_shl:15 row_mask:0xf bank_mask:0xf
	v_fmac_f32_dpp v211, v61, v129 row_shl:15 row_mask:0xf bank_mask:0xf
	v_fmac_f32_dpp v212, v62, v130 row_shl:15 row_mask:0xf bank_mask:0xf
	v_fmac_f32_dpp v213, v63, v131 row_shl:15 row_mask:0xf bank_mask:0xf
	v_fmac_f32_dpp v214, v52, v132 row_shl:15 row_mask:0xf bank_mask:0xf
	v_fmac_f32_dpp v215, v53, v133 row_shl:15 row_mask:0xf bank_mask:0xf
	v_fmac_f32_dpp v216, v54, v134 row_shl:15 row_mask:0xf bank_mask:0xf
	v_fmac_f32_dpp v217, v55, v135 row_shl:15 row_mask:0xf bank_mask:0xf
	v_fmac_f32_dpp v210, v60, v88 row_shl:14 row_mask:0xf bank_mask:0xf
	v_fmac_f32_dpp v211, v61, v89 row_shl:14 row_mask:0xf bank_mask:0xf
	v_fmac_f32_dpp v212, v62, v90 row_shl:14 row_mask:0xf bank_mask:0xf
	v_fmac_f32_dpp v213, v63, v91 row_shl:14 row_mask:0xf bank_mask:0xf
	v_fmac_f32_dpp v214, v52, v92 row_shl:14 row_mask:0xf bank_mask:0xf
	v_fmac_f32_dpp v215, v53, v93 row_shl:14 row_mask:0xf bank_mask:0xf
	v_fmac_f32_dpp v216, v54, v94 row_shl:14 row_mask:0xf bank_mask:0xf
	v_fmac_f32_dpp v217, v55, v95 row_shl:14 row_mask:0xf bank_mask:0xf
	v_exp_f32_e32 v218, v210
	v_exp_f32_e32 v219, v211
	v_exp_f32_e32 v220, v212
	v_exp_f32_e32 v221, v213
	v_exp_f32_e32 v222, v214
	v_exp_f32_e32 v223, v215
	v_exp_f32_e32 v224, v216
	v_exp_f32_e32 v225, v217
	v_pk_fma_f32 v[218:219], v[218:219], v[206:207], v[206:207] op_sel:[0,1,1]
	v_pk_fma_f32 v[220:221], v[220:221], v[206:207], v[206:207] op_sel:[0,1,1]
	v_pk_fma_f32 v[222:223], v[222:223], v[206:207], v[206:207] op_sel:[0,1,1]
	v_pk_fma_f32 v[224:225], v[224:225], v[206:207], v[206:207] op_sel:[0,1,1]
	v_rcp_f32_e32 v218, v218
	v_rcp_f32_e32 v219, v219
	v_rcp_f32_e32 v220, v220
	v_rcp_f32_e32 v221, v221
	v_rcp_f32_e32 v222, v222
	v_rcp_f32_e32 v223, v223
	v_rcp_f32_e32 v224, v224
	v_rcp_f32_e32 v225, v225
	v_pk_mul_f32 v[210:211], v[210:211], v[218:219]
	v_pk_mul_f32 v[212:213], v[212:213], v[220:221]
	v_pk_mul_f32 v[214:215], v[214:215], v[222:223]
	v_pk_mul_f32 v[216:217], v[216:217], v[224:225]
	v_pk_mul_f32 v[36:37], v[210:211], v[36:37]
	v_pk_mul_f32 v[38:39], v[212:213], v[38:39]
	v_pk_mul_f32 v[32:33], v[214:215], v[32:33]
	v_pk_mul_f32 v[34:35], v[216:217], v[34:35]
	v_cvt_pk_bf16_f32 v226, v36, v37
	v_cvt_pk_bf16_f32 v227, v38, v39
	v_cvt_pk_bf16_f32 v228, v32, v33
	v_cvt_pk_bf16_f32 v229, v34, v35
	v_add_u32_e32 v234, 0xc6000, v230
	global_store_dwordx4 v234, v[226:229], s[96:97] nt
	v_pk_mul_f32 v[28:29], v[28:29], v[78:79] op_sel_hi:[1,0]
	v_pk_mul_f32 v[30:31], v[30:31], v[78:79] op_sel_hi:[1,0]
	v_pk_mul_f32 v[24:25], v[24:25], v[78:79] op_sel_hi:[1,0]
	v_pk_mul_f32 v[26:27], v[26:27], v[78:79] op_sel_hi:[1,0]
	v_pk_fma_f32 v[210:211], v[28:29], v[136:137], v[174:175]
	v_pk_fma_f32 v[212:213], v[30:31], v[138:139], v[176:177]
	v_pk_fma_f32 v[214:215], v[24:25], v[140:141], v[178:179]
	v_pk_fma_f32 v[216:217], v[26:27], v[142:143], v[180:181]
	v_fmac_f32_dpp v210, v28, v128 row_shr:1 row_mask:0xf bank_mask:0xf
	v_fmac_f32_dpp v211, v29, v129 row_shr:1 row_mask:0xf bank_mask:0xf
	v_fmac_f32_dpp v212, v30, v130 row_shr:1 row_mask:0xf bank_mask:0xf
	v_fmac_f32_dpp v213, v31, v131 row_shr:1 row_mask:0xf bank_mask:0xf
	v_fmac_f32_dpp v214, v24, v132 row_shr:1 row_mask:0xf bank_mask:0xf
	v_fmac_f32_dpp v215, v25, v133 row_shr:1 row_mask:0xf bank_mask:0xf
	v_fmac_f32_dpp v216, v26, v134 row_shr:1 row_mask:0xf bank_mask:0xf
	v_fmac_f32_dpp v217, v27, v135 row_shr:1 row_mask:0xf bank_mask:0xf
	v_fmac_f32_dpp v210, v28, v88 row_shr:2 row_mask:0xf bank_mask:0xf
; __device__ __forceinline__ unsigned cvt_pk_bf16(float lo, float hi) { unsigned r; asm volatile("v_cvt_pk_bf16_f32 %0, %1, %2" : "=v"(r) : "v"(lo), "v"(hi)); return r; }
; __device__ __forceinline__ float silu_f(float x) { return x * __builtin_amdgcn_rcpf(1.0f + __builtin_amdgcn_exp2f(x * -1.44269504f)); }
; template <int CTRL> __device__ __forceinline__ float dpp_rot(float x) { return __int_as_float(__builtin_amdgcn_mov_dpp(__float_as_int(x), CTRL, 0xf, 0xf, false)); }
;     __device__ __forceinline__ void operator()(const Acc& acc, const Unit& u, int wr, int wc, int fr, int fq, LAS unsigned char* lds, f32x4 epar) const {
;     ...
; #pragma unroll
;                 for (int i = 0; i < NV; ++i) {
;                     const float a1 = dpp_rot<0x121>(X[i]), a2 = dpp_rot<0x122>(X[i]);
;                     const float q1 = fr >= 1 ? a1 : p1prev[i], q2 = fr >= 2 ? a2 : p2prev[i];
;                     p1prev[i] = a1; p2prev[i] = a2;
;                     const float cv = w2[i] * X[i] + w1[i] * q1 + w0[i] * q2 + bb[i];
;                     o[i] = MODE == 0 ? silu_f(cv) * Y[i] : cv * Y[i];
;                 }
;                 if (m == 0 && fr < 2) {
;                     bf16_t* hx = halo + ((size_t)strip * 6 + 2 + fr) * C + c0; bf16_t* hy = halo + ((size_t)strip * 6 + 4 + fr) * C + c0;
;                     u32x4 px, py; px.x = cvt_pk_bf16(X[0], X[1]); px.y = cvt_pk_bf16(X[2], X[3]); px.z = cvt_pk_bf16(X[4 % NV], X[5 % NV]); px.w = cvt_pk_bf16(X[6 % NV], X[7 % NV]);
;                     py.x = cvt_pk_bf16(Y[0], Y[1]); py.y = cvt_pk_bf16(Y[2], Y[3]); py.z = cvt_pk_bf16(Y[4 % NV], Y[5 % NV]); py.w = cvt_pk_bf16(Y[6 % NV], Y[7 % NV]);
;                     if (MODE == 0) { *(u32x4*)hx = px; *(u32x4*)hy = py; } else { u32x2 a; a.x = px.x; a.y = px.y; *(u32x2*)hx = a; u32x2 b; b.x = py.x; b.y = py.y; *(u32x2*)hy = b; }
;                 } else {
;                     if (MODE == 0) { u32x4 w; w.x = cvt_pk_bf16(o[0], o[1]); w.y = cvt_pk_bf16(o[2], o[3]); w.z = cvt_pk_bf16(o[4 % NV], o[5 % NV]); w.w = cvt_pk_bf16(o[6 % NV], o[7 % NV]);
;                         __builtin_nontemporal_store(w, (u32x4*)(out + (size_t)r * C + c0)); }
;                     else { u32x2 w; w.x = cvt_pk_bf16(o[0], o[1]); w.y = cvt_pk_bf16(o[2], o[3]); __builtin_nontemporal_store(w, (u32x2*)(out + (size_t)r * C + c0)); }
;                 }
	v_fmac_f32_dpp v211, v29, v89 row_shr:2 row_mask:0xf bank_mask:0xf
	v_fmac_f32_dpp v212, v30, v90 row_shr:2 row_mask:0xf bank_mask:0xf
	v_fmac_f32_dpp v213, v31, v91 row_shr:2 row_mask:0xf bank_mask:0xf
	v_fmac_f32_dpp v214, v24, v92 row_shr:2 row_mask:0xf bank_mask:0xf
	v_fmac_f32_dpp v215, v25, v93 row_shr:2 row_mask:0xf bank_mask:0xf
	v_fmac_f32_dpp v216, v26, v94 row_shr:2 row_mask:0xf bank_mask:0xf
	v_fmac_f32_dpp v217, v27, v95 row_shr:2 row_mask:0xf bank_mask:0xf
	v_fmac_f32_dpp v210, v44, v128 row_shl:15 row_mask:0xf bank_mask:0xf
	v_fmac_f32_dpp v211, v45, v129 row_shl:15 row_mask:0xf bank_mask:0xf
	v_fmac_f32_dpp v212, v46, v130 row_shl:15 row_mask:0xf bank_mask:0xf
	v_fmac_f32_dpp v213, v47, v131 row_shl:15 row_mask:0xf bank_mask:0xf
	v_fmac_f32_dpp v214, v40, v132 row_shl:15 row_mask:0xf bank_mask:0xf
	v_fmac_f32_dpp v215, v41, v133 row_shl:15 row_mask:0xf bank_mask:0xf
	v_fmac_f32_dpp v216, v42, v134 row_shl:15 row_mask:0xf bank_mask:0xf
	v_fmac_f32_dpp v217, v43, v135 row_shl:15 row_mask:0xf bank_mask:0xf
	v_fmac_f32_dpp v210, v44, v88 row_shl:14 row_mask:0xf bank_mask:0xf
	v_fmac_f32_dpp v211, v45, v89 row_shl:14 row_mask:0xf bank_mask:0xf
	v_fmac_f32_dpp v212, v46, v90 row_shl:14 row_mask:0xf bank_mask:0xf
	v_fmac_f32_dpp v213, v47, v91 row_shl:14 row_mask:0xf bank_mask:0xf
	v_fmac_f32_dpp v214, v40, v92 row_shl:14 row_mask:0xf bank_mask:0xf
	v_fmac_f32_dpp v215, v41, v93 row_shl:14 row_mask:0xf bank_mask:0xf
	v_fmac_f32_dpp v216, v42, v94 row_shl:14 row_mask:0xf bank_mask:0xf
	v_fmac_f32_dpp v217, v43, v95 row_shl:14 row_mask:0xf bank_mask:0xf
	v_exp_f32_e32 v218, v210
	v_exp_f32_e32 v219, v211
	v_exp_f32_e32 v220, v212
	v_exp_f32_e32 v221, v213
	v_exp_f32_e32 v222, v214
	v_exp_f32_e32 v223, v215
	v_exp_f32_e32 v224, v216
	v_exp_f32_e32 v225, v217
	v_pk_fma_f32 v[218:219], v[218:219], v[208:209], v[208:209] op_sel_hi:[1,0,0]
	v_pk_fma_f32 v[220:221], v[220:221], v[208:209], v[208:209] op_sel_hi:[1,0,0]
	v_pk_fma_f32 v[222:223], v[222:223], v[208:209], v[208:209] op_sel_hi:[1,0,0]
	v_pk_fma_f32 v[224:225], v[224:225], v[208:209], v[208:209] op_sel_hi:[1,0,0]
	v_rcp_f32_e32 v218, v218
	v_rcp_f32_e32 v219, v219
	v_rcp_f32_e32 v220, v220
	v_rcp_f32_e32 v221, v221
	v_rcp_f32_e32 v222, v222
	v_rcp_f32_e32 v223, v223
	v_rcp_f32_e32 v224, v224
	v_rcp_f32_e32 v225, v225
	v_pk_mul_f32 v[210:211], v[210:211], v[218:219]
	v_pk_mul_f32 v[212:213], v[212:213], v[220:221]
	v_pk_mul_f32 v[214:215], v[214:215], v[222:223]
	v_pk_mul_f32 v[216:217], v[216:217], v[224:225]
	v_pk_mul_f32 v[20:21], v[210:211], v[20:21]
	v_pk_mul_f32 v[22:23], v[212:213], v[22:23]
	v_pk_mul_f32 v[16:17], v[214:215], v[16:17]
	v_pk_mul_f32 v[18:19], v[216:217], v[18:19]
	v_cvt_pk_bf16_f32 v226, v20, v21
	v_cvt_pk_bf16_f32 v227, v22, v23
	v_cvt_pk_bf16_f32 v228, v16, v17
	v_cvt_pk_bf16_f32 v229, v18, v19
	v_add_u32_e32 v234, 0xdc000, v230
	global_store_dwordx4 v234, v[226:229], s[96:97] nt
	v_pk_mul_f32 v[12:13], v[12:13], v[78:79] op_sel:[0,1]
	v_pk_mul_f32 v[14:15], v[14:15], v[78:79] op_sel:[0,1]
	v_pk_mul_f32 v[8:9], v[8:9], v[78:79] op_sel:[0,1]
	v_pk_mul_f32 v[10:11], v[10:11], v[78:79] op_sel:[0,1]
	v_pk_fma_f32 v[210:211], v[12:13], v[136:137], v[174:175]
	v_pk_fma_f32 v[212:213], v[14:15], v[138:139], v[176:177]
	v_pk_fma_f32 v[214:215], v[8:9], v[140:141], v[178:179]
	v_pk_fma_f32 v[216:217], v[10:11], v[142:143], v[180:181]
	v_cvt_pk_bf16_f32 v236, v12, v13
	v_cvt_pk_bf16_f32 v237, v14, v15
	v_cvt_pk_bf16_f32 v238, v8, v9
	v_cvt_pk_bf16_f32 v239, v10, v11
	v_add_u32_e32 v235, 0xffffd400, v233
	s_and_b64 exec, exec, s[10:11]
; __device__ __forceinline__ float silu_f(float x) { return x * __builtin_amdgcn_rcpf(1.0f + __builtin_amdgcn_exp2f(x * -1.44269504f)); }
;     __device__ __forceinline__ void operator()(const Acc& acc, const Unit& u, int wr, int wc, int fr, int fq, LAS unsigned char* lds, f32x4 epar) const {
;     ...
;                 for (int i = 0; i < NV; ++i) {
;                     const float a1 = dpp_rot<0x121>(X[i]), a2 = dpp_rot<0x122>(X[i]);
;                     const float q1 = fr >= 1 ? a1 : p1prev[i], q2 = fr >= 2 ? a2 : p2prev[i];
;                     p1prev[i] = a1; p2prev[i] = a2;
;                     const float cv = w2[i] * X[i] + w1[i] * q1 + w0[i] * q2 + bb[i];
;                     o[i] = MODE == 0 ? silu_f(cv) * Y[i] : cv * Y[i];
;                 }
;                 if (m == 0 && fr < 2) {
;                     bf16_t* hx = halo + ((size_t)strip * 6 + 2 + fr) * C + c0; bf16_t* hy = halo + ((size_t)strip * 6 + 4 + fr) * C + c0;
;                     u32x4 px, py; px.x = cvt_pk_bf16(X[0], X[1]); px.y = cvt_pk_bf16(X[2], X[3]); px.z = cvt_pk_bf16(X[4 % NV], X[5 % NV]); px.w = cvt_pk_bf16(X[6 % NV], X[7 % NV]);
;                     py.x = cvt_pk_bf16(Y[0], Y[1]); py.y = cvt_pk_bf16(Y[2], Y[3]); py.z = cvt_pk_bf16(Y[4 % NV], Y[5 % NV]); py.w = cvt_pk_bf16(Y[6 % NV], Y[7 % NV]);
;                     if (MODE == 0) { *(u32x4*)hx = px; *(u32x4*)hy = py; } else { u32x2 a; a.x = px.x; a.y = px.y; *(u32x2*)hx = a; u32x2 b; b.x = py.x; b.y = py.y; *(u32x2*)hy = b; }
;                 } else {
;                     if (MODE == 0) { u32x4 w; w.x = cvt_pk_bf16(o[0], o[1]); w.y = cvt_pk_bf16(o[2], o[3]); w.z = cvt_pk_bf16(o[4 % NV], o[5 % NV]); w.w = cvt_pk_bf16(o[6 % NV], o[7 % NV]);
;                         __builtin_nontemporal_store(w, (u32x4*)(out + (size_t)r * C + c0)); }
;                     else { u32x2 w; w.x = cvt_pk_bf16(o[0], o[1]); w.y = cvt_pk_bf16(o[2], o[3]); __builtin_nontemporal_store(w, (u32x2*)(out + (size_t)r * C + c0)); }
;                 }
;                 if (m == 3 && fr >= 14) { bf16_t* hx = halo + ((size_t)strip * 6 + (fr - 14)) * C + c0;
;                     u32x4 px; px.x = cvt_pk_bf16(X[0], X[1]); px.y = cvt_pk_bf16(X[2], X[3]); px.z = cvt_pk_bf16(X[4 % NV], X[5 % NV]); px.w = cvt_pk_bf16(X[6 % NV], X[7 % NV]);
;                     if (MODE == 0) *(u32x4*)hx = px; else { u32x2 a; a.x = px.x; a.y = px.y; *(u32x2*)hx = a; } }
	global_store_dwordx4 v235, v[236:239], s[42:43]
	s_mov_b64 exec, s[24:25]
	v_fmac_f32_dpp v210, v12, v128 row_shr:1 row_mask:0xf bank_mask:0xf
	v_fmac_f32_dpp v211, v13, v129 row_shr:1 row_mask:0xf bank_mask:0xf
	v_fmac_f32_dpp v212, v14, v130 row_shr:1 row_mask:0xf bank_mask:0xf
	v_fmac_f32_dpp v213, v15, v131 row_shr:1 row_mask:0xf bank_mask:0xf
	v_fmac_f32_dpp v214, v8, v132 row_shr:1 row_mask:0xf bank_mask:0xf
	v_fmac_f32_dpp v215, v9, v133 row_shr:1 row_mask:0xf bank_mask:0xf
	v_fmac_f32_dpp v216, v10, v134 row_shr:1 row_mask:0xf bank_mask:0xf
	v_fmac_f32_dpp v217, v11, v135 row_shr:1 row_mask:0xf bank_mask:0xf
	v_fmac_f32_dpp v210, v12, v88 row_shr:2 row_mask:0xf bank_mask:0xf
	v_fmac_f32_dpp v211, v13, v89 row_shr:2 row_mask:0xf bank_mask:0xf
	v_fmac_f32_dpp v212, v14, v90 row_shr:2 row_mask:0xf bank_mask:0xf
	v_fmac_f32_dpp v213, v15, v91 row_shr:2 row_mask:0xf bank_mask:0xf
	v_fmac_f32_dpp v214, v8, v92 row_shr:2 row_mask:0xf bank_mask:0xf
	v_fmac_f32_dpp v215, v9, v93 row_shr:2 row_mask:0xf bank_mask:0xf
	v_fmac_f32_dpp v216, v10, v94 row_shr:2 row_mask:0xf bank_mask:0xf
	v_fmac_f32_dpp v217, v11, v95 row_shr:2 row_mask:0xf bank_mask:0xf
	v_fmac_f32_dpp v210, v28, v128 row_shl:15 row_mask:0xf bank_mask:0xf
	v_fmac_f32_dpp v211, v29, v129 row_shl:15 row_mask:0xf bank_mask:0xf
	v_fmac_f32_dpp v212, v30, v130 row_shl:15 row_mask:0xf bank_mask:0xf
	v_fmac_f32_dpp v213, v31, v131 row_shl:15 row_mask:0xf bank_mask:0xf
	v_fmac_f32_dpp v214, v24, v132 row_shl:15 row_mask:0xf bank_mask:0xf
	v_fmac_f32_dpp v215, v25, v133 row_shl:15 row_mask:0xf bank_mask:0xf
	v_fmac_f32_dpp v216, v26, v134 row_shl:15 row_mask:0xf bank_mask:0xf
	v_fmac_f32_dpp v217, v27, v135 row_shl:15 row_mask:0xf bank_mask:0xf
	v_fmac_f32_dpp v210, v28, v88 row_shl:14 row_mask:0xf bank_mask:0xf
	v_fmac_f32_dpp v211, v29, v89 row_shl:14 row_mask:0xf bank_mask:0xf
	v_fmac_f32_dpp v212, v30, v90 row_shl:14 row_mask:0xf bank_mask:0xf
	v_fmac_f32_dpp v213, v31, v91 row_shl:14 row_mask:0xf bank_mask:0xf
	v_fmac_f32_dpp v214, v24, v92 row_shl:14 row_mask:0xf bank_mask:0xf
	v_fmac_f32_dpp v215, v25, v93 row_shl:14 row_mask:0xf bank_mask:0xf
	v_fmac_f32_dpp v216, v26, v94 row_shl:14 row_mask:0xf bank_mask:0xf
	v_fmac_f32_dpp v217, v27, v95 row_shl:14 row_mask:0xf bank_mask:0xf
	v_exp_f32_e32 v218, v210
	v_exp_f32_e32 v219, v211
	v_exp_f32_e32 v220, v212
	v_exp_f32_e32 v221, v213
	v_exp_f32_e32 v222, v214
	v_exp_f32_e32 v223, v215
	v_exp_f32_e32 v224, v216
	v_exp_f32_e32 v225, v217
	v_pk_fma_f32 v[218:219], v[218:219], v[208:209], v[208:209] op_sel:[0,1,1]
	v_pk_fma_f32 v[220:221], v[220:221], v[208:209], v[208:209] op_sel:[0,1,1]
	v_pk_fma_f32 v[222:223], v[222:223], v[208:209], v[208:209] op_sel:[0,1,1]
	v_pk_fma_f32 v[224:225], v[224:225], v[208:209], v[208:209] op_sel:[0,1,1]
	v_rcp_f32_e32 v218, v218
	v_rcp_f32_e32 v219, v219
	v_rcp_f32_e32 v220, v220
	v_rcp_f32_e32 v221, v221
	v_rcp_f32_e32 v222, v222
	v_rcp_f32_e32 v223, v223
	v_rcp_f32_e32 v224, v224
	v_rcp_f32_e32 v225, v225
	v_pk_mul_f32 v[210:211], v[210:211], v[218:219]
	v_pk_mul_f32 v[212:213], v[212:213], v[220:221]
	v_pk_mul_f32 v[214:215], v[214:215], v[222:223]
	v_pk_mul_f32 v[216:217], v[216:217], v[224:225]
	v_pk_mul_f32 v[4:5], v[210:211], v[4:5]
	v_pk_mul_f32 v[6:7], v[212:213], v[6:7]
	v_pk_mul_f32 v[0:1], v[214:215], v[0:1]
	v_pk_mul_f32 v[2:3], v[216:217], v[2:3]
	v_cvt_pk_bf16_f32 v226, v4, v5
	v_cvt_pk_bf16_f32 v227, v6, v7
	v_cvt_pk_bf16_f32 v228, v0, v1
	v_cvt_pk_bf16_f32 v229, v2, v3
	v_add_u32_e32 v234, 0xf2000, v230
	global_store_dwordx4 v234, v[226:229], s[96:97] nt

;     __device__ __forceinline__ void operator()(const Acc& acc, const Unit& u, int wr, int wc, int fr, int fq, LAS unsigned char* lds, f32x4 epar) const {
;         constexpr int NV = MODE == 0 ? 8 : 4;
;         const int c0 = MODE == 0 ? (u.pn * 128 + wc * 32 + 8 * fq) : (u.pn * 64 + wc * 16 + 4 * fq);
;         LAS float* pw = (LAS float*)(lds + STAGE_BYTES + 64 + (wr * 4 + wc) * 1024);
;         *(LAS f32x4*)(pw + (fq * 16 + fr) * 4) = epar;
;         asm volatile("s_waitcnt lgkmcnt(0)" ::: "memory");
;         float w0[NV], w1[NV], w2[NV], bb[NV];
; #pragma unroll
;         for (int i = 0; i < NV; i += 4) { const f32x4 a = *(const LAS f32x4*)(pw + NV * fq + i), b = *(const LAS f32x4*)(pw + 32 + NV * fq + i), c = *(const LAS f32x4*)(pw + 64 + NV * fq + i);
;             f32x4 d = (f32x4){0.f, 0.f, 0.f, 0.f}; if (MODE == 0) d = *(const LAS f32x4*)(pw + 96 + NV * fq + i);
; #pragma unroll
;             for (int j = 0; j < 4; ++j) { w0[i + j] = a[j]; w1[i + j] = b[j]; w2[i + j] = c[j]; bb[i + j] = d[j]; } }
;         float sq[2][4];
; #pragma unroll
;         for (int ai = 0; ai < 2; ++ai)
; #pragma unroll
;             for (int m = 0; m < 4; ++m) sq[ai][m] = pw[128 + ai * 64 + m * 16 + fr];
; #pragma unroll
;         for (int ai = 0; ai < 2; ++ai) {
;             const int strip = u.pm * 4 + ai * 2 + wr;
;             float p1prev[NV], p2prev[NV];
; #pragma unroll
;             for (int i = 0; i < NV; ++i) { p1prev[i] = 0.f; p2prev[i] = 0.f; }
; #pragma unroll
;             for (int m = 0; m < 4; ++m) {
;                 const int r = u.pm * BM + ai * HALF + wr * 64 + m * 16 + fr;
;                 const float rs = __builtin_amdgcn_rsqf(sq[ai][m] * (1.0f / DM) + RMS_EPS);
;                 float X[NV], Y[NV], o[NV];
;                 if (MODE == 0) {
; #pragma unroll
;                     for (int n = 0; n < 2; ++n)
; #pragma unroll
;                         for (int j = 0; j < 4; ++j) { X[n * 4 + j] = acc[ai][0][m][n][j] * rs; Y[n * 4 + j] = acc[ai][1][m][n][j] * rs; }
;                 } else {
; #pragma unroll
;                     for (int j = 0; j < 4; ++j) { X[j] = (acc[ai][0][m][1][j] * rs) * (acc[ai][1][m][0][j] * rs); Y[j] = acc[ai][0][m][0][j] * rs; }
;                 }
; #pragma unroll
;                 for (int i = 0; i < NV; ++i) {
;                     const float a1 = dpp_rot<0x121>(X[i]), a2 = dpp_rot<0x122>(X[i]);
.LBB0_846:
	.p2align 6
	s_nop 0
	ds_write_b128 v146, v[24:27]
	s_mov_b64 s[24:25], exec
	s_waitcnt lgkmcnt(0)
	ds_read_b128 v[186:189], v147
	ds_read_b128 v[190:193], v147 offset:128
	ds_read_b128 v[194:197], v147 offset:256
	ds_read2_b32 v[198:199], v139 offset0:128 offset1:144
	ds_read2_b32 v[200:201], v139 offset0:160 offset1:176
	ds_read2_b32 v[202:203], v139 offset0:192 offset1:208
	ds_read2_b32 v[204:205], v139 offset0:224 offset1:240
	v_lshl_add_u32 v206, s70, 8, v138
	v_lshl_or_b32 v207, s72, 6, v140
	v_lshlrev_b32_e32 v206, 11, v206
	s_lshl_b32 s22, s70, 2
	s_add_i32 s22, s22, s15
	s_mul_i32 s16, s22, 6
	v_and_b32_e32 v208, 15, v138
	v_lshl_add_u32 v206, v207, 1, v206
	v_add_u32_e32 v208, s16, v208
	v_lshlrev_b32_e32 v208, 11, v208
	s_nop 0
	v_lshl_add_u32 v208, v207, 1, v208
	s_waitcnt lgkmcnt(0)
	v_fmamk_f32 v198, v198, 0x3a800000, v148
	v_fmamk_f32 v199, v199, 0x3a800000, v148
	v_fmamk_f32 v200, v200, 0x3a800000, v148
	v_fmamk_f32 v201, v201, 0x3a800000, v148
	v_fmamk_f32 v202, v202, 0x3a800000, v148
	v_fmamk_f32 v203, v203, 0x3a800000, v148
	v_fmamk_f32 v204, v204, 0x3a800000, v148
	v_fmamk_f32 v205, v205, 0x3a800000, v148
	v_rsq_f32_e32 v198, v198
	v_rsq_f32_e32 v199, v199
	v_rsq_f32_e32 v200, v200
	v_rsq_f32_e32 v201, v201
	v_rsq_f32_e32 v202, v202
	v_rsq_f32_e32 v203, v203
	v_rsq_f32_e32 v204, v204
	v_rsq_f32_e32 v205, v205
	s_nop 0
	v_pk_mul_f32 v[96:97], v[96:97], v[198:199] op_sel_hi:[1,0]
	v_pk_mul_f32 v[98:99], v[98:99], v[198:199] op_sel_hi:[1,0]
	v_pk_mul_f32 v[92:93], v[92:93], v[198:199] op_sel_hi:[1,0]
	v_pk_mul_f32 v[94:95], v[94:95], v[198:199] op_sel_hi:[1,0]
	v_pk_mul_f32 v[88:89], v[88:89], v[198:199] op_sel_hi:[1,0]
	v_pk_mul_f32 v[90:91], v[90:91], v[198:199] op_sel_hi:[1,0]
	v_pk_mul_f32 v[96:97], v[96:97], v[92:93]
	v_pk_mul_f32 v[98:99], v[98:99], v[94:95]
	v_mul_f32_e32 v209, v96, v194
	v_mul_f32_e32 v210, v97, v195
	v_mul_f32_e32 v211, v98, v196
	v_mul_f32_e32 v212, v99, v197
	v_cvt_pk_bf16_f32 v218, v96, v97
	v_cvt_pk_bf16_f32 v219, v98, v99
	v_cvt_pk_bf16_f32 v220, v88, v89
	v_cvt_pk_bf16_f32 v221, v90, v91
	v_add_u32_e32 v216, 0x1000, v208
	v_add_u32_e32 v217, 0x2000, v208
	s_andn2_b64 exec, exec, s[8:9]
	global_store_dwordx2 v216, v[218:219], s[42:43]
	global_store_dwordx2 v217, v[220:221], s[42:43]
	s_mov_b64 exec, s[24:25]
	v_fmac_f32_dpp v209, v96, v190 row_shr:1 row_mask:0xf bank_mask:0xf
	v_fmac_f32_dpp v210, v97, v191 row_shr:1 row_mask:0xf bank_mask:0xf
	v_fmac_f32_dpp v211, v98, v192 row_shr:1 row_mask:0xf bank_mask:0xf
	v_fmac_f32_dpp v212, v99, v193 row_shr:1 row_mask:0xf bank_mask:0xf
	v_fmac_f32_dpp v209, v96, v186 row_shr:2 row_mask:0xf bank_mask:0xf
	v_fmac_f32_dpp v210, v97, v187 row_shr:2 row_mask:0xf bank_mask:0xf
	v_fmac_f32_dpp v211, v98, v188 row_shr:2 row_mask:0xf bank_mask:0xf
	v_fmac_f32_dpp v212, v99, v189 row_shr:2 row_mask:0xf bank_mask:0xf
	v_mul_f32_e32 v88, v209, v88
	v_mul_f32_e32 v89, v210, v89
	v_mul_f32_e32 v90, v211, v90
	v_mul_f32_e32 v91, v212, v91
	v_cvt_pk_bf16_f32 v214, v88, v89
	v_cvt_pk_bf16_f32 v215, v90, v91
	v_add_u32_e32 v216, 0x0, v206
	s_and_b64 exec, exec, s[8:9]
	global_store_dwordx2 v216, v[214:215], s[40:41] nt
	s_mov_b64 exec, s[24:25]
	v_pk_mul_f32 v[84:85], v[84:85], v[198:199] op_sel:[0,1]
	v_pk_mul_f32 v[86:87], v[86:87], v[198:199] op_sel:[0,1]
	v_pk_mul_f32 v[80:81], v[80:81], v[198:199] op_sel:[0,1]
	v_pk_mul_f32 v[82:83], v[82:83], v[198:199] op_sel:[0,1]
	v_pk_mul_f32 v[76:77], v[76:77], v[198:199] op_sel:[0,1]
	v_pk_mul_f32 v[78:79], v[78:79], v[198:199] op_sel:[0,1]
	v_pk_mul_f32 v[84:85], v[84:85], v[80:81]
	v_pk_mul_f32 v[86:87], v[86:87], v[82:83]
	v_mul_f32_e32 v209, v84, v194
	v_mul_f32_e32 v210, v85, v195
	v_mul_f32_e32 v211, v86, v196
	v_mul_f32_e32 v212, v87, v197
	v_fmac_f32_dpp v209, v84, v190 row_shr:1 row_mask:0xf bank_mask:0xf
	v_fmac_f32_dpp v210, v85, v191 row_shr:1 row_mask:0xf bank_mask:0xf
	v_fmac_f32_dpp v211, v86, v192 row_shr:1 row_mask:0xf bank_mask:0xf
	v_fmac_f32_dpp v212, v87, v193 row_shr:1 row_mask:0xf bank_mask:0xf
	v_fmac_f32_dpp v209, v84, v186 row_shr:2 row_mask:0xf bank_mask:0xf
	v_fmac_f32_dpp v210, v85, v187 row_shr:2 row_mask:0xf bank_mask:0xf
	v_fmac_f32_dpp v211, v86, v188 row_shr:2 row_mask:0xf bank_mask:0xf
	v_fmac_f32_dpp v212, v87, v189 row_shr:2 row_mask:0xf bank_mask:0xf
	v_fmac_f32_dpp v209, v96, v190 row_shl:15 row_mask:0xf bank_mask:0xf
	v_fmac_f32_dpp v210, v97, v191 row_shl:15 row_mask:0xf bank_mask:0xf
	v_fmac_f32_dpp v211, v98, v192 row_shl:15 row_mask:0xf bank_mask:0xf
	v_fmac_f32_dpp v212, v99, v193 row_shl:15 row_mask:0xf bank_mask:0xf
	v_fmac_f32_dpp v209, v96, v186 row_shl:14 row_mask:0xf bank_mask:0xf
	v_fmac_f32_dpp v210, v97, v187 row_shl:14 row_mask:0xf bank_mask:0xf
	v_fmac_f32_dpp v211, v98, v188 row_shl:14 row_mask:0xf bank_mask:0xf
	v_fmac_f32_dpp v212, v99, v189 row_shl:14 row_mask:0xf bank_mask:0xf
	v_mul_f32_e32 v76, v209, v76
	v_mul_f32_e32 v77, v210, v77
	v_mul_f32_e32 v78, v211, v78
	v_mul_f32_e32 v79, v212, v79
	v_cvt_pk_bf16_f32 v214, v76, v77
	v_cvt_pk_bf16_f32 v215, v78, v79
	v_add_u32_e32 v216, 0x8000, v206
	global_store_dwordx2 v216, v[214:215], s[40:41] nt
	v_pk_mul_f32 v[72:73], v[72:73], v[200:201] op_sel_hi:[1,0]
	v_pk_mul_f32 v[74:75], v[74:75], v[200:201] op_sel_hi:[1,0]
	v_pk_mul_f32 v[68:69], v[68:69], v[200:201] op_sel_hi:[1,0]
	v_pk_mul_f32 v[70:71], v[70:71], v[200:201] op_sel_hi:[1,0]
	v_pk_mul_f32 v[64:65], v[64:65], v[200:201] op_sel_hi:[1,0]
	v_pk_mul_f32 v[66:67], v[66:67], v[200:201] op_sel_hi:[1,0]
	v_pk_mul_f32 v[72:73], v[72:73], v[68:69]
	v_pk_mul_f32 v[74:75], v[74:75], v[70:71]
	v_mul_f32_e32 v209, v72, v194
	v_mul_f32_e32 v210, v73, v195
;     __device__ __forceinline__ void operator()(const Acc& acc, const Unit& u, int wr, int wc, int fr, int fq, LAS unsigned char* lds, f32x4 epar) const {
;     ...
;         for (int ai = 0; ai < 2; ++ai) {
;             const int strip = u.pm * 4 + ai * 2 + wr;
;             float p1prev[NV], p2prev[NV];
; #pragma unroll
;             for (int i = 0; i < NV; ++i) { p1prev[i] = 0.f; p2prev[i] = 0.f; }
; #pragma unroll
;             for (int m = 0; m < 4; ++m) {
;                 const int r = u.pm * BM + ai * HALF + wr * 64 + m * 16 + fr;
;                 const float rs = __builtin_amdgcn_rsqf(sq[ai][m] * (1.0f / DM) + RMS_EPS);
;                 float X[NV], Y[NV], o[NV];
;                 if (MODE == 0) {
; #pragma unroll
;                     for (int n = 0; n < 2; ++n)
; #pragma unroll
;                         for (int j = 0; j < 4; ++j) { X[n * 4 + j] = acc[ai][0][m][n][j] * rs; Y[n * 4 + j] = acc[ai][1][m][n][j] * rs; }
;                 } else {
; #pragma unroll
;                     for (int j = 0; j < 4; ++j) { X[j] = (acc[ai][0][m][1][j] * rs) * (acc[ai][1][m][0][j] * rs); Y[j] = acc[ai][0][m][0][j] * rs; }
;                 }
; #pragma unroll
;                 for (int i = 0; i < NV; ++i) {
;                     const float a1 = dpp_rot<0x121>(X[i]), a2 = dpp_rot<0x122>(X[i]);
;                     const float q1 = fr >= 1 ? a1 : p1prev[i], q2 = fr >= 2 ? a2 : p2prev[i];
;                     p1prev[i] = a1; p2prev[i] = a2;
;                     const float cv = w2[i] * X[i] + w1[i] * q1 + w0[i] * q2 + bb[i];
;                     o[i] = MODE == 0 ? silu_f(cv) * Y[i] : cv * Y[i];
;                 }
;                 if (m == 0 && fr < 2) {
;                     bf16_t* hx = halo + ((size_t)strip * 6 + 2 + fr) * C + c0; bf16_t* hy = halo + ((size_t)strip * 6 + 4 + fr) * C + c0;
;                     u32x4 px, py; px.x = cvt_pk_bf16(X[0], X[1]); px.y = cvt_pk_bf16(X[2], X[3]); px.z = cvt_pk_bf16(X[4 % NV], X[5 % NV]); px.w = cvt_pk_bf16(X[6 % NV], X[7 % NV]);
;                     py.x = cvt_pk_bf16(Y[0], Y[1]); py.y = cvt_pk_bf16(Y[2], Y[3]); py.z = cvt_pk_bf16(Y[4 % NV], Y[5 % NV]); py.w = cvt_pk_bf16(Y[6 % NV], Y[7 % NV]);
;                     if (MODE == 0) { *(u32x4*)hx = px; *(u32x4*)hy = py; } else { u32x2 a; a.x = px.x; a.y = px.y; *(u32x2*)hx = a; u32x2 b; b.x = py.x; b.y = py.y; *(u32x2*)hy = b; }
;                 } else {
	v_mul_f32_e32 v211, v74, v196
	v_mul_f32_e32 v212, v75, v197
	v_fmac_f32_dpp v209, v72, v190 row_shr:1 row_mask:0xf bank_mask:0xf
	v_fmac_f32_dpp v210, v73, v191 row_shr:1 row_mask:0xf bank_mask:0xf
	v_fmac_f32_dpp v211, v74, v192 row_shr:1 row_mask:0xf bank_mask:0xf
	v_fmac_f32_dpp v212, v75, v193 row_shr:1 row_mask:0xf bank_mask:0xf
	v_fmac_f32_dpp v209, v72, v186 row_shr:2 row_mask:0xf bank_mask:0xf
	v_fmac_f32_dpp v210, v73, v187 row_shr:2 row_mask:0xf bank_mask:0xf
	v_fmac_f32_dpp v211, v74, v188 row_shr:2 row_mask:0xf bank_mask:0xf
	v_fmac_f32_dpp v212, v75, v189 row_shr:2 row_mask:0xf bank_mask:0xf
	v_fmac_f32_dpp v209, v84, v190 row_shl:15 row_mask:0xf bank_mask:0xf
	v_fmac_f32_dpp v210, v85, v191 row_shl:15 row_mask:0xf bank_mask:0xf
	v_fmac_f32_dpp v211, v86, v192 row_shl:15 row_mask:0xf bank_mask:0xf
	v_fmac_f32_dpp v212, v87, v193 row_shl:15 row_mask:0xf bank_mask:0xf
	v_fmac_f32_dpp v209, v84, v186 row_shl:14 row_mask:0xf bank_mask:0xf
	v_fmac_f32_dpp v210, v85, v187 row_shl:14 row_mask:0xf bank_mask:0xf
	v_fmac_f32_dpp v211, v86, v188 row_shl:14 row_mask:0xf bank_mask:0xf
	v_fmac_f32_dpp v212, v87, v189 row_shl:14 row_mask:0xf bank_mask:0xf
	v_mul_f32_e32 v64, v209, v64
	v_mul_f32_e32 v65, v210, v65
	v_mul_f32_e32 v66, v211, v66
	v_mul_f32_e32 v67, v212, v67
	v_cvt_pk_bf16_f32 v214, v64, v65
	v_cvt_pk_bf16_f32 v215, v66, v67
	v_add_u32_e32 v216, 0x10000, v206
	global_store_dwordx2 v216, v[214:215], s[40:41] nt
	v_pk_mul_f32 v[60:61], v[60:61], v[200:201] op_sel:[0,1]
	v_pk_mul_f32 v[62:63], v[62:63], v[200:201] op_sel:[0,1]
	v_pk_mul_f32 v[56:57], v[56:57], v[200:201] op_sel:[0,1]
	v_pk_mul_f32 v[58:59], v[58:59], v[200:201] op_sel:[0,1]
	v_pk_mul_f32 v[52:53], v[52:53], v[200:201] op_sel:[0,1]
	v_pk_mul_f32 v[54:55], v[54:55], v[200:201] op_sel:[0,1]
	v_pk_mul_f32 v[60:61], v[60:61], v[56:57]
	v_pk_mul_f32 v[62:63], v[62:63], v[58:59]
	v_mul_f32_e32 v209, v60, v194
	v_mul_f32_e32 v210, v61, v195
	v_mul_f32_e32 v211, v62, v196
	v_mul_f32_e32 v212, v63, v197
	v_cvt_pk_bf16_f32 v218, v60, v61
	v_cvt_pk_bf16_f32 v219, v62, v63
	v_add_u32_e32 v217, 0xffff9000, v208
	s_and_b64 exec, exec, s[10:11]
	global_store_dwordx2 v217, v[218:219], s[42:43]
	s_mov_b64 exec, s[24:25]
	v_fmac_f32_dpp v209, v60, v190 row_shr:1 row_mask:0xf bank_mask:0xf
	v_fmac_f32_dpp v210, v61, v191 row_shr:1 row_mask:0xf bank_mask:0xf
	v_fmac_f32_dpp v211, v62, v192 row_shr:1 row_mask:0xf bank_mask:0xf
	v_fmac_f32_dpp v212, v63, v193 row_shr:1 row_mask:0xf bank_mask:0xf
	v_fmac_f32_dpp v209, v60, v186 row_shr:2 row_mask:0xf bank_mask:0xf
	v_fmac_f32_dpp v210, v61, v187 row_shr:2 row_mask:0xf bank_mask:0xf
	v_fmac_f32_dpp v211, v62, v188 row_shr:2 row_mask:0xf bank_mask:0xf
	v_fmac_f32_dpp v212, v63, v189 row_shr:2 row_mask:0xf bank_mask:0xf
	v_fmac_f32_dpp v209, v72, v190 row_shl:15 row_mask:0xf bank_mask:0xf
	v_fmac_f32_dpp v210, v73, v191 row_shl:15 row_mask:0xf bank_mask:0xf
	v_fmac_f32_dpp v211, v74, v192 row_shl:15 row_mask:0xf bank_mask:0xf
	v_fmac_f32_dpp v212, v75, v193 row_shl:15 row_mask:0xf bank_mask:0xf
	v_fmac_f32_dpp v209, v72, v186 row_shl:14 row_mask:0xf bank_mask:0xf
	v_fmac_f32_dpp v210, v73, v187 row_shl:14 row_mask:0xf bank_mask:0xf
	v_fmac_f32_dpp v211, v74, v188 row_shl:14 row_mask:0xf bank_mask:0xf
	v_fmac_f32_dpp v212, v75, v189 row_shl:14 row_mask:0xf bank_mask:0xf
	v_mul_f32_e32 v52, v209, v52
	v_mul_f32_e32 v53, v210, v53
	v_mul_f32_e32 v54, v211, v54
	v_mul_f32_e32 v55, v212, v55
	v_cvt_pk_bf16_f32 v214, v52, v53
	v_cvt_pk_bf16_f32 v215, v54, v55
	v_add_u32_e32 v216, 0x18000, v206
	global_store_dwordx2 v216, v[214:215], s[40:41] nt
	v_pk_mul_f32 v[48:49], v[48:49], v[202:203] op_sel_hi:[1,0]
	v_pk_mul_f32 v[50:51], v[50:51], v[202:203] op_sel_hi:[1,0]
	v_pk_mul_f32 v[40:41], v[40:41], v[202:203] op_sel_hi:[1,0]
	v_pk_mul_f32 v[42:43], v[42:43], v[202:203] op_sel_hi:[1,0]
	v_pk_mul_f32 v[44:45], v[44:45], v[202:203] op_sel_hi:[1,0]
	v_pk_mul_f32 v[46:47], v[46:47], v[202:203] op_sel_hi:[1,0]
	v_pk_mul_f32 v[48:49], v[48:49], v[40:41]
	v_pk_mul_f32 v[50:51], v[50:51], v[42:43]
	v_mul_f32_e32 v209, v48, v194
	v_mul_f32_e32 v210, v49, v195
	v_mul_f32_e32 v211, v50, v196
	v_mul_f32_e32 v212, v51, v197
	v_cvt_pk_bf16_f32 v218, v48, v49
	v_cvt_pk_bf16_f32 v219, v50, v51
	v_cvt_pk_bf16_f32 v220, v44, v45
	v_cvt_pk_bf16_f32 v221, v46, v47
	v_add_u32_e32 v216, 0x7000, v208
	v_add_u32_e32 v217, 0x8000, v208
	s_andn2_b64 exec, exec, s[8:9]
	global_store_dwordx2 v216, v[218:219], s[42:43]
	global_store_dwordx2 v217, v[220:221], s[42:43]
	s_mov_b64 exec, s[24:25]
	v_fmac_f32_dpp v209, v48, v190 row_shr:1 row_mask:0xf bank_mask:0xf
	v_fmac_f32_dpp v210, v49, v191 row_shr:1 row_mask:0xf bank_mask:0xf
	v_fmac_f32_dpp v211, v50, v192 row_shr:1 row_mask:0xf bank_mask:0xf
	v_fmac_f32_dpp v212, v51, v193 row_shr:1 row_mask:0xf bank_mask:0xf
	v_fmac_f32_dpp v209, v48, v186 row_shr:2 row_mask:0xf bank_mask:0xf
	v_fmac_f32_dpp v210, v49, v187 row_shr:2 row_mask:0xf bank_mask:0xf
	v_fmac_f32_dpp v211, v50, v188 row_shr:2 row_mask:0xf bank_mask:0xf
	v_fmac_f32_dpp v212, v51, v189 row_shr:2 row_mask:0xf bank_mask:0xf
	v_mul_f32_e32 v44, v209, v44
	v_mul_f32_e32 v45, v210, v45
	v_mul_f32_e32 v46, v211, v46
	v_mul_f32_e32 v47, v212, v47
	v_cvt_pk_bf16_f32 v214, v44, v45
	v_cvt_pk_bf16_f32 v215, v46, v47
	v_add_u32_e32 v216, 0x40000, v206
	s_and_b64 exec, exec, s[8:9]
	global_store_dwordx2 v216, v[214:215], s[40:41] nt
	s_mov_b64 exec, s[24:25]
	v_pk_mul_f32 v[36:37], v[36:37], v[202:203] op_sel:[0,1]
	v_pk_mul_f32 v[38:39], v[38:39], v[202:203] op_sel:[0,1]
	v_pk_mul_f32 v[32:33], v[32:33], v[202:203] op_sel:[0,1]
	v_pk_mul_f32 v[34:35], v[34:35], v[202:203] op_sel:[0,1]
;     __device__ __forceinline__ void operator()(const Acc& acc, const Unit& u, int wr, int wc, int fr, int fq, LAS unsigned char* lds, f32x4 epar) const {
;     ...
;         for (int ai = 0; ai < 2; ++ai) {
;             const int strip = u.pm * 4 + ai * 2 + wr;
;             float p1prev[NV], p2prev[NV];
; #pragma unroll
;             for (int i = 0; i < NV; ++i) { p1prev[i] = 0.f; p2prev[i] = 0.f; }
; #pragma unroll
;             for (int m = 0; m < 4; ++m) {
;                 const int r = u.pm * BM + ai * HALF + wr * 64 + m * 16 + fr;
;                 const float rs = __builtin_amdgcn_rsqf(sq[ai][m] * (1.0f / DM) + RMS_EPS);
;                 float X[NV], Y[NV], o[NV];
;                 if (MODE == 0) {
; #pragma unroll
;                     for (int n = 0; n < 2; ++n)
; #pragma unroll
;                         for (int j = 0; j < 4; ++j) { X[n * 4 + j] = acc[ai][0][m][n][j] * rs; Y[n * 4 + j] = acc[ai][1][m][n][j] * rs; }
;                 } else {
; #pragma unroll
;                     for (int j = 0; j < 4; ++j) { X[j] = (acc[ai][0][m][1][j] * rs) * (acc[ai][1][m][0][j] * rs); Y[j] = acc[ai][0][m][0][j] * rs; }
;                 }
; #pragma unroll
;                 for (int i = 0; i < NV; ++i) {
;                     const float a1 = dpp_rot<0x121>(X[i]), a2 = dpp_rot<0x122>(X[i]);
;                     const float q1 = fr >= 1 ? a1 : p1prev[i], q2 = fr >= 2 ? a2 : p2prev[i];
;                     p1prev[i] = a1; p2prev[i] = a2;
;                     const float cv = w2[i] * X[i] + w1[i] * q1 + w0[i] * q2 + bb[i];
;                     o[i] = MODE == 0 ? silu_f(cv) * Y[i] : cv * Y[i];
;                 }
;                 if (m == 0 && fr < 2) {
;                     bf16_t* hx = halo + ((size_t)strip * 6 + 2 + fr) * C + c0; bf16_t* hy = halo + ((size_t)strip * 6 + 4 + fr) * C + c0;
;                     u32x4 px, py; px.x = cvt_pk_bf16(X[0], X[1]); px.y = cvt_pk_bf16(X[2], X[3]); px.z = cvt_pk_bf16(X[4 % NV], X[5 % NV]); px.w = cvt_pk_bf16(X[6 % NV], X[7 % NV]);
;                     py.x = cvt_pk_bf16(Y[0], Y[1]); py.y = cvt_pk_bf16(Y[2], Y[3]); py.z = cvt_pk_bf16(Y[4 % NV], Y[5 % NV]); py.w = cvt_pk_bf16(Y[6 % NV], Y[7 % NV]);
;                     if (MODE == 0) { *(u32x4*)hx = px; *(u32x4*)hy = py; } else { u32x2 a; a.x = px.x; a.y = px.y; *(u32x2*)hx = a; u32x2 b; b.x = py.x; b.y = py.y; *(u32x2*)hy = b; }
;                 } else {
	v_pk_mul_f32 v[28:29], v[28:29], v[202:203] op_sel:[0,1]
	v_pk_mul_f32 v[30:31], v[30:31], v[202:203] op_sel:[0,1]
	v_pk_mul_f32 v[36:37], v[36:37], v[32:33]
	v_pk_mul_f32 v[38:39], v[38:39], v[34:35]
	v_mul_f32_e32 v209, v36, v194
	v_mul_f32_e32 v210, v37, v195
	v_mul_f32_e32 v211, v38, v196
	v_mul_f32_e32 v212, v39, v197
	v_fmac_f32_dpp v209, v36, v190 row_shr:1 row_mask:0xf bank_mask:0xf
	v_fmac_f32_dpp v210, v37, v191 row_shr:1 row_mask:0xf bank_mask:0xf
	v_fmac_f32_dpp v211, v38, v192 row_shr:1 row_mask:0xf bank_mask:0xf
	v_fmac_f32_dpp v212, v39, v193 row_shr:1 row_mask:0xf bank_mask:0xf
	v_fmac_f32_dpp v209, v36, v186 row_shr:2 row_mask:0xf bank_mask:0xf
	v_fmac_f32_dpp v210, v37, v187 row_shr:2 row_mask:0xf bank_mask:0xf
	v_fmac_f32_dpp v211, v38, v188 row_shr:2 row_mask:0xf bank_mask:0xf
	v_fmac_f32_dpp v212, v39, v189 row_shr:2 row_mask:0xf bank_mask:0xf
	v_fmac_f32_dpp v209, v48, v190 row_shl:15 row_mask:0xf bank_mask:0xf
	v_fmac_f32_dpp v210, v49, v191 row_shl:15 row_mask:0xf bank_mask:0xf
	v_fmac_f32_dpp v211, v50, v192 row_shl:15 row_mask:0xf bank_mask:0xf
	v_fmac_f32_dpp v212, v51, v193 row_shl:15 row_mask:0xf bank_mask:0xf
	v_fmac_f32_dpp v209, v48, v186 row_shl:14 row_mask:0xf bank_mask:0xf
	v_fmac_f32_dpp v210, v49, v187 row_shl:14 row_mask:0xf bank_mask:0xf
	v_fmac_f32_dpp v211, v50, v188 row_shl:14 row_mask:0xf bank_mask:0xf
	v_fmac_f32_dpp v212, v51, v189 row_shl:14 row_mask:0xf bank_mask:0xf
	v_mul_f32_e32 v28, v209, v28
	v_mul_f32_e32 v29, v210, v29
	v_mul_f32_e32 v30, v211, v30
	v_mul_f32_e32 v31, v212, v31
	v_cvt_pk_bf16_f32 v214, v28, v29
	v_cvt_pk_bf16_f32 v215, v30, v31
	v_add_u32_e32 v216, 0x48000, v206
	global_store_dwordx2 v216, v[214:215], s[40:41] nt
	v_pk_mul_f32 v[20:21], v[20:21], v[204:205] op_sel_hi:[1,0]
	v_pk_mul_f32 v[22:23], v[22:23], v[204:205] op_sel_hi:[1,0]
	v_pk_mul_f32 v[16:17], v[16:17], v[204:205] op_sel_hi:[1,0]
	v_pk_mul_f32 v[18:19], v[18:19], v[204:205] op_sel_hi:[1,0]
	v_pk_mul_f32 v[12:13], v[12:13], v[204:205] op_sel_hi:[1,0]
	v_pk_mul_f32 v[14:15], v[14:15], v[204:205] op_sel_hi:[1,0]
	v_pk_mul_f32 v[20:21], v[20:21], v[16:17]
	v_pk_mul_f32 v[22:23], v[22:23], v[18:19]
	v_mul_f32_e32 v209, v20, v194
	v_mul_f32_e32 v210, v21, v195
	v_mul_f32_e32 v211, v22, v196
	v_mul_f32_e32 v212, v23, v197
	v_fmac_f32_dpp v209, v20, v190 row_shr:1 row_mask:0xf bank_mask:0xf
	v_fmac_f32_dpp v210, v21, v191 row_shr:1 row_mask:0xf bank_mask:0xf
	v_fmac_f32_dpp v211, v22, v192 row_shr:1 row_mask:0xf bank_mask:0xf
	v_fmac_f32_dpp v212, v23, v193 row_shr:1 row_mask:0xf bank_mask:0xf
	v_fmac_f32_dpp v209, v20, v186 row_shr:2 row_mask:0xf bank_mask:0xf
	v_fmac_f32_dpp v210, v21, v187 row_shr:2 row_mask:0xf bank_mask:0xf
	v_fmac_f32_dpp v211, v22, v188 row_shr:2 row_mask:0xf bank_mask:0xf
	v_fmac_f32_dpp v212, v23, v189 row_shr:2 row_mask:0xf bank_mask:0xf
	v_fmac_f32_dpp v209, v36, v190 row_shl:15 row_mask:0xf bank_mask:0xf
	v_fmac_f32_dpp v210, v37, v191 row_shl:15 row_mask:0xf bank_mask:0xf
	v_fmac_f32_dpp v211, v38, v192 row_shl:15 row_mask:0xf bank_mask:0xf
	v_fmac_f32_dpp v212, v39, v193 row_shl:15 row_mask:0xf bank_mask:0xf
	v_fmac_f32_dpp v209, v36, v186 row_shl:14 row_mask:0xf bank_mask:0xf
	v_fmac_f32_dpp v210, v37, v187 row_shl:14 row_mask:0xf bank_mask:0xf
	v_fmac_f32_dpp v211, v38, v188 row_shl:14 row_mask:0xf bank_mask:0xf
	v_fmac_f32_dpp v212, v39, v189 row_shl:14 row_mask:0xf bank_mask:0xf
	v_mul_f32_e32 v12, v209, v12
	v_mul_f32_e32 v13, v210, v13
	v_mul_f32_e32 v14, v211, v14
	v_mul_f32_e32 v15, v212, v15
	v_cvt_pk_bf16_f32 v214, v12, v13
	v_cvt_pk_bf16_f32 v215, v14, v15
	v_add_u32_e32 v216, 0x50000, v206
	global_store_dwordx2 v216, v[214:215], s[40:41] nt
	v_pk_mul_f32 v[8:9], v[8:9], v[204:205] op_sel:[0,1]
	v_pk_mul_f32 v[10:11], v[10:11], v[204:205] op_sel:[0,1]
	v_pk_mul_f32 v[4:5], v[4:5], v[204:205] op_sel:[0,1]
	v_pk_mul_f32 v[6:7], v[6:7], v[204:205] op_sel:[0,1]
	v_pk_mul_f32 v[0:1], v[0:1], v[204:205] op_sel:[0,1]
	v_pk_mul_f32 v[2:3], v[2:3], v[204:205] op_sel:[0,1]
	v_pk_mul_f32 v[8:9], v[8:9], v[4:5]
	v_pk_mul_f32 v[10:11], v[10:11], v[6:7]
	v_mul_f32_e32 v209, v8, v194
	v_mul_f32_e32 v210, v9, v195
	v_mul_f32_e32 v211, v10, v196
	v_mul_f32_e32 v212, v11, v197
	v_cvt_pk_bf16_f32 v218, v8, v9
	v_cvt_pk_bf16_f32 v219, v10, v11
	v_add_u32_e32 v217, 0xfffff000, v208
	s_and_b64 exec, exec, s[10:11]
	global_store_dwordx2 v217, v[218:219], s[42:43]
	s_mov_b64 exec, s[24:25]
	v_fmac_f32_dpp v209, v8, v190 row_shr:1 row_mask:0xf bank_mask:0xf
	v_fmac_f32_dpp v210, v9, v191 row_shr:1 row_mask:0xf bank_mask:0xf
	v_fmac_f32_dpp v211, v10, v192 row_shr:1 row_mask:0xf bank_mask:0xf
	v_fmac_f32_dpp v212, v11, v193 row_shr:1 row_mask:0xf bank_mask:0xf
	v_fmac_f32_dpp v209, v8, v186 row_shr:2 row_mask:0xf bank_mask:0xf
	v_fmac_f32_dpp v210, v9, v187 row_shr:2 row_mask:0xf bank_mask:0xf
	v_fmac_f32_dpp v211, v10, v188 row_shr:2 row_mask:0xf bank_mask:0xf
	v_fmac_f32_dpp v212, v11, v189 row_shr:2 row_mask:0xf bank_mask:0xf
	v_fmac_f32_dpp v209, v20, v190 row_shl:15 row_mask:0xf bank_mask:0xf
	v_fmac_f32_dpp v210, v21, v191 row_shl:15 row_mask:0xf bank_mask:0xf
	v_fmac_f32_dpp v211, v22, v192 row_shl:15 row_mask:0xf bank_mask:0xf
	v_fmac_f32_dpp v212, v23, v193 row_shl:15 row_mask:0xf bank_mask:0xf
	v_fmac_f32_dpp v209, v20, v186 row_shl:14 row_mask:0xf bank_mask:0xf
	v_fmac_f32_dpp v210, v21, v187 row_shl:14 row_mask:0xf bank_mask:0xf
	v_fmac_f32_dpp v211, v22, v188 row_shl:14 row_mask:0xf bank_mask:0xf
	v_fmac_f32_dpp v212, v23, v189 row_shl:14 row_mask:0xf bank_mask:0xf
	v_mul_f32_e32 v0, v209, v0
	v_mul_f32_e32 v1, v210, v1
	v_mul_f32_e32 v2, v211, v2
	v_mul_f32_e32 v3, v212, v3
	v_cvt_pk_bf16_f32 v214, v0, v1
	v_cvt_pk_bf16_f32 v215, v2, v3
	v_add_u32_e32 v216, 0x58000, v206
	global_store_dwordx2 v216, v[214:215], s[40:41] nt

;     __device__ __forceinline__ void operator()(const Acc& acc, const Unit& u, int wr, int wc, int fr, int fq, LAS unsigned char* lds, f32x4 epar) const {
;         constexpr int NV = MODE == 0 ? 8 : 4;
;         const int c0 = MODE == 0 ? (u.pn * 128 + wc * 32 + 8 * fq) : (u.pn * 64 + wc * 16 + 4 * fq);
;         LAS float* pw = (LAS float*)(lds + STAGE_BYTES + 64 + (wr * 4 + wc) * 1024);
;         *(LAS f32x4*)(pw + (fq * 16 + fr) * 4) = epar;
;         asm volatile("s_waitcnt lgkmcnt(0)" ::: "memory");
;         float w0[NV], w1[NV], w2[NV], bb[NV];
; #pragma unroll
;         for (int i = 0; i < NV; i += 4) { const f32x4 a = *(const LAS f32x4*)(pw + NV * fq + i), b = *(const LAS f32x4*)(pw + 32 + NV * fq + i), c = *(const LAS f32x4*)(pw + 64 + NV * fq + i);
;             f32x4 d = (f32x4){0.f, 0.f, 0.f, 0.f}; if (MODE == 0) d = *(const LAS f32x4*)(pw + 96 + NV * fq + i);
; #pragma unroll
;             for (int j = 0; j < 4; ++j) { w0[i + j] = a[j]; w1[i + j] = b[j]; w2[i + j] = c[j]; bb[i + j] = d[j]; } }
;         float sq[2][4];
; #pragma unroll
;         for (int ai = 0; ai < 2; ++ai)
; #pragma unroll
;             for (int m = 0; m < 4; ++m) sq[ai][m] = pw[128 + ai * 64 + m * 16 + fr];
; #pragma unroll
;         for (int ai = 0; ai < 2; ++ai) {
;             const int strip = u.pm * 4 + ai * 2 + wr;
;             float p1prev[NV], p2prev[NV];
; #pragma unroll
;             for (int i = 0; i < NV; ++i) { p1prev[i] = 0.f; p2prev[i] = 0.f; }
; #pragma unroll
;             for (int m = 0; m < 4; ++m) {
;                 const int r = u.pm * BM + ai * HALF + wr * 64 + m * 16 + fr;
;                 const float rs = __builtin_amdgcn_rsqf(sq[ai][m] * (1.0f / DM) + RMS_EPS);
;                 float X[NV], Y[NV], o[NV];
;                 if (MODE == 0) {
; #pragma unroll
;                     for (int n = 0; n < 2; ++n)
; #pragma unroll
;                         for (int j = 0; j < 4; ++j) { X[n * 4 + j] = acc[ai][0][m][n][j] * rs; Y[n * 4 + j] = acc[ai][1][m][n][j] * rs; }
;                 } else {
; #pragma unroll
;                     for (int j = 0; j < 4; ++j) { X[j] = (acc[ai][0][m][1][j] * rs) * (acc[ai][1][m][0][j] * rs); Y[j] = acc[ai][0][m][0][j] * rs; }
;                 }
; #pragma unroll
;                 for (int i = 0; i < NV; ++i) {
;                     const float a1 = dpp_rot<0x121>(X[i]), a2 = dpp_rot<0x122>(X[i]);
.LBB0_986:
	.p2align 6
	s_nop 0
	s_nop 0
	s_nop 0
	s_nop 0
	s_nop 0
	s_nop 0
	s_nop 0
	s_nop 0
	s_nop 0
	s_nop 0
	s_nop 0
	s_nop 0
	s_nop 0
	s_nop 0
	s_nop 0
	s_mov_b32 s100, 0xbfb8aa3b
	ds_write_b128 v198, v[72:75]
	s_mov_b64 s[24:25], exec
	s_waitcnt lgkmcnt(0)
	ds_read_b128 v[88:91], v199
	ds_read_b128 v[92:95], v199 offset:16
	ds_read_b128 v[128:131], v199 offset:128
	ds_read_b128 v[132:135], v199 offset:144
	ds_read_b128 v[136:139], v199 offset:256
	ds_read_b128 v[140:143], v199 offset:272
	ds_read_b128 v[174:177], v199 offset:384
	ds_read_b128 v[178:181], v199 offset:400
	ds_read2_b32 v[182:183], v191 offset0:128 offset1:144
	ds_read2_b32 v[184:185], v191 offset0:160 offset1:176
	ds_read2_b32 v[76:77], v191 offset0:192 offset1:208
	ds_read2_b32 v[78:79], v191 offset0:224 offset1:240
	v_lshl_add_u32 v230, s66, 8, v190
	v_lshl_or_b32 v231, s70, 7, v192
	v_mul_u32_u24_e32 v230, 0x1600, v230
	s_lshl_b32 s26, s66, 2
	s_add_i32 s26, s26, s15
	s_mul_i32 s16, s26, 6
	v_and_b32_e32 v233, 15, v190
	v_lshl_add_u32 v230, v231, 1, v230
	v_add_u32_e32 v233, s16, v233
	v_mul_u32_u24_e32 v233, 0x1600, v233
	s_nop 0
	v_lshl_add_u32 v233, v231, 1, v233
	s_waitcnt lgkmcnt(0)
	v_pk_mul_f32 v[88:89], s[100:101], v[88:89] op_sel_hi:[0,1]
	v_pk_mul_f32 v[90:91], s[100:101], v[90:91] op_sel_hi:[0,1]
	v_pk_mul_f32 v[92:93], s[100:101], v[92:93] op_sel_hi:[0,1]
	v_pk_mul_f32 v[94:95], s[100:101], v[94:95] op_sel_hi:[0,1]
	v_pk_mul_f32 v[128:129], s[100:101], v[128:129] op_sel_hi:[0,1]
	v_pk_mul_f32 v[130:131], s[100:101], v[130:131] op_sel_hi:[0,1]
	v_pk_mul_f32 v[132:133], s[100:101], v[132:133] op_sel_hi:[0,1]
	v_pk_mul_f32 v[134:135], s[100:101], v[134:135] op_sel_hi:[0,1]
	v_pk_mul_f32 v[136:137], s[100:101], v[136:137] op_sel_hi:[0,1]
	v_pk_mul_f32 v[138:139], s[100:101], v[138:139] op_sel_hi:[0,1]
	v_pk_mul_f32 v[140:141], s[100:101], v[140:141] op_sel_hi:[0,1]
	v_pk_mul_f32 v[142:143], s[100:101], v[142:143] op_sel_hi:[0,1]
	v_pk_mul_f32 v[174:175], s[100:101], v[174:175] op_sel_hi:[0,1]
	v_pk_mul_f32 v[176:177], s[100:101], v[176:177] op_sel_hi:[0,1]
	v_pk_mul_f32 v[178:179], s[100:101], v[178:179] op_sel_hi:[0,1]
	v_pk_mul_f32 v[180:181], s[100:101], v[180:181] op_sel_hi:[0,1]
	v_fmamk_f32 v182, v182, 0x3a800000, v200
	v_fmamk_f32 v183, v183, 0x3a800000, v200
	v_fmamk_f32 v184, v184, 0x3a800000, v200
	v_fmamk_f32 v185, v185, 0x3a800000, v200
	v_fmamk_f32 v76, v76, 0x3a800000, v200
	v_fmamk_f32 v77, v77, 0x3a800000, v200
	v_fmamk_f32 v78, v78, 0x3a800000, v200
	v_fmamk_f32 v79, v79, 0x3a800000, v200
	v_pk_mul_f32 v[202:203], s[100:101], v[182:183] op_sel_hi:[0,1]
	v_pk_mul_f32 v[204:205], s[100:101], v[184:185] op_sel_hi:[0,1]
	v_pk_mul_f32 v[206:207], s[100:101], v[76:77] op_sel_hi:[0,1]
	v_pk_mul_f32 v[208:209], s[100:101], v[78:79] op_sel_hi:[0,1]
	v_rsq_f32_e32 v182, v182
	v_rsq_f32_e32 v183, v183
	v_rsq_f32_e32 v184, v184
	v_rsq_f32_e32 v185, v185
	v_rsq_f32_e32 v76, v76
	v_rsq_f32_e32 v77, v77
	v_rsq_f32_e32 v78, v78
	v_rsq_f32_e32 v79, v79
	s_nop 0
	v_pk_mul_f32 v[202:203], v[202:203], v[182:183]
	v_pk_mul_f32 v[204:205], v[204:205], v[184:185]
	v_pk_mul_f32 v[206:207], v[206:207], v[76:77]
	v_pk_mul_f32 v[208:209], v[208:209], v[78:79]
	v_pk_mul_f32 v[152:153], v[152:153], v[182:183] op_sel_hi:[1,0]
	v_pk_mul_f32 v[154:155], v[154:155], v[182:183] op_sel_hi:[1,0]
	v_pk_mul_f32 v[144:145], v[144:145], v[182:183] op_sel_hi:[1,0]
	v_pk_mul_f32 v[146:147], v[146:147], v[182:183] op_sel_hi:[1,0]
	v_pk_fma_f32 v[210:211], v[152:153], v[136:137], v[174:175]
	v_pk_fma_f32 v[212:213], v[154:155], v[138:139], v[176:177]
	v_pk_fma_f32 v[214:215], v[144:145], v[140:141], v[178:179]
	v_pk_fma_f32 v[216:217], v[146:147], v[142:143], v[180:181]
	v_pk_mul_f32 v[218:219], v[156:157], v[182:183] op_sel_hi:[1,0]
	v_pk_mul_f32 v[220:221], v[158:159], v[182:183] op_sel_hi:[1,0]
	v_pk_mul_f32 v[222:223], v[148:149], v[182:183] op_sel_hi:[1,0]
	v_pk_mul_f32 v[224:225], v[150:151], v[182:183] op_sel_hi:[1,0]
	v_cvt_pk_bf16_f32 v236, v152, v153
	v_cvt_pk_bf16_f32 v237, v154, v155
	v_cvt_pk_bf16_f32 v238, v144, v145
	v_cvt_pk_bf16_f32 v239, v146, v147
	v_cvt_pk_bf16_f32 v240, v218, v219
	v_cvt_pk_bf16_f32 v241, v220, v221
	v_cvt_pk_bf16_f32 v242, v222, v223
	v_cvt_pk_bf16_f32 v243, v224, v225
	v_add_u32_e32 v234, 0x2c00, v233
	v_add_u32_e32 v235, 0x5800, v233
	s_andn2_b64 exec, exec, s[8:9]
	global_store_dwordx4 v234, v[236:239], s[42:43]
	global_store_dwordx4 v235, v[240:243], s[42:43]
	s_mov_b64 exec, s[24:25]
	v_fmac_f32_dpp v210, v152, v128 row_shr:1 row_mask:0xf bank_mask:0xf
	v_fmac_f32_dpp v211, v153, v129 row_shr:1 row_mask:0xf bank_mask:0xf
	v_fmac_f32_dpp v212, v154, v130 row_shr:1 row_mask:0xf bank_mask:0xf
	v_fmac_f32_dpp v213, v155, v131 row_shr:1 row_mask:0xf bank_mask:0xf
	v_fmac_f32_dpp v214, v144, v132 row_shr:1 row_mask:0xf bank_mask:0xf
	v_fmac_f32_dpp v215, v145, v133 row_shr:1 row_mask:0xf bank_mask:0xf
	v_fmac_f32_dpp v216, v146, v134 row_shr:1 row_mask:0xf bank_mask:0xf
	v_fmac_f32_dpp v217, v147, v135 row_shr:1 row_mask:0xf bank_mask:0xf
	v_fmac_f32_dpp v210, v152, v88 row_shr:2 row_mask:0xf bank_mask:0xf
	v_fmac_f32_dpp v211, v153, v89 row_shr:2 row_mask:0xf bank_mask:0xf
	v_fmac_f32_dpp v212, v154, v90 row_shr:2 row_mask:0xf bank_mask:0xf
	v_fmac_f32_dpp v213, v155, v91 row_shr:2 row_mask:0xf bank_mask:0xf
	v_fmac_f32_dpp v214, v144, v92 row_shr:2 row_mask:0xf bank_mask:0xf
	v_fmac_f32_dpp v215, v145, v93 row_shr:2 row_mask:0xf bank_mask:0xf
	v_fmac_f32_dpp v216, v146, v94 row_shr:2 row_mask:0xf bank_mask:0xf
	v_fmac_f32_dpp v217, v147, v95 row_shr:2 row_mask:0xf bank_mask:0xf
	v_exp_f32_e32 v218, v210
	v_exp_f32_e32 v219, v211
;     __device__ __forceinline__ void operator()(const Acc& acc, const Unit& u, int wr, int wc, int fr, int fq, LAS unsigned char* lds, f32x4 epar) const {
;     ...
;             for (int m = 0; m < 4; ++m) {
;                 const int r = u.pm * BM + ai * HALF + wr * 64 + m * 16 + fr;
;                 const float rs = __builtin_amdgcn_rsqf(sq[ai][m] * (1.0f / DM) + RMS_EPS);
;                 float X[NV], Y[NV], o[NV];
;                 if (MODE == 0) {
; #pragma unroll
;                     for (int n = 0; n < 2; ++n)
; #pragma unroll
;                         for (int j = 0; j < 4; ++j) { X[n * 4 + j] = acc[ai][0][m][n][j] * rs; Y[n * 4 + j] = acc[ai][1][m][n][j] * rs; }
;                 } else {
; #pragma unroll
;                     for (int j = 0; j < 4; ++j) { X[j] = (acc[ai][0][m][1][j] * rs) * (acc[ai][1][m][0][j] * rs); Y[j] = acc[ai][0][m][0][j] * rs; }
;                 }
; #pragma unroll
;                 for (int i = 0; i < NV; ++i) {
;                     const float a1 = dpp_rot<0x121>(X[i]), a2 = dpp_rot<0x122>(X[i]);
;                     const float q1 = fr >= 1 ? a1 : p1prev[i], q2 = fr >= 2 ? a2 : p2prev[i];
;                     p1prev[i] = a1; p2prev[i] = a2;
;                     const float cv = w2[i] * X[i] + w1[i] * q1 + w0[i] * q2 + bb[i];
;                     o[i] = MODE == 0 ? silu_f(cv) * Y[i] : cv * Y[i];
;                 }
;                 if (m == 0 && fr < 2) {
;                     bf16_t* hx = halo + ((size_t)strip * 6 + 2 + fr) * C + c0; bf16_t* hy = halo + ((size_t)strip * 6 + 4 + fr) * C + c0;
;                     u32x4 px, py; px.x = cvt_pk_bf16(X[0], X[1]); px.y = cvt_pk_bf16(X[2], X[3]); px.z = cvt_pk_bf16(X[4 % NV], X[5 % NV]); px.w = cvt_pk_bf16(X[6 % NV], X[7 % NV]);
;                     py.x = cvt_pk_bf16(Y[0], Y[1]); py.y = cvt_pk_bf16(Y[2], Y[3]); py.z = cvt_pk_bf16(Y[4 % NV], Y[5 % NV]); py.w = cvt_pk_bf16(Y[6 % NV], Y[7 % NV]);
;                     if (MODE == 0) { *(u32x4*)hx = px; *(u32x4*)hy = py; } else { u32x2 a; a.x = px.x; a.y = px.y; *(u32x2*)hx = a; u32x2 b; b.x = py.x; b.y = py.y; *(u32x2*)hy = b; }
;                 } else {
;                     if (MODE == 0) { u32x4 w; w.x = cvt_pk_bf16(o[0], o[1]); w.y = cvt_pk_bf16(o[2], o[3]); w.z = cvt_pk_bf16(o[4 % NV], o[5 % NV]); w.w = cvt_pk_bf16(o[6 % NV], o[7 % NV]);
	v_exp_f32_e32 v220, v212
	v_exp_f32_e32 v221, v213
	v_exp_f32_e32 v222, v214
	v_exp_f32_e32 v223, v215
	v_exp_f32_e32 v224, v216
	v_exp_f32_e32 v225, v217
	v_pk_fma_f32 v[218:219], v[218:219], v[202:203], v[202:203] op_sel_hi:[1,0,0]
	v_pk_fma_f32 v[220:221], v[220:221], v[202:203], v[202:203] op_sel_hi:[1,0,0]
	v_pk_fma_f32 v[222:223], v[222:223], v[202:203], v[202:203] op_sel_hi:[1,0,0]
	v_pk_fma_f32 v[224:225], v[224:225], v[202:203], v[202:203] op_sel_hi:[1,0,0]
	v_rcp_f32_e32 v218, v218
	v_rcp_f32_e32 v219, v219
	v_rcp_f32_e32 v220, v220
	v_rcp_f32_e32 v221, v221
	v_rcp_f32_e32 v222, v222
	v_rcp_f32_e32 v223, v223
	v_rcp_f32_e32 v224, v224
	v_rcp_f32_e32 v225, v225
	v_pk_mul_f32 v[210:211], v[210:211], v[218:219]
	v_pk_mul_f32 v[212:213], v[212:213], v[220:221]
	v_pk_mul_f32 v[214:215], v[214:215], v[222:223]
	v_pk_mul_f32 v[216:217], v[216:217], v[224:225]
	v_pk_mul_f32 v[156:157], v[210:211], v[156:157]
	v_pk_mul_f32 v[158:159], v[212:213], v[158:159]
	v_pk_mul_f32 v[148:149], v[214:215], v[148:149]
	v_pk_mul_f32 v[150:151], v[216:217], v[150:151]
	v_cvt_pk_bf16_f32 v226, v156, v157
	v_cvt_pk_bf16_f32 v227, v158, v159
	v_cvt_pk_bf16_f32 v228, v148, v149
	v_cvt_pk_bf16_f32 v229, v150, v151
	v_add_u32_e32 v234, 0x0, v230
	s_and_b64 exec, exec, s[8:9]
	global_store_dwordx4 v234, v[226:229], s[96:97] nt
	s_mov_b64 exec, s[24:25]
	v_pk_mul_f32 v[124:125], v[124:125], v[182:183] op_sel:[0,1]
	v_pk_mul_f32 v[126:127], v[126:127], v[182:183] op_sel:[0,1]
	v_pk_mul_f32 v[120:121], v[120:121], v[182:183] op_sel:[0,1]
	v_pk_mul_f32 v[122:123], v[122:123], v[182:183] op_sel:[0,1]
	v_pk_fma_f32 v[210:211], v[124:125], v[136:137], v[174:175]
	v_pk_fma_f32 v[212:213], v[126:127], v[138:139], v[176:177]
	v_pk_fma_f32 v[214:215], v[120:121], v[140:141], v[178:179]
	v_pk_fma_f32 v[216:217], v[122:123], v[142:143], v[180:181]
	v_fmac_f32_dpp v210, v124, v128 row_shr:1 row_mask:0xf bank_mask:0xf
	v_fmac_f32_dpp v211, v125, v129 row_shr:1 row_mask:0xf bank_mask:0xf
	v_fmac_f32_dpp v212, v126, v130 row_shr:1 row_mask:0xf bank_mask:0xf
	v_fmac_f32_dpp v213, v127, v131 row_shr:1 row_mask:0xf bank_mask:0xf
	v_fmac_f32_dpp v214, v120, v132 row_shr:1 row_mask:0xf bank_mask:0xf
	v_fmac_f32_dpp v215, v121, v133 row_shr:1 row_mask:0xf bank_mask:0xf
	v_fmac_f32_dpp v216, v122, v134 row_shr:1 row_mask:0xf bank_mask:0xf
	v_fmac_f32_dpp v217, v123, v135 row_shr:1 row_mask:0xf bank_mask:0xf
	v_fmac_f32_dpp v210, v124, v88 row_shr:2 row_mask:0xf bank_mask:0xf
	v_fmac_f32_dpp v211, v125, v89 row_shr:2 row_mask:0xf bank_mask:0xf
	v_fmac_f32_dpp v212, v126, v90 row_shr:2 row_mask:0xf bank_mask:0xf
	v_fmac_f32_dpp v213, v127, v91 row_shr:2 row_mask:0xf bank_mask:0xf
	v_fmac_f32_dpp v214, v120, v92 row_shr:2 row_mask:0xf bank_mask:0xf
	v_fmac_f32_dpp v215, v121, v93 row_shr:2 row_mask:0xf bank_mask:0xf
	v_fmac_f32_dpp v216, v122, v94 row_shr:2 row_mask:0xf bank_mask:0xf
	v_fmac_f32_dpp v217, v123, v95 row_shr:2 row_mask:0xf bank_mask:0xf
	v_fmac_f32_dpp v210, v152, v128 row_shl:15 row_mask:0xf bank_mask:0xf
	v_fmac_f32_dpp v211, v153, v129 row_shl:15 row_mask:0xf bank_mask:0xf
	v_fmac_f32_dpp v212, v154, v130 row_shl:15 row_mask:0xf bank_mask:0xf
	v_fmac_f32_dpp v213, v155, v131 row_shl:15 row_mask:0xf bank_mask:0xf
	v_fmac_f32_dpp v214, v144, v132 row_shl:15 row_mask:0xf bank_mask:0xf
	v_fmac_f32_dpp v215, v145, v133 row_shl:15 row_mask:0xf bank_mask:0xf
	v_fmac_f32_dpp v216, v146, v134 row_shl:15 row_mask:0xf bank_mask:0xf
	v_fmac_f32_dpp v217, v147, v135 row_shl:15 row_mask:0xf bank_mask:0xf
	v_fmac_f32_dpp v210, v152, v88 row_shl:14 row_mask:0xf bank_mask:0xf
	v_fmac_f32_dpp v211, v153, v89 row_shl:14 row_mask:0xf bank_mask:0xf
	v_fmac_f32_dpp v212, v154, v90 row_shl:14 row_mask:0xf bank_mask:0xf
	v_fmac_f32_dpp v213, v155, v91 row_shl:14 row_mask:0xf bank_mask:0xf
	v_fmac_f32_dpp v214, v144, v92 row_shl:14 row_mask:0xf bank_mask:0xf
	v_fmac_f32_dpp v215, v145, v93 row_shl:14 row_mask:0xf bank_mask:0xf
	v_fmac_f32_dpp v216, v146, v94 row_shl:14 row_mask:0xf bank_mask:0xf
	v_fmac_f32_dpp v217, v147, v95 row_shl:14 row_mask:0xf bank_mask:0xf
	v_exp_f32_e32 v218, v210
	v_exp_f32_e32 v219, v211
	v_exp_f32_e32 v220, v212
	v_exp_f32_e32 v221, v213
	v_exp_f32_e32 v222, v214
	v_exp_f32_e32 v223, v215
	v_exp_f32_e32 v224, v216
	v_exp_f32_e32 v225, v217
	v_pk_fma_f32 v[218:219], v[218:219], v[202:203], v[202:203] op_sel:[0,1,1]
	v_pk_fma_f32 v[220:221], v[220:221], v[202:203], v[202:203] op_sel:[0,1,1]
	v_pk_fma_f32 v[222:223], v[222:223], v[202:203], v[202:203] op_sel:[0,1,1]
	v_pk_fma_f32 v[224:225], v[224:225], v[202:203], v[202:203] op_sel:[0,1,1]
	v_rcp_f32_e32 v218, v218
	v_rcp_f32_e32 v219, v219
	v_rcp_f32_e32 v220, v220
	v_rcp_f32_e32 v221, v221
	v_rcp_f32_e32 v222, v222
	v_rcp_f32_e32 v223, v223
	v_rcp_f32_e32 v224, v224
	v_rcp_f32_e32 v225, v225
	v_pk_mul_f32 v[210:211], v[210:211], v[218:219]
	v_pk_mul_f32 v[212:213], v[212:213], v[220:221]
	v_pk_mul_f32 v[214:215], v[214:215], v[222:223]
	v_pk_mul_f32 v[216:217], v[216:217], v[224:225]
	v_pk_mul_f32 v[116:117], v[210:211], v[116:117]
	v_pk_mul_f32 v[118:119], v[212:213], v[118:119]
	v_pk_mul_f32 v[112:113], v[214:215], v[112:113]
	v_pk_mul_f32 v[114:115], v[216:217], v[114:115]
	v_cvt_pk_bf16_f32 v226, v116, v117
	v_cvt_pk_bf16_f32 v227, v118, v119
	v_cvt_pk_bf16_f32 v228, v112, v113
	v_cvt_pk_bf16_f32 v229, v114, v115
	v_add_u32_e32 v234, 0x16000, v230
	global_store_dwordx4 v234, v[226:229], s[96:97] nt
	v_pk_mul_f32 v[108:109], v[108:109], v[184:185] op_sel_hi:[1,0]
	v_pk_mul_f32 v[110:111], v[110:111], v[184:185] op_sel_hi:[1,0]
	v_pk_mul_f32 v[104:105], v[104:105], v[184:185] op_sel_hi:[1,0]
;     __device__ __forceinline__ void operator()(const Acc& acc, const Unit& u, int wr, int wc, int fr, int fq, LAS unsigned char* lds, f32x4 epar) const {
;     ...
;             for (int m = 0; m < 4; ++m) {
;                 const int r = u.pm * BM + ai * HALF + wr * 64 + m * 16 + fr;
;                 const float rs = __builtin_amdgcn_rsqf(sq[ai][m] * (1.0f / DM) + RMS_EPS);
;                 float X[NV], Y[NV], o[NV];
;                 if (MODE == 0) {
; #pragma unroll
;                     for (int n = 0; n < 2; ++n)
; #pragma unroll
;                         for (int j = 0; j < 4; ++j) { X[n * 4 + j] = acc[ai][0][m][n][j] * rs; Y[n * 4 + j] = acc[ai][1][m][n][j] * rs; }
;                 } else {
; #pragma unroll
;                     for (int j = 0; j < 4; ++j) { X[j] = (acc[ai][0][m][1][j] * rs) * (acc[ai][1][m][0][j] * rs); Y[j] = acc[ai][0][m][0][j] * rs; }
;                 }
; #pragma unroll
;                 for (int i = 0; i < NV; ++i) {
;                     const float a1 = dpp_rot<0x121>(X[i]), a2 = dpp_rot<0x122>(X[i]);
;                     const float q1 = fr >= 1 ? a1 : p1prev[i], q2 = fr >= 2 ? a2 : p2prev[i];
;                     p1prev[i] = a1; p2prev[i] = a2;
;                     const float cv = w2[i] * X[i] + w1[i] * q1 + w0[i] * q2 + bb[i];
;                     o[i] = MODE == 0 ? silu_f(cv) * Y[i] : cv * Y[i];
;                 }
;                 if (m == 0 && fr < 2) {
;                     bf16_t* hx = halo + ((size_t)strip * 6 + 2 + fr) * C + c0; bf16_t* hy = halo + ((size_t)strip * 6 + 4 + fr) * C + c0;
;                     u32x4 px, py; px.x = cvt_pk_bf16(X[0], X[1]); px.y = cvt_pk_bf16(X[2], X[3]); px.z = cvt_pk_bf16(X[4 % NV], X[5 % NV]); px.w = cvt_pk_bf16(X[6 % NV], X[7 % NV]);
;                     py.x = cvt_pk_bf16(Y[0], Y[1]); py.y = cvt_pk_bf16(Y[2], Y[3]); py.z = cvt_pk_bf16(Y[4 % NV], Y[5 % NV]); py.w = cvt_pk_bf16(Y[6 % NV], Y[7 % NV]);
;                     if (MODE == 0) { *(u32x4*)hx = px; *(u32x4*)hy = py; } else { u32x2 a; a.x = px.x; a.y = px.y; *(u32x2*)hx = a; u32x2 b; b.x = py.x; b.y = py.y; *(u32x2*)hy = b; }
;                 } else {
;                     if (MODE == 0) { u32x4 w; w.x = cvt_pk_bf16(o[0], o[1]); w.y = cvt_pk_bf16(o[2], o[3]); w.z = cvt_pk_bf16(o[4 % NV], o[5 % NV]); w.w = cvt_pk_bf16(o[6 % NV], o[7 % NV]);
	v_pk_mul_f32 v[106:107], v[106:107], v[184:185] op_sel_hi:[1,0]
	v_pk_fma_f32 v[210:211], v[108:109], v[136:137], v[174:175]
	v_pk_fma_f32 v[212:213], v[110:111], v[138:139], v[176:177]
	v_pk_fma_f32 v[214:215], v[104:105], v[140:141], v[178:179]
	v_pk_fma_f32 v[216:217], v[106:107], v[142:143], v[180:181]
	v_fmac_f32_dpp v210, v108, v128 row_shr:1 row_mask:0xf bank_mask:0xf
	v_fmac_f32_dpp v211, v109, v129 row_shr:1 row_mask:0xf bank_mask:0xf
	v_fmac_f32_dpp v212, v110, v130 row_shr:1 row_mask:0xf bank_mask:0xf
	v_fmac_f32_dpp v213, v111, v131 row_shr:1 row_mask:0xf bank_mask:0xf
	v_fmac_f32_dpp v214, v104, v132 row_shr:1 row_mask:0xf bank_mask:0xf
	v_fmac_f32_dpp v215, v105, v133 row_shr:1 row_mask:0xf bank_mask:0xf
	v_fmac_f32_dpp v216, v106, v134 row_shr:1 row_mask:0xf bank_mask:0xf
	v_fmac_f32_dpp v217, v107, v135 row_shr:1 row_mask:0xf bank_mask:0xf
	v_fmac_f32_dpp v210, v108, v88 row_shr:2 row_mask:0xf bank_mask:0xf
	v_fmac_f32_dpp v211, v109, v89 row_shr:2 row_mask:0xf bank_mask:0xf
	v_fmac_f32_dpp v212, v110, v90 row_shr:2 row_mask:0xf bank_mask:0xf
	v_fmac_f32_dpp v213, v111, v91 row_shr:2 row_mask:0xf bank_mask:0xf
	v_fmac_f32_dpp v214, v104, v92 row_shr:2 row_mask:0xf bank_mask:0xf
	v_fmac_f32_dpp v215, v105, v93 row_shr:2 row_mask:0xf bank_mask:0xf
	v_fmac_f32_dpp v216, v106, v94 row_shr:2 row_mask:0xf bank_mask:0xf
	v_fmac_f32_dpp v217, v107, v95 row_shr:2 row_mask:0xf bank_mask:0xf
	v_fmac_f32_dpp v210, v124, v128 row_shl:15 row_mask:0xf bank_mask:0xf
	v_fmac_f32_dpp v211, v125, v129 row_shl:15 row_mask:0xf bank_mask:0xf
	v_fmac_f32_dpp v212, v126, v130 row_shl:15 row_mask:0xf bank_mask:0xf
	v_fmac_f32_dpp v213, v127, v131 row_shl:15 row_mask:0xf bank_mask:0xf
	v_fmac_f32_dpp v214, v120, v132 row_shl:15 row_mask:0xf bank_mask:0xf
	v_fmac_f32_dpp v215, v121, v133 row_shl:15 row_mask:0xf bank_mask:0xf
	v_fmac_f32_dpp v216, v122, v134 row_shl:15 row_mask:0xf bank_mask:0xf
	v_fmac_f32_dpp v217, v123, v135 row_shl:15 row_mask:0xf bank_mask:0xf
	v_fmac_f32_dpp v210, v124, v88 row_shl:14 row_mask:0xf bank_mask:0xf
	v_fmac_f32_dpp v211, v125, v89 row_shl:14 row_mask:0xf bank_mask:0xf
	v_fmac_f32_dpp v212, v126, v90 row_shl:14 row_mask:0xf bank_mask:0xf
	v_fmac_f32_dpp v213, v127, v91 row_shl:14 row_mask:0xf bank_mask:0xf
	v_fmac_f32_dpp v214, v120, v92 row_shl:14 row_mask:0xf bank_mask:0xf
	v_fmac_f32_dpp v215, v121, v93 row_shl:14 row_mask:0xf bank_mask:0xf
	v_fmac_f32_dpp v216, v122, v94 row_shl:14 row_mask:0xf bank_mask:0xf
	v_fmac_f32_dpp v217, v123, v95 row_shl:14 row_mask:0xf bank_mask:0xf
	v_exp_f32_e32 v218, v210
	v_exp_f32_e32 v219, v211
	v_exp_f32_e32 v220, v212
	v_exp_f32_e32 v221, v213
	v_exp_f32_e32 v222, v214
	v_exp_f32_e32 v223, v215
	v_exp_f32_e32 v224, v216
	v_exp_f32_e32 v225, v217
	v_pk_fma_f32 v[218:219], v[218:219], v[204:205], v[204:205] op_sel_hi:[1,0,0]
	v_pk_fma_f32 v[220:221], v[220:221], v[204:205], v[204:205] op_sel_hi:[1,0,0]
	v_pk_fma_f32 v[222:223], v[222:223], v[204:205], v[204:205] op_sel_hi:[1,0,0]
	v_pk_fma_f32 v[224:225], v[224:225], v[204:205], v[204:205] op_sel_hi:[1,0,0]
	v_rcp_f32_e32 v218, v218
	v_rcp_f32_e32 v219, v219
	v_rcp_f32_e32 v220, v220
	v_rcp_f32_e32 v221, v221
	v_rcp_f32_e32 v222, v222
	v_rcp_f32_e32 v223, v223
	v_rcp_f32_e32 v224, v224
	v_rcp_f32_e32 v225, v225
	v_pk_mul_f32 v[210:211], v[210:211], v[218:219]
	v_pk_mul_f32 v[212:213], v[212:213], v[220:221]
	v_pk_mul_f32 v[214:215], v[214:215], v[222:223]
	v_pk_mul_f32 v[216:217], v[216:217], v[224:225]
	v_pk_mul_f32 v[100:101], v[210:211], v[100:101]
	v_pk_mul_f32 v[102:103], v[212:213], v[102:103]
	v_pk_mul_f32 v[96:97], v[214:215], v[96:97]
	v_pk_mul_f32 v[98:99], v[216:217], v[98:99]
	v_cvt_pk_bf16_f32 v226, v100, v101
	v_cvt_pk_bf16_f32 v227, v102, v103
	v_cvt_pk_bf16_f32 v228, v96, v97
	v_cvt_pk_bf16_f32 v229, v98, v99
	v_add_u32_e32 v234, 0x2c000, v230
	global_store_dwordx4 v234, v[226:229], s[96:97] nt
	v_pk_mul_f32 v[84:85], v[84:85], v[184:185] op_sel:[0,1]
	v_pk_mul_f32 v[86:87], v[86:87], v[184:185] op_sel:[0,1]
	v_pk_mul_f32 v[80:81], v[80:81], v[184:185] op_sel:[0,1]
	v_pk_mul_f32 v[82:83], v[82:83], v[184:185] op_sel:[0,1]
	v_pk_fma_f32 v[210:211], v[84:85], v[136:137], v[174:175]
	v_pk_fma_f32 v[212:213], v[86:87], v[138:139], v[176:177]
	v_pk_fma_f32 v[214:215], v[80:81], v[140:141], v[178:179]
	v_pk_fma_f32 v[216:217], v[82:83], v[142:143], v[180:181]
	v_cvt_pk_bf16_f32 v236, v84, v85
	v_cvt_pk_bf16_f32 v237, v86, v87
	v_cvt_pk_bf16_f32 v238, v80, v81
	v_cvt_pk_bf16_f32 v239, v82, v83
	v_add_u32_e32 v235, 0xfffecc00, v233
	s_and_b64 exec, exec, s[10:11]
	global_store_dwordx4 v235, v[236:239], s[42:43]
	s_mov_b64 exec, s[24:25]
	v_fmac_f32_dpp v210, v84, v128 row_shr:1 row_mask:0xf bank_mask:0xf
	v_fmac_f32_dpp v211, v85, v129 row_shr:1 row_mask:0xf bank_mask:0xf
	v_fmac_f32_dpp v212, v86, v130 row_shr:1 row_mask:0xf bank_mask:0xf
	v_fmac_f32_dpp v213, v87, v131 row_shr:1 row_mask:0xf bank_mask:0xf
	v_fmac_f32_dpp v214, v80, v132 row_shr:1 row_mask:0xf bank_mask:0xf
	v_fmac_f32_dpp v215, v81, v133 row_shr:1 row_mask:0xf bank_mask:0xf
	v_fmac_f32_dpp v216, v82, v134 row_shr:1 row_mask:0xf bank_mask:0xf
	v_fmac_f32_dpp v217, v83, v135 row_shr:1 row_mask:0xf bank_mask:0xf
	v_fmac_f32_dpp v210, v84, v88 row_shr:2 row_mask:0xf bank_mask:0xf
	v_fmac_f32_dpp v211, v85, v89 row_shr:2 row_mask:0xf bank_mask:0xf
	v_fmac_f32_dpp v212, v86, v90 row_shr:2 row_mask:0xf bank_mask:0xf
	v_fmac_f32_dpp v213, v87, v91 row_shr:2 row_mask:0xf bank_mask:0xf
	v_fmac_f32_dpp v214, v80, v92 row_shr:2 row_mask:0xf bank_mask:0xf
	v_fmac_f32_dpp v215, v81, v93 row_shr:2 row_mask:0xf bank_mask:0xf
	v_fmac_f32_dpp v216, v82, v94 row_shr:2 row_mask:0xf bank_mask:0xf
;     __device__ __forceinline__ void operator()(const Acc& acc, const Unit& u, int wr, int wc, int fr, int fq, LAS unsigned char* lds, f32x4 epar) const {
;     ...
;             for (int m = 0; m < 4; ++m) {
;                 const int r = u.pm * BM + ai * HALF + wr * 64 + m * 16 + fr;
;                 const float rs = __builtin_amdgcn_rsqf(sq[ai][m] * (1.0f / DM) + RMS_EPS);
;                 float X[NV], Y[NV], o[NV];
;                 if (MODE == 0) {
; #pragma unroll
;                     for (int n = 0; n < 2; ++n)
; #pragma unroll
;                         for (int j = 0; j < 4; ++j) { X[n * 4 + j] = acc[ai][0][m][n][j] * rs; Y[n * 4 + j] = acc[ai][1][m][n][j] * rs; }
;                 } else {
; #pragma unroll
;                     for (int j = 0; j < 4; ++j) { X[j] = (acc[ai][0][m][1][j] * rs) * (acc[ai][1][m][0][j] * rs); Y[j] = acc[ai][0][m][0][j] * rs; }
;                 }
; #pragma unroll
;                 for (int i = 0; i < NV; ++i) {
;                     const float a1 = dpp_rot<0x121>(X[i]), a2 = dpp_rot<0x122>(X[i]);
;                     const float q1 = fr >= 1 ? a1 : p1prev[i], q2 = fr >= 2 ? a2 : p2prev[i];
;                     p1prev[i] = a1; p2prev[i] = a2;
;                     const float cv = w2[i] * X[i] + w1[i] * q1 + w0[i] * q2 + bb[i];
;                     o[i] = MODE == 0 ? silu_f(cv) * Y[i] : cv * Y[i];
;                 }
;                 if (m == 0 && fr < 2) {
;                     bf16_t* hx = halo + ((size_t)strip * 6 + 2 + fr) * C + c0; bf16_t* hy = halo + ((size_t)strip * 6 + 4 + fr) * C + c0;
;                     u32x4 px, py; px.x = cvt_pk_bf16(X[0], X[1]); px.y = cvt_pk_bf16(X[2], X[3]); px.z = cvt_pk_bf16(X[4 % NV], X[5 % NV]); px.w = cvt_pk_bf16(X[6 % NV], X[7 % NV]);
;                     py.x = cvt_pk_bf16(Y[0], Y[1]); py.y = cvt_pk_bf16(Y[2], Y[3]); py.z = cvt_pk_bf16(Y[4 % NV], Y[5 % NV]); py.w = cvt_pk_bf16(Y[6 % NV], Y[7 % NV]);
;                     if (MODE == 0) { *(u32x4*)hx = px; *(u32x4*)hy = py; } else { u32x2 a; a.x = px.x; a.y = px.y; *(u32x2*)hx = a; u32x2 b; b.x = py.x; b.y = py.y; *(u32x2*)hy = b; }
;                 } else {
;                     if (MODE == 0) { u32x4 w; w.x = cvt_pk_bf16(o[0], o[1]); w.y = cvt_pk_bf16(o[2], o[3]); w.z = cvt_pk_bf16(o[4 % NV], o[5 % NV]); w.w = cvt_pk_bf16(o[6 % NV], o[7 % NV]);
	v_fmac_f32_dpp v217, v83, v95 row_shr:2 row_mask:0xf bank_mask:0xf
	v_fmac_f32_dpp v210, v108, v128 row_shl:15 row_mask:0xf bank_mask:0xf
	v_fmac_f32_dpp v211, v109, v129 row_shl:15 row_mask:0xf bank_mask:0xf
	v_fmac_f32_dpp v212, v110, v130 row_shl:15 row_mask:0xf bank_mask:0xf
	v_fmac_f32_dpp v213, v111, v131 row_shl:15 row_mask:0xf bank_mask:0xf
	v_fmac_f32_dpp v214, v104, v132 row_shl:15 row_mask:0xf bank_mask:0xf
	v_fmac_f32_dpp v215, v105, v133 row_shl:15 row_mask:0xf bank_mask:0xf
	v_fmac_f32_dpp v216, v106, v134 row_shl:15 row_mask:0xf bank_mask:0xf
	v_fmac_f32_dpp v217, v107, v135 row_shl:15 row_mask:0xf bank_mask:0xf
	v_fmac_f32_dpp v210, v108, v88 row_shl:14 row_mask:0xf bank_mask:0xf
	v_fmac_f32_dpp v211, v109, v89 row_shl:14 row_mask:0xf bank_mask:0xf
	v_fmac_f32_dpp v212, v110, v90 row_shl:14 row_mask:0xf bank_mask:0xf
	v_fmac_f32_dpp v213, v111, v91 row_shl:14 row_mask:0xf bank_mask:0xf
	v_fmac_f32_dpp v214, v104, v92 row_shl:14 row_mask:0xf bank_mask:0xf
	v_fmac_f32_dpp v215, v105, v93 row_shl:14 row_mask:0xf bank_mask:0xf
	v_fmac_f32_dpp v216, v106, v94 row_shl:14 row_mask:0xf bank_mask:0xf
	v_fmac_f32_dpp v217, v107, v95 row_shl:14 row_mask:0xf bank_mask:0xf
	v_exp_f32_e32 v218, v210
	v_exp_f32_e32 v219, v211
	v_exp_f32_e32 v220, v212
	v_exp_f32_e32 v221, v213
	v_exp_f32_e32 v222, v214
	v_exp_f32_e32 v223, v215
	v_exp_f32_e32 v224, v216
	v_exp_f32_e32 v225, v217
	v_pk_fma_f32 v[218:219], v[218:219], v[204:205], v[204:205] op_sel:[0,1,1]
	v_pk_fma_f32 v[220:221], v[220:221], v[204:205], v[204:205] op_sel:[0,1,1]
	v_pk_fma_f32 v[222:223], v[222:223], v[204:205], v[204:205] op_sel:[0,1,1]
	v_pk_fma_f32 v[224:225], v[224:225], v[204:205], v[204:205] op_sel:[0,1,1]
	v_rcp_f32_e32 v218, v218
	v_rcp_f32_e32 v219, v219
	v_rcp_f32_e32 v220, v220
	v_rcp_f32_e32 v221, v221
	v_rcp_f32_e32 v222, v222
	v_rcp_f32_e32 v223, v223
	v_rcp_f32_e32 v224, v224
	v_rcp_f32_e32 v225, v225
	v_pk_mul_f32 v[210:211], v[210:211], v[218:219]
	v_pk_mul_f32 v[212:213], v[212:213], v[220:221]
	v_pk_mul_f32 v[214:215], v[214:215], v[222:223]
	v_pk_mul_f32 v[216:217], v[216:217], v[224:225]
	v_pk_mul_f32 v[68:69], v[210:211], v[68:69]
	v_pk_mul_f32 v[70:71], v[212:213], v[70:71]
	v_pk_mul_f32 v[64:65], v[214:215], v[64:65]
	v_pk_mul_f32 v[66:67], v[216:217], v[66:67]
	v_cvt_pk_bf16_f32 v226, v68, v69
	v_cvt_pk_bf16_f32 v227, v70, v71
	v_cvt_pk_bf16_f32 v228, v64, v65
	v_cvt_pk_bf16_f32 v229, v66, v67
	v_add_u32_e32 v234, 0x42000, v230
	global_store_dwordx4 v234, v[226:229], s[96:97] nt
	v_pk_mul_f32 v[60:61], v[60:61], v[76:77] op_sel_hi:[1,0]
	v_pk_mul_f32 v[62:63], v[62:63], v[76:77] op_sel_hi:[1,0]
	v_pk_mul_f32 v[52:53], v[52:53], v[76:77] op_sel_hi:[1,0]
	v_pk_mul_f32 v[54:55], v[54:55], v[76:77] op_sel_hi:[1,0]
	v_pk_fma_f32 v[210:211], v[60:61], v[136:137], v[174:175]
	v_pk_fma_f32 v[212:213], v[62:63], v[138:139], v[176:177]
	v_pk_fma_f32 v[214:215], v[52:53], v[140:141], v[178:179]
	v_pk_fma_f32 v[216:217], v[54:55], v[142:143], v[180:181]
	v_pk_mul_f32 v[218:219], v[56:57], v[76:77] op_sel_hi:[1,0]
	v_pk_mul_f32 v[220:221], v[58:59], v[76:77] op_sel_hi:[1,0]
	v_pk_mul_f32 v[222:223], v[48:49], v[76:77] op_sel_hi:[1,0]
	v_pk_mul_f32 v[224:225], v[50:51], v[76:77] op_sel_hi:[1,0]
	v_cvt_pk_bf16_f32 v236, v60, v61
	v_cvt_pk_bf16_f32 v237, v62, v63
	v_cvt_pk_bf16_f32 v238, v52, v53
	v_cvt_pk_bf16_f32 v239, v54, v55
	v_cvt_pk_bf16_f32 v240, v218, v219
	v_cvt_pk_bf16_f32 v241, v220, v221
	v_cvt_pk_bf16_f32 v242, v222, v223
	v_cvt_pk_bf16_f32 v243, v224, v225
	v_add_u32_e32 v234, 0x13400, v233
	v_add_u32_e32 v235, 0x16000, v233
	s_andn2_b64 exec, exec, s[8:9]
	global_store_dwordx4 v234, v[236:239], s[42:43]
	global_store_dwordx4 v235, v[240:243], s[42:43]
	s_mov_b64 exec, s[24:25]
	v_fmac_f32_dpp v210, v60, v128 row_shr:1 row_mask:0xf bank_mask:0xf
	v_fmac_f32_dpp v211, v61, v129 row_shr:1 row_mask:0xf bank_mask:0xf
	v_fmac_f32_dpp v212, v62, v130 row_shr:1 row_mask:0xf bank_mask:0xf
	v_fmac_f32_dpp v213, v63, v131 row_shr:1 row_mask:0xf bank_mask:0xf
	v_fmac_f32_dpp v214, v52, v132 row_shr:1 row_mask:0xf bank_mask:0xf
	v_fmac_f32_dpp v215, v53, v133 row_shr:1 row_mask:0xf bank_mask:0xf
	v_fmac_f32_dpp v216, v54, v134 row_shr:1 row_mask:0xf bank_mask:0xf
	v_fmac_f32_dpp v217, v55, v135 row_shr:1 row_mask:0xf bank_mask:0xf
	v_fmac_f32_dpp v210, v60, v88 row_shr:2 row_mask:0xf bank_mask:0xf
	v_fmac_f32_dpp v211, v61, v89 row_shr:2 row_mask:0xf bank_mask:0xf
	v_fmac_f32_dpp v212, v62, v90 row_shr:2 row_mask:0xf bank_mask:0xf
	v_fmac_f32_dpp v213, v63, v91 row_shr:2 row_mask:0xf bank_mask:0xf
	v_fmac_f32_dpp v214, v52, v92 row_shr:2 row_mask:0xf bank_mask:0xf
	v_fmac_f32_dpp v215, v53, v93 row_shr:2 row_mask:0xf bank_mask:0xf
	v_fmac_f32_dpp v216, v54, v94 row_shr:2 row_mask:0xf bank_mask:0xf
	v_fmac_f32_dpp v217, v55, v95 row_shr:2 row_mask:0xf bank_mask:0xf
	v_exp_f32_e32 v218, v210
	v_exp_f32_e32 v219, v211
	v_exp_f32_e32 v220, v212
	v_exp_f32_e32 v221, v213
	v_exp_f32_e32 v222, v214
	v_exp_f32_e32 v223, v215
	v_exp_f32_e32 v224, v216
	v_exp_f32_e32 v225, v217
	v_pk_fma_f32 v[218:219], v[218:219], v[206:207], v[206:207] op_sel_hi:[1,0,0]
	v_pk_fma_f32 v[220:221], v[220:221], v[206:207], v[206:207] op_sel_hi:[1,0,0]
	v_pk_fma_f32 v[222:223], v[222:223], v[206:207], v[206:207] op_sel_hi:[1,0,0]
	v_pk_fma_f32 v[224:225], v[224:225], v[206:207], v[206:207] op_sel_hi:[1,0,0]
	v_rcp_f32_e32 v218, v218
	v_rcp_f32_e32 v219, v219
	v_rcp_f32_e32 v220, v220
	v_rcp_f32_e32 v221, v221
	v_rcp_f32_e32 v222, v222
	v_rcp_f32_e32 v223, v223
	v_rcp_f32_e32 v224, v224
	v_rcp_f32_e32 v225, v225
	v_pk_mul_f32 v[210:211], v[210:211], v[218:219]
	v_pk_mul_f32 v[212:213], v[212:213], v[220:221]
;     __device__ __forceinline__ void operator()(const Acc& acc, const Unit& u, int wr, int wc, int fr, int fq, LAS unsigned char* lds, f32x4 epar) const {
;     ...
;             for (int m = 0; m < 4; ++m) {
;                 const int r = u.pm * BM + ai * HALF + wr * 64 + m * 16 + fr;
;                 const float rs = __builtin_amdgcn_rsqf(sq[ai][m] * (1.0f / DM) + RMS_EPS);
;                 float X[NV], Y[NV], o[NV];
;                 if (MODE == 0) {
; #pragma unroll
;                     for (int n = 0; n < 2; ++n)
; #pragma unroll
;                         for (int j = 0; j < 4; ++j) { X[n * 4 + j] = acc[ai][0][m][n][j] * rs; Y[n * 4 + j] = acc[ai][1][m][n][j] * rs; }
;                 } else {
; #pragma unroll
;                     for (int j = 0; j < 4; ++j) { X[j] = (acc[ai][0][m][1][j] * rs) * (acc[ai][1][m][0][j] * rs); Y[j] = acc[ai][0][m][0][j] * rs; }
;                 }
; #pragma unroll
;                 for (int i = 0; i < NV; ++i) {
;                     const float a1 = dpp_rot<0x121>(X[i]), a2 = dpp_rot<0x122>(X[i]);
;                     const float q1 = fr >= 1 ? a1 : p1prev[i], q2 = fr >= 2 ? a2 : p2prev[i];
;                     p1prev[i] = a1; p2prev[i] = a2;
;                     const float cv = w2[i] * X[i] + w1[i] * q1 + w0[i] * q2 + bb[i];
;                     o[i] = MODE == 0 ? silu_f(cv) * Y[i] : cv * Y[i];
;                 }
;                 if (m == 0 && fr < 2) {
;                     bf16_t* hx = halo + ((size_t)strip * 6 + 2 + fr) * C + c0; bf16_t* hy = halo + ((size_t)strip * 6 + 4 + fr) * C + c0;
;                     u32x4 px, py; px.x = cvt_pk_bf16(X[0], X[1]); px.y = cvt_pk_bf16(X[2], X[3]); px.z = cvt_pk_bf16(X[4 % NV], X[5 % NV]); px.w = cvt_pk_bf16(X[6 % NV], X[7 % NV]);
;                     py.x = cvt_pk_bf16(Y[0], Y[1]); py.y = cvt_pk_bf16(Y[2], Y[3]); py.z = cvt_pk_bf16(Y[4 % NV], Y[5 % NV]); py.w = cvt_pk_bf16(Y[6 % NV], Y[7 % NV]);
;                     if (MODE == 0) { *(u32x4*)hx = px; *(u32x4*)hy = py; } else { u32x2 a; a.x = px.x; a.y = px.y; *(u32x2*)hx = a; u32x2 b; b.x = py.x; b.y = py.y; *(u32x2*)hy = b; }
;                 } else {
;                     if (MODE == 0) { u32x4 w; w.x = cvt_pk_bf16(o[0], o[1]); w.y = cvt_pk_bf16(o[2], o[3]); w.z = cvt_pk_bf16(o[4 % NV], o[5 % NV]); w.w = cvt_pk_bf16(o[6 % NV], o[7 % NV]);
	v_pk_mul_f32 v[214:215], v[214:215], v[222:223]
	v_pk_mul_f32 v[216:217], v[216:217], v[224:225]
	v_pk_mul_f32 v[56:57], v[210:211], v[56:57]
	v_pk_mul_f32 v[58:59], v[212:213], v[58:59]
	v_pk_mul_f32 v[48:49], v[214:215], v[48:49]
	v_pk_mul_f32 v[50:51], v[216:217], v[50:51]
	v_cvt_pk_bf16_f32 v226, v56, v57
	v_cvt_pk_bf16_f32 v227, v58, v59
	v_cvt_pk_bf16_f32 v228, v48, v49
	v_cvt_pk_bf16_f32 v229, v50, v51
	v_add_u32_e32 v234, 0xb0000, v230
	s_and_b64 exec, exec, s[8:9]
	global_store_dwordx4 v234, v[226:229], s[96:97] nt
	s_mov_b64 exec, s[24:25]
	v_pk_mul_f32 v[44:45], v[44:45], v[76:77] op_sel:[0,1]
	v_pk_mul_f32 v[46:47], v[46:47], v[76:77] op_sel:[0,1]
	v_pk_mul_f32 v[40:41], v[40:41], v[76:77] op_sel:[0,1]
	v_pk_mul_f32 v[42:43], v[42:43], v[76:77] op_sel:[0,1]
	v_pk_fma_f32 v[210:211], v[44:45], v[136:137], v[174:175]
	v_pk_fma_f32 v[212:213], v[46:47], v[138:139], v[176:177]
	v_pk_fma_f32 v[214:215], v[40:41], v[140:141], v[178:179]
	v_pk_fma_f32 v[216:217], v[42:43], v[142:143], v[180:181]
	v_fmac_f32_dpp v210, v44, v128 row_shr:1 row_mask:0xf bank_mask:0xf
	v_fmac_f32_dpp v211, v45, v129 row_shr:1 row_mask:0xf bank_mask:0xf
	v_fmac_f32_dpp v212, v46, v130 row_shr:1 row_mask:0xf bank_mask:0xf
	v_fmac_f32_dpp v213, v47, v131 row_shr:1 row_mask:0xf bank_mask:0xf
	v_fmac_f32_dpp v214, v40, v132 row_shr:1 row_mask:0xf bank_mask:0xf
	v_fmac_f32_dpp v215, v41, v133 row_shr:1 row_mask:0xf bank_mask:0xf
	v_fmac_f32_dpp v216, v42, v134 row_shr:1 row_mask:0xf bank_mask:0xf
	v_fmac_f32_dpp v217, v43, v135 row_shr:1 row_mask:0xf bank_mask:0xf
	v_fmac_f32_dpp v210, v44, v88 row_shr:2 row_mask:0xf bank_mask:0xf
	v_fmac_f32_dpp v211, v45, v89 row_shr:2 row_mask:0xf bank_mask:0xf
	v_fmac_f32_dpp v212, v46, v90 row_shr:2 row_mask:0xf bank_mask:0xf
	v_fmac_f32_dpp v213, v47, v91 row_shr:2 row_mask:0xf bank_mask:0xf
	v_fmac_f32_dpp v214, v40, v92 row_shr:2 row_mask:0xf bank_mask:0xf
	v_fmac_f32_dpp v215, v41, v93 row_shr:2 row_mask:0xf bank_mask:0xf
	v_fmac_f32_dpp v216, v42, v94 row_shr:2 row_mask:0xf bank_mask:0xf
	v_fmac_f32_dpp v217, v43, v95 row_shr:2 row_mask:0xf bank_mask:0xf
	v_fmac_f32_dpp v210, v60, v128 row_shl:15 row_mask:0xf bank_mask:0xf
	v_fmac_f32_dpp v211, v61, v129 row_shl:15 row_mask:0xf bank_mask:0xf
	v_fmac_f32_dpp v212, v62, v130 row_shl:15 row_mask:0xf bank_mask:0xf
	v_fmac_f32_dpp v213, v63, v131 row_shl:15 row_mask:0xf bank_mask:0xf
	v_fmac_f32_dpp v214, v52, v132 row_shl:15 row_mask:0xf bank_mask:0xf
	v_fmac_f32_dpp v215, v53, v133 row_shl:15 row_mask:0xf bank_mask:0xf
	v_fmac_f32_dpp v216, v54, v134 row_shl:15 row_mask:0xf bank_mask:0xf
	v_fmac_f32_dpp v217, v55, v135 row_shl:15 row_mask:0xf bank_mask:0xf
	v_fmac_f32_dpp v210, v60, v88 row_shl:14 row_mask:0xf bank_mask:0xf
	v_fmac_f32_dpp v211, v61, v89 row_shl:14 row_mask:0xf bank_mask:0xf
	v_fmac_f32_dpp v212, v62, v90 row_shl:14 row_mask:0xf bank_mask:0xf
	v_fmac_f32_dpp v213, v63, v91 row_shl:14 row_mask:0xf bank_mask:0xf
	v_fmac_f32_dpp v214, v52, v92 row_shl:14 row_mask:0xf bank_mask:0xf
	v_fmac_f32_dpp v215, v53, v93 row_shl:14 row_mask:0xf bank_mask:0xf
	v_fmac_f32_dpp v216, v54, v94 row_shl:14 row_mask:0xf bank_mask:0xf
	v_fmac_f32_dpp v217, v55, v95 row_shl:14 row_mask:0xf bank_mask:0xf
	v_exp_f32_e32 v218, v210
	v_exp_f32_e32 v219, v211
	v_exp_f32_e32 v220, v212
	v_exp_f32_e32 v221, v213
	v_exp_f32_e32 v222, v214
	v_exp_f32_e32 v223, v215
	v_exp_f32_e32 v224, v216
	v_exp_f32_e32 v225, v217
	v_pk_fma_f32 v[218:219], v[218:219], v[206:207], v[206:207] op_sel:[0,1,1]
	v_pk_fma_f32 v[220:221], v[220:221], v[206:207], v[206:207] op_sel:[0,1,1]
	v_pk_fma_f32 v[222:223], v[222:223], v[206:207], v[206:207] op_sel:[0,1,1]
	v_pk_fma_f32 v[224:225], v[224:225], v[206:207], v[206:207] op_sel:[0,1,1]
	v_rcp_f32_e32 v218, v218
	v_rcp_f32_e32 v219, v219
	v_rcp_f32_e32 v220, v220
	v_rcp_f32_e32 v221, v221
	v_rcp_f32_e32 v222, v222
	v_rcp_f32_e32 v223, v223
	v_rcp_f32_e32 v224, v224
	v_rcp_f32_e32 v225, v225
	v_pk_mul_f32 v[210:211], v[210:211], v[218:219]
	v_pk_mul_f32 v[212:213], v[212:213], v[220:221]
	v_pk_mul_f32 v[214:215], v[214:215], v[222:223]
	v_pk_mul_f32 v[216:217], v[216:217], v[224:225]
	v_pk_mul_f32 v[36:37], v[210:211], v[36:37]
	v_pk_mul_f32 v[38:39], v[212:213], v[38:39]
	v_pk_mul_f32 v[32:33], v[214:215], v[32:33]
	v_pk_mul_f32 v[34:35], v[216:217], v[34:35]
	v_cvt_pk_bf16_f32 v226, v36, v37
	v_cvt_pk_bf16_f32 v227, v38, v39
	v_cvt_pk_bf16_f32 v228, v32, v33
	v_cvt_pk_bf16_f32 v229, v34, v35
	v_add_u32_e32 v234, 0xc6000, v230
	global_store_dwordx4 v234, v[226:229], s[96:97] nt
	v_pk_mul_f32 v[28:29], v[28:29], v[78:79] op_sel_hi:[1,0]
	v_pk_mul_f32 v[30:31], v[30:31], v[78:79] op_sel_hi:[1,0]
	v_pk_mul_f32 v[24:25], v[24:25], v[78:79] op_sel_hi:[1,0]
	v_pk_mul_f32 v[26:27], v[26:27], v[78:79] op_sel_hi:[1,0]
	v_pk_fma_f32 v[210:211], v[28:29], v[136:137], v[174:175]
	v_pk_fma_f32 v[212:213], v[30:31], v[138:139], v[176:177]
	v_pk_fma_f32 v[214:215], v[24:25], v[140:141], v[178:179]
	v_pk_fma_f32 v[216:217], v[26:27], v[142:143], v[180:181]
	v_fmac_f32_dpp v210, v28, v128 row_shr:1 row_mask:0xf bank_mask:0xf
	v_fmac_f32_dpp v211, v29, v129 row_shr:1 row_mask:0xf bank_mask:0xf
	v_fmac_f32_dpp v212, v30, v130 row_shr:1 row_mask:0xf bank_mask:0xf
	v_fmac_f32_dpp v213, v31, v131 row_shr:1 row_mask:0xf bank_mask:0xf
	v_fmac_f32_dpp v214, v24, v132 row_shr:1 row_mask:0xf bank_mask:0xf
	v_fmac_f32_dpp v215, v25, v133 row_shr:1 row_mask:0xf bank_mask:0xf
	v_fmac_f32_dpp v216, v26, v134 row_shr:1 row_mask:0xf bank_mask:0xf
	v_fmac_f32_dpp v217, v27, v135 row_shr:1 row_mask:0xf bank_mask:0xf
	v_fmac_f32_dpp v210, v28, v88 row_shr:2 row_mask:0xf bank_mask:0xf
; __device__ __forceinline__ unsigned cvt_pk_bf16(float lo, float hi) { unsigned r; asm volatile("v_cvt_pk_bf16_f32 %0, %1, %2" : "=v"(r) : "v"(lo), "v"(hi)); return r; }
; __device__ __forceinline__ float silu_f(float x) { return x * __builtin_amdgcn_rcpf(1.0f + __builtin_amdgcn_exp2f(x * -1.44269504f)); }
; template <int CTRL> __device__ __forceinline__ float dpp_rot(float x) { return __int_as_float(__builtin_amdgcn_mov_dpp(__float_as_int(x), CTRL, 0xf, 0xf, false)); }
;     __device__ __forceinline__ void operator()(const Acc& acc, const Unit& u, int wr, int wc, int fr, int fq, LAS unsigned char* lds, f32x4 epar) const {
;     ...
; #pragma unroll
;                 for (int i = 0; i < NV; ++i) {
;                     const float a1 = dpp_rot<0x121>(X[i]), a2 = dpp_rot<0x122>(X[i]);
;                     const float q1 = fr >= 1 ? a1 : p1prev[i], q2 = fr >= 2 ? a2 : p2prev[i];
;                     p1prev[i] = a1; p2prev[i] = a2;
;                     const float cv = w2[i] * X[i] + w1[i] * q1 + w0[i] * q2 + bb[i];
;                     o[i] = MODE == 0 ? silu_f(cv) * Y[i] : cv * Y[i];
;                 }
;                 if (m == 0 && fr < 2) {
;                     bf16_t* hx = halo + ((size_t)strip * 6 + 2 + fr) * C + c0; bf16_t* hy = halo + ((size_t)strip * 6 + 4 + fr) * C + c0;
;                     u32x4 px, py; px.x = cvt_pk_bf16(X[0], X[1]); px.y = cvt_pk_bf16(X[2], X[3]); px.z = cvt_pk_bf16(X[4 % NV], X[5 % NV]); px.w = cvt_pk_bf16(X[6 % NV], X[7 % NV]);
;                     py.x = cvt_pk_bf16(Y[0], Y[1]); py.y = cvt_pk_bf16(Y[2], Y[3]); py.z = cvt_pk_bf16(Y[4 % NV], Y[5 % NV]); py.w = cvt_pk_bf16(Y[6 % NV], Y[7 % NV]);
;                     if (MODE == 0) { *(u32x4*)hx = px; *(u32x4*)hy = py; } else { u32x2 a; a.x = px.x; a.y = px.y; *(u32x2*)hx = a; u32x2 b; b.x = py.x; b.y = py.y; *(u32x2*)hy = b; }
;                 } else {
;                     if (MODE == 0) { u32x4 w; w.x = cvt_pk_bf16(o[0], o[1]); w.y = cvt_pk_bf16(o[2], o[3]); w.z = cvt_pk_bf16(o[4 % NV], o[5 % NV]); w.w = cvt_pk_bf16(o[6 % NV], o[7 % NV]);
;                         __builtin_nontemporal_store(w, (u32x4*)(out + (size_t)r * C + c0)); }
;                     else { u32x2 w; w.x = cvt_pk_bf16(o[0], o[1]); w.y = cvt_pk_bf16(o[2], o[3]); __builtin_nontemporal_store(w, (u32x2*)(out + (size_t)r * C + c0)); }
;                 }
	v_fmac_f32_dpp v211, v29, v89 row_shr:2 row_mask:0xf bank_mask:0xf
	v_fmac_f32_dpp v212, v30, v90 row_shr:2 row_mask:0xf bank_mask:0xf
	v_fmac_f32_dpp v213, v31, v91 row_shr:2 row_mask:0xf bank_mask:0xf
	v_fmac_f32_dpp v214, v24, v92 row_shr:2 row_mask:0xf bank_mask:0xf
	v_fmac_f32_dpp v215, v25, v93 row_shr:2 row_mask:0xf bank_mask:0xf
	v_fmac_f32_dpp v216, v26, v94 row_shr:2 row_mask:0xf bank_mask:0xf
	v_fmac_f32_dpp v217, v27, v95 row_shr:2 row_mask:0xf bank_mask:0xf
	v_fmac_f32_dpp v210, v44, v128 row_shl:15 row_mask:0xf bank_mask:0xf
	v_fmac_f32_dpp v211, v45, v129 row_shl:15 row_mask:0xf bank_mask:0xf
	v_fmac_f32_dpp v212, v46, v130 row_shl:15 row_mask:0xf bank_mask:0xf
	v_fmac_f32_dpp v213, v47, v131 row_shl:15 row_mask:0xf bank_mask:0xf
	v_fmac_f32_dpp v214, v40, v132 row_shl:15 row_mask:0xf bank_mask:0xf
	v_fmac_f32_dpp v215, v41, v133 row_shl:15 row_mask:0xf bank_mask:0xf
	v_fmac_f32_dpp v216, v42, v134 row_shl:15 row_mask:0xf bank_mask:0xf
	v_fmac_f32_dpp v217, v43, v135 row_shl:15 row_mask:0xf bank_mask:0xf
	v_fmac_f32_dpp v210, v44, v88 row_shl:14 row_mask:0xf bank_mask:0xf
	v_fmac_f32_dpp v211, v45, v89 row_shl:14 row_mask:0xf bank_mask:0xf
	v_fmac_f32_dpp v212, v46, v90 row_shl:14 row_mask:0xf bank_mask:0xf
	v_fmac_f32_dpp v213, v47, v91 row_shl:14 row_mask:0xf bank_mask:0xf
	v_fmac_f32_dpp v214, v40, v92 row_shl:14 row_mask:0xf bank_mask:0xf
	v_fmac_f32_dpp v215, v41, v93 row_shl:14 row_mask:0xf bank_mask:0xf
	v_fmac_f32_dpp v216, v42, v94 row_shl:14 row_mask:0xf bank_mask:0xf
	v_fmac_f32_dpp v217, v43, v95 row_shl:14 row_mask:0xf bank_mask:0xf
	v_exp_f32_e32 v218, v210
	v_exp_f32_e32 v219, v211
	v_exp_f32_e32 v220, v212
	v_exp_f32_e32 v221, v213
	v_exp_f32_e32 v222, v214
	v_exp_f32_e32 v223, v215
	v_exp_f32_e32 v224, v216
	v_exp_f32_e32 v225, v217
	v_pk_fma_f32 v[218:219], v[218:219], v[208:209], v[208:209] op_sel_hi:[1,0,0]
	v_pk_fma_f32 v[220:221], v[220:221], v[208:209], v[208:209] op_sel_hi:[1,0,0]
	v_pk_fma_f32 v[222:223], v[222:223], v[208:209], v[208:209] op_sel_hi:[1,0,0]
	v_pk_fma_f32 v[224:225], v[224:225], v[208:209], v[208:209] op_sel_hi:[1,0,0]
	v_rcp_f32_e32 v218, v218
	v_rcp_f32_e32 v219, v219
	v_rcp_f32_e32 v220, v220
	v_rcp_f32_e32 v221, v221
	v_rcp_f32_e32 v222, v222
	v_rcp_f32_e32 v223, v223
	v_rcp_f32_e32 v224, v224
	v_rcp_f32_e32 v225, v225
	v_pk_mul_f32 v[210:211], v[210:211], v[218:219]
	v_pk_mul_f32 v[212:213], v[212:213], v[220:221]
	v_pk_mul_f32 v[214:215], v[214:215], v[222:223]
	v_pk_mul_f32 v[216:217], v[216:217], v[224:225]
	v_pk_mul_f32 v[20:21], v[210:211], v[20:21]
	v_pk_mul_f32 v[22:23], v[212:213], v[22:23]
	v_pk_mul_f32 v[16:17], v[214:215], v[16:17]
	v_pk_mul_f32 v[18:19], v[216:217], v[18:19]
	v_cvt_pk_bf16_f32 v226, v20, v21
	v_cvt_pk_bf16_f32 v227, v22, v23
	v_cvt_pk_bf16_f32 v228, v16, v17
	v_cvt_pk_bf16_f32 v229, v18, v19
	v_add_u32_e32 v234, 0xdc000, v230
	global_store_dwordx4 v234, v[226:229], s[96:97] nt
	v_pk_mul_f32 v[12:13], v[12:13], v[78:79] op_sel:[0,1]
	v_pk_mul_f32 v[14:15], v[14:15], v[78:79] op_sel:[0,1]
	v_pk_mul_f32 v[8:9], v[8:9], v[78:79] op_sel:[0,1]
	v_pk_mul_f32 v[10:11], v[10:11], v[78:79] op_sel:[0,1]
	v_pk_fma_f32 v[210:211], v[12:13], v[136:137], v[174:175]
	v_pk_fma_f32 v[212:213], v[14:15], v[138:139], v[176:177]
	v_pk_fma_f32 v[214:215], v[8:9], v[140:141], v[178:179]
	v_pk_fma_f32 v[216:217], v[10:11], v[142:143], v[180:181]
	v_cvt_pk_bf16_f32 v236, v12, v13
	v_cvt_pk_bf16_f32 v237, v14, v15
	v_cvt_pk_bf16_f32 v238, v8, v9
	v_cvt_pk_bf16_f32 v239, v10, v11
	v_add_u32_e32 v235, 0xffffd400, v233
	s_and_b64 exec, exec, s[10:11]
; __device__ __forceinline__ unsigned cvt_pk_bf16(float lo, float hi) { unsigned r; asm volatile("v_cvt_pk_bf16_f32 %0, %1, %2" : "=v"(r) : "v"(lo), "v"(hi)); return r; }
; __device__ __forceinline__ float silu_f(float x) { return x * __builtin_amdgcn_rcpf(1.0f + __builtin_amdgcn_exp2f(x * -1.44269504f)); }
; template <int CTRL> __device__ __forceinline__ float dpp_rot(float x) { return __int_as_float(__builtin_amdgcn_mov_dpp(__float_as_int(x), CTRL, 0xf, 0xf, false)); }
;     __device__ __forceinline__ void operator()(const Acc& acc, const Unit& u, int wr, int wc, int fr, int fq, LAS unsigned char* lds, f32x4 epar) const {
;     ...
;                 for (int i = 0; i < NV; ++i) {
;                     const float a1 = dpp_rot<0x121>(X[i]), a2 = dpp_rot<0x122>(X[i]);
;                     const float q1 = fr >= 1 ? a1 : p1prev[i], q2 = fr >= 2 ? a2 : p2prev[i];
;                     p1prev[i] = a1; p2prev[i] = a2;
;                     const float cv = w2[i] * X[i] + w1[i] * q1 + w0[i] * q2 + bb[i];
;                     o[i] = MODE == 0 ? silu_f(cv) * Y[i] : cv * Y[i];
;                 }
;                 if (m == 0 && fr < 2) {
;                     bf16_t* hx = halo + ((size_t)strip * 6 + 2 + fr) * C + c0; bf16_t* hy = halo + ((size_t)strip * 6 + 4 + fr) * C + c0;
;                     u32x4 px, py; px.x = cvt_pk_bf16(X[0], X[1]); px.y = cvt_pk_bf16(X[2], X[3]); px.z = cvt_pk_bf16(X[4 % NV], X[5 % NV]); px.w = cvt_pk_bf16(X[6 % NV], X[7 % NV]);
;                     py.x = cvt_pk_bf16(Y[0], Y[1]); py.y = cvt_pk_bf16(Y[2], Y[3]); py.z = cvt_pk_bf16(Y[4 % NV], Y[5 % NV]); py.w = cvt_pk_bf16(Y[6 % NV], Y[7 % NV]);
;                     if (MODE == 0) { *(u32x4*)hx = px; *(u32x4*)hy = py; } else { u32x2 a; a.x = px.x; a.y = px.y; *(u32x2*)hx = a; u32x2 b; b.x = py.x; b.y = py.y; *(u32x2*)hy = b; }
;                 } else {
;                     if (MODE == 0) { u32x4 w; w.x = cvt_pk_bf16(o[0], o[1]); w.y = cvt_pk_bf16(o[2], o[3]); w.z = cvt_pk_bf16(o[4 % NV], o[5 % NV]); w.w = cvt_pk_bf16(o[6 % NV], o[7 % NV]);
;                         __builtin_nontemporal_store(w, (u32x4*)(out + (size_t)r * C + c0)); }
;                     else { u32x2 w; w.x = cvt_pk_bf16(o[0], o[1]); w.y = cvt_pk_bf16(o[2], o[3]); __builtin_nontemporal_store(w, (u32x2*)(out + (size_t)r * C + c0)); }
;                 }
	global_store_dwordx4 v235, v[236:239], s[42:43]
	s_mov_b64 exec, s[24:25]
	v_fmac_f32_dpp v210, v12, v128 row_shr:1 row_mask:0xf bank_mask:0xf
	v_fmac_f32_dpp v211, v13, v129 row_shr:1 row_mask:0xf bank_mask:0xf
	v_fmac_f32_dpp v212, v14, v130 row_shr:1 row_mask:0xf bank_mask:0xf
	v_fmac_f32_dpp v213, v15, v131 row_shr:1 row_mask:0xf bank_mask:0xf
	v_fmac_f32_dpp v214, v8, v132 row_shr:1 row_mask:0xf bank_mask:0xf
	v_fmac_f32_dpp v215, v9, v133 row_shr:1 row_mask:0xf bank_mask:0xf
	v_fmac_f32_dpp v216, v10, v134 row_shr:1 row_mask:0xf bank_mask:0xf
	v_fmac_f32_dpp v217, v11, v135 row_shr:1 row_mask:0xf bank_mask:0xf
	v_fmac_f32_dpp v210, v12, v88 row_shr:2 row_mask:0xf bank_mask:0xf
	v_fmac_f32_dpp v211, v13, v89 row_shr:2 row_mask:0xf bank_mask:0xf
	v_fmac_f32_dpp v212, v14, v90 row_shr:2 row_mask:0xf bank_mask:0xf
	v_fmac_f32_dpp v213, v15, v91 row_shr:2 row_mask:0xf bank_mask:0xf
	v_fmac_f32_dpp v214, v8, v92 row_shr:2 row_mask:0xf bank_mask:0xf
	v_fmac_f32_dpp v215, v9, v93 row_shr:2 row_mask:0xf bank_mask:0xf
	v_fmac_f32_dpp v216, v10, v94 row_shr:2 row_mask:0xf bank_mask:0xf
	v_fmac_f32_dpp v217, v11, v95 row_shr:2 row_mask:0xf bank_mask:0xf
	v_fmac_f32_dpp v210, v28, v128 row_shl:15 row_mask:0xf bank_mask:0xf
	v_fmac_f32_dpp v211, v29, v129 row_shl:15 row_mask:0xf bank_mask:0xf
	v_fmac_f32_dpp v212, v30, v130 row_shl:15 row_mask:0xf bank_mask:0xf
	v_fmac_f32_dpp v213, v31, v131 row_shl:15 row_mask:0xf bank_mask:0xf
	v_fmac_f32_dpp v214, v24, v132 row_shl:15 row_mask:0xf bank_mask:0xf
	v_fmac_f32_dpp v215, v25, v133 row_shl:15 row_mask:0xf bank_mask:0xf
	v_fmac_f32_dpp v216, v26, v134 row_shl:15 row_mask:0xf bank_mask:0xf
	v_fmac_f32_dpp v217, v27, v135 row_shl:15 row_mask:0xf bank_mask:0xf
	v_fmac_f32_dpp v210, v28, v88 row_shl:14 row_mask:0xf bank_mask:0xf
	v_fmac_f32_dpp v211, v29, v89 row_shl:14 row_mask:0xf bank_mask:0xf
	v_fmac_f32_dpp v212, v30, v90 row_shl:14 row_mask:0xf bank_mask:0xf
	v_fmac_f32_dpp v213, v31, v91 row_shl:14 row_mask:0xf bank_mask:0xf
	v_fmac_f32_dpp v214, v24, v92 row_shl:14 row_mask:0xf bank_mask:0xf
	v_fmac_f32_dpp v215, v25, v93 row_shl:14 row_mask:0xf bank_mask:0xf
	v_fmac_f32_dpp v216, v26, v94 row_shl:14 row_mask:0xf bank_mask:0xf
	v_fmac_f32_dpp v217, v27, v95 row_shl:14 row_mask:0xf bank_mask:0xf
	v_exp_f32_e32 v218, v210
	v_exp_f32_e32 v219, v211
	v_exp_f32_e32 v220, v212
	v_exp_f32_e32 v221, v213
	v_exp_f32_e32 v222, v214
	v_exp_f32_e32 v223, v215
	v_exp_f32_e32 v224, v216
	v_exp_f32_e32 v225, v217
	v_pk_fma_f32 v[218:219], v[218:219], v[208:209], v[208:209] op_sel:[0,1,1]
	v_pk_fma_f32 v[220:221], v[220:221], v[208:209], v[208:209] op_sel:[0,1,1]
	v_pk_fma_f32 v[222:223], v[222:223], v[208:209], v[208:209] op_sel:[0,1,1]
	v_pk_fma_f32 v[224:225], v[224:225], v[208:209], v[208:209] op_sel:[0,1,1]
	v_rcp_f32_e32 v218, v218
	v_rcp_f32_e32 v219, v219
	v_rcp_f32_e32 v220, v220
	v_rcp_f32_e32 v221, v221
	v_rcp_f32_e32 v222, v222
	v_rcp_f32_e32 v223, v223
	v_rcp_f32_e32 v224, v224
	v_rcp_f32_e32 v225, v225
	v_pk_mul_f32 v[210:211], v[210:211], v[218:219]
	v_pk_mul_f32 v[212:213], v[212:213], v[220:221]
	v_pk_mul_f32 v[214:215], v[214:215], v[222:223]
	v_pk_mul_f32 v[216:217], v[216:217], v[224:225]
	v_pk_mul_f32 v[4:5], v[210:211], v[4:5]
	v_pk_mul_f32 v[6:7], v[212:213], v[6:7]
	v_pk_mul_f32 v[0:1], v[214:215], v[0:1]
	v_pk_mul_f32 v[2:3], v[216:217], v[2:3]
	v_cvt_pk_bf16_f32 v226, v4, v5
	v_cvt_pk_bf16_f32 v227, v6, v7
	v_cvt_pk_bf16_f32 v228, v0, v1
	v_cvt_pk_bf16_f32 v229, v2, v3
	v_add_u32_e32 v234, 0xf2000, v230
	global_store_dwordx4 v234, v[226:229], s[96:97] nt
